# per-MMA-block s_setprio flips removed from the GEMM K-loops (A/B)
# baseline (speedup 1.0000x reference)
; #define PG8_STAGE(bufoff, gbase, voff) do { _Pragma("unroll") for (int _i = 0; _i < 2; ++_i) \
;         __builtin_amdgcn_global_load_lds((const unsigned*)((const char*)(gbase) + (voff)[_i]), (LAS unsigned*)(lds + (bufoff) + ldsw + _i * 8192), 16, 0, 0); } while (0)
; #define PG8_LDA(dst, b, h) do { _Pragma("unroll") for (int m = 0; m < 4; ++m) _Pragma("unroll") for (int k = 0; k < 2; ++k) dst[m][k] = *(const LAS bf16x8*)(lds + PG8_SA(b, h) + aoff + m * 2048 + k * 1024); } while (0)
; template <class Epi, class Sched, bool HALFN = false>
; __device__ __forceinline__ void gemm_phase(LAS unsigned char* lds, const Gemm g, const Sched& S, const Epi& E) {
;     ...
;         for (int t = 0; t < nt; t += 2) {
;             const bool last = (t == nt - 2);
;             const char* a1 = cA + (size_t)(t + 1) * kstep;
;             const char* a2 = last ? nA : cA + (size_t)(t + 2) * kstep; const char* b2 = last ? nB : cB + (size_t)(t + 2) * kstep;
;             const char* a3 = a2 + kstep; const char* b3 = b2 + kstep;
;             if constexpr (HALFN) {
;             PG8_LDB(B0, 0, 0); PG8_SCHED; PG8_LDA(At, 0, 0); PG8_STAGE(PG8_SA(1, 1), a1 + hstep, voffA);
;             PG8_WAIT_V(6); PG8_WAIT_L(0); PG8_BAR; PG8_MMA(0, 0, At, B0); PG8_BAR; PG8_SCHED;
;             PG8_LDA(At, 0, 1); PG8_STAGE(PG8_SB(0, 0), b2, voffB); PG8_STAGE(PG8_SA(0, 0), a2, voffA);
;             PG8_WAIT_V(6); PG8_WAIT_L(0); PG8_BAR; PG8_MMA(1, 0, At, B0); PG8_BAR; PG8_SCHED;
;             PG8_LDB(B0, 1, 0); PG8_SCHED; PG8_LDA(At, 1, 0); PG8_STAGE(PG8_SA(0, 1), a2 + hstep, voffA);
;             PG8_WAIT_V(6); PG8_WAIT_L(0); PG8_BAR; PG8_MMA(0, 0, At, B0); PG8_BAR; PG8_SCHED;
;             PG8_LDA(At, 1, 1); PG8_STAGE(PG8_SB(1, 0), b3, voffB); PG8_STAGE(PG8_SA(1, 0), a3, voffA);
;             PG8_WAIT_V(6); PG8_WAIT_L(0); PG8_BAR; PG8_MMA(1, 0, At, B0); PG8_BAR; PG8_SCHED;
;             } else {
;             PG8_LDB(B0, 0, 0); PG8_LDB(B1, 0, 1); PG8_SCHED; PG8_LDA(At, 0, 0); PG8_STAGE(PG8_SA(1, 1), a1 + hstep, voffA);
;             PG8_WAIT_V(8); PG8_WAIT_L(0); PG8_BAR; PG8_MMA(0, 0, At, B0); PG8_MMA(0, 1, At, B1); PG8_BAR; PG8_SCHED;
;             PG8_LDA(At, 0, 1); PG8_STAGE(PG8_SB(0, 0), b2, voffB); PG8_STAGE(PG8_SB(0, 1), b2 + hstep, voffB); PG8_STAGE(PG8_SA(0, 0), a2, voffA);
;             PG8_WAIT_V(8); PG8_WAIT_L(0); PG8_BAR; PG8_MMA(1, 0, At, B0); PG8_MMA(1, 1, At, B1); PG8_BAR; PG8_SCHED;
.LBB0_45:
	s_add_i32 s62, s20, 2
	s_add_u32 s63, s18, 0x80
	s_addc_u32 s21, s19, 0
	s_add_i32 s66, 0, 0x10000
	s_cmp_eq_u32 s45, s20
	s_cselect_b32 s21, s5, s21
	s_cselect_b32 s20, s4, s63
	v_add_u32_e32 v138, s66, v167
	s_cselect_b32 s65, s17, s61
	s_cselect_b32 s64, s16, s60
	s_add_i32 s63, 0, 0x14000
	ds_read_b128 v[154:157], v138
	ds_read_b128 v[158:161], v138 offset:1024
	ds_read_b128 v[162:165], v138 offset:2048
	ds_read_b128 v[182:185], v138 offset:3072
	v_add_u32_e32 v138, s63, v167
	ds_read_b128 v[186:189], v138
	ds_read_b128 v[190:193], v138 offset:1024
	ds_read_b128 v[194:197], v138 offset:2048
	ds_read_b128 v[198:201], v138 offset:3072
	v_lshl_add_u64 v[138:139], s[18:19], 0, v[152:153]
	s_add_i32 m0, s34, 0xc000
	ds_read_b128 v[202:205], v180
	ds_read_b128 v[206:209], v180 offset:1024
	ds_read_b128 v[210:213], v180 offset:2048
	ds_read_b128 v[214:217], v180 offset:3072
	ds_read_b128 v[218:221], v180 offset:4096
	ds_read_b128 v[222:225], v180 offset:5120
	ds_read_b128 v[226:229], v180 offset:6144
	ds_read_b128 v[230:233], v180 offset:7168
	global_load_lds_dwordx4 v[138:139], off
	v_lshl_add_u64 v[138:139], s[18:19], 0, v[150:151]
	s_add_i32 m0, s34, 0xe000
	s_nop 0
	global_load_lds_dwordx4 v[138:139], off
	s_waitcnt vmcnt(8)
	s_waitcnt lgkmcnt(0)
	s_barrier
	s_waitcnt lgkmcnt(0)
	v_mfma_f32_16x16x32_bf16 v[126:129], v[154:157], v[202:205], v[126:129]
	v_mfma_f32_16x16x32_bf16 v[122:125], v[162:165], v[202:205], v[122:125]
	v_mfma_f32_16x16x32_bf16 v[118:121], v[154:157], v[210:213], v[118:121]
	v_mfma_f32_16x16x32_bf16 v[114:117], v[162:165], v[210:213], v[114:117]
	v_mfma_f32_16x16x32_bf16 v[106:109], v[154:157], v[218:221], v[106:109]
	v_mfma_f32_16x16x32_bf16 v[98:101], v[162:165], v[218:221], v[98:101]
	v_mfma_f32_16x16x32_bf16 v[90:93], v[154:157], v[226:229], v[90:93]
	v_mfma_f32_16x16x32_bf16 v[82:85], v[162:165], v[226:229], v[82:85]
	v_mfma_f32_16x16x32_bf16 v[126:129], v[158:161], v[206:209], v[126:129]
	v_mfma_f32_16x16x32_bf16 v[122:125], v[182:185], v[206:209], v[122:125]
	v_mfma_f32_16x16x32_bf16 v[118:121], v[158:161], v[214:217], v[118:121]
	v_mfma_f32_16x16x32_bf16 v[114:117], v[182:185], v[214:217], v[114:117]
	v_mfma_f32_16x16x32_bf16 v[106:109], v[158:161], v[222:225], v[106:109]
	v_mfma_f32_16x16x32_bf16 v[98:101], v[182:185], v[222:225], v[98:101]
	v_mfma_f32_16x16x32_bf16 v[90:93], v[158:161], v[230:233], v[90:93]
	v_mfma_f32_16x16x32_bf16 v[82:85], v[182:185], v[230:233], v[82:85]
	v_mfma_f32_16x16x32_bf16 v[110:113], v[186:189], v[202:205], v[110:113]
	v_mfma_f32_16x16x32_bf16 v[102:105], v[194:197], v[202:205], v[102:105]
	v_mfma_f32_16x16x32_bf16 v[94:97], v[186:189], v[210:213], v[94:97]
	v_mfma_f32_16x16x32_bf16 v[86:89], v[194:197], v[210:213], v[86:89]
	v_mfma_f32_16x16x32_bf16 v[78:81], v[186:189], v[218:221], v[78:81]
	v_mfma_f32_16x16x32_bf16 v[74:77], v[194:197], v[218:221], v[74:77]
	v_mfma_f32_16x16x32_bf16 v[70:73], v[186:189], v[226:229], v[70:73]
	v_mfma_f32_16x16x32_bf16 v[66:69], v[194:197], v[226:229], v[66:69]
	v_mfma_f32_16x16x32_bf16 v[110:113], v[190:193], v[206:209], v[110:113]
	v_mfma_f32_16x16x32_bf16 v[102:105], v[198:201], v[206:209], v[102:105]
	v_mfma_f32_16x16x32_bf16 v[94:97], v[190:193], v[214:217], v[94:97]
	v_mfma_f32_16x16x32_bf16 v[86:89], v[198:201], v[214:217], v[86:89]
	v_mfma_f32_16x16x32_bf16 v[78:81], v[190:193], v[222:225], v[78:81]
	v_mfma_f32_16x16x32_bf16 v[74:77], v[198:201], v[222:225], v[74:77]
	v_mfma_f32_16x16x32_bf16 v[70:73], v[190:193], v[230:233], v[70:73]
	v_mfma_f32_16x16x32_bf16 v[66:69], v[198:201], v[230:233], v[66:69]
	s_barrier
	s_add_i32 s66, s66, s25
	v_lshl_add_u64 v[138:139], s[64:65], 0, v[0:1]
	s_mov_b32 m0, s66
	ds_read_b128 v[202:205], v180 offset:16384
	ds_read_b128 v[206:209], v180 offset:17408
	ds_read_b128 v[210:213], v180 offset:18432
	ds_read_b128 v[214:217], v180 offset:19456
	ds_read_b128 v[218:221], v180 offset:20480
	ds_read_b128 v[222:225], v180 offset:21504
	ds_read_b128 v[226:229], v180 offset:22528
	ds_read_b128 v[230:233], v180 offset:23552
	global_load_lds_dwordx4 v[138:139], off
	s_add_i32 m0, s66, 0x2000
	v_lshl_add_u64 v[234:235], s[64:65], 0, v[148:149]
	s_add_u32 s64, s64, s6
	s_addc_u32 s65, s65, s7
	s_add_i32 s63, s63, s25
	global_load_lds_dwordx4 v[234:235], off
	v_lshl_add_u64 v[236:237], s[64:65], 0, v[0:1]
	s_mov_b32 m0, s63
	v_lshl_add_u64 v[238:239], s[64:65], 0, v[148:149]
	global_load_lds_dwordx4 v[236:237], off
	s_add_i32 m0, s63, 0x2000
	v_lshl_add_u64 v[240:241], s[20:21], 0, v[0:1]
	global_load_lds_dwordx4 v[238:239], off
	s_mov_b32 m0, s34
	v_lshl_add_u64 v[242:243], s[20:21], 0, v[148:149]
	global_load_lds_dwordx4 v[240:241], off
	s_mov_b32 m0, s35
	s_nop 0
	global_load_lds_dwordx4 v[242:243], off
	s_waitcnt vmcnt(8)
	s_waitcnt lgkmcnt(0)
	s_barrier
; #define PG8_STAGE(bufoff, gbase, voff) do { _Pragma("unroll") for (int _i = 0; _i < 2; ++_i) \
;         __builtin_amdgcn_global_load_lds((const unsigned*)((const char*)(gbase) + (voff)[_i]), (LAS unsigned*)(lds + (bufoff) + ldsw + _i * 8192), 16, 0, 0); } while (0)
; #define PG8_LDA(dst, b, h) do { _Pragma("unroll") for (int m = 0; m < 4; ++m) _Pragma("unroll") for (int k = 0; k < 2; ++k) dst[m][k] = *(const LAS bf16x8*)(lds + PG8_SA(b, h) + aoff + m * 2048 + k * 1024); } while (0)
; #define PG8_LDB(dst, b, h) do { _Pragma("unroll") for (int n = 0; n < 2; ++n) _Pragma("unroll") for (int k = 0; k < 2; ++k) dst[n][k] = *(const LAS bf16x8*)(lds + PG8_SB(b, h) + boff + n * 2048 + k * 1024); } while (0)
; #define PG8_MMA(ai, bj, At, Bt) do { __builtin_amdgcn_s_setprio(1); _Pragma("unroll") for (int m = 0; m < 4; ++m) _Pragma("unroll") for (int n = 0; n < 2; ++n) _Pragma("unroll") for (int k = 0; k < 2; ++k) \
;         acc[ai][bj][m][n] = __builtin_amdgcn_mfma_f32_16x16x32_bf16(Bt[n][k], At[m][k], acc[ai][bj][m][n], 0, 0, 0); __builtin_amdgcn_s_setprio(0); } while (0)
; #define PG8_WAIT_V(n) asm volatile("s_waitcnt vmcnt(" #n ")" ::: "memory")
; #define PG8_WAIT_L(n) asm volatile("s_waitcnt lgkmcnt(" #n ")" ::: "memory")
; #define PG8_BAR __builtin_amdgcn_s_barrier()
; #define PG8_SCHED __builtin_amdgcn_sched_barrier(0)
; template <class Epi, class Sched, bool HALFN = false>
; __device__ __forceinline__ void gemm_phase(LAS unsigned char* lds, const Gemm g, const Sched& S, const Epi& E) {
;     ...
;             PG8_WAIT_V(8); PG8_WAIT_L(0); PG8_BAR; PG8_MMA(1, 0, At, B0); PG8_MMA(1, 1, At, B1); PG8_BAR; PG8_SCHED;
;             PG8_LDB(B0, 1, 0); PG8_LDB(B1, 1, 1); PG8_SCHED; PG8_LDA(At, 1, 0); PG8_STAGE(PG8_SA(0, 1), a2 + hstep, voffA);
;             PG8_WAIT_V(8); PG8_WAIT_L(0); PG8_BAR; PG8_MMA(0, 0, At, B0); PG8_MMA(0, 1, At, B1); PG8_BAR; PG8_SCHED;
	s_waitcnt lgkmcnt(0)
	v_mfma_f32_16x16x32_bf16 v[62:65], v[154:157], v[202:205], v[62:65]
	v_mfma_f32_16x16x32_bf16 v[58:61], v[162:165], v[202:205], v[58:61]
	v_mfma_f32_16x16x32_bf16 v[54:57], v[154:157], v[210:213], v[54:57]
	v_mfma_f32_16x16x32_bf16 v[50:53], v[162:165], v[210:213], v[50:53]
	v_mfma_f32_16x16x32_bf16 v[42:45], v[154:157], v[218:221], v[42:45]
	v_mfma_f32_16x16x32_bf16 v[34:37], v[162:165], v[218:221], v[34:37]
	v_mfma_f32_16x16x32_bf16 v[26:29], v[154:157], v[226:229], v[26:29]
	v_mfma_f32_16x16x32_bf16 v[18:21], v[162:165], v[226:229], v[18:21]
	v_mfma_f32_16x16x32_bf16 v[62:65], v[158:161], v[206:209], v[62:65]
	v_mfma_f32_16x16x32_bf16 v[58:61], v[182:185], v[206:209], v[58:61]
	v_mfma_f32_16x16x32_bf16 v[54:57], v[158:161], v[214:217], v[54:57]
	v_mfma_f32_16x16x32_bf16 v[50:53], v[182:185], v[214:217], v[50:53]
	v_mfma_f32_16x16x32_bf16 v[42:45], v[158:161], v[222:225], v[42:45]
	v_mfma_f32_16x16x32_bf16 v[34:37], v[182:185], v[222:225], v[34:37]
	v_mfma_f32_16x16x32_bf16 v[26:29], v[158:161], v[230:233], v[26:29]
	v_mfma_f32_16x16x32_bf16 v[18:21], v[182:185], v[230:233], v[18:21]
	v_mfma_f32_16x16x32_bf16 v[46:49], v[186:189], v[202:205], v[46:49]
	v_mfma_f32_16x16x32_bf16 v[38:41], v[194:197], v[202:205], v[38:41]
	v_mfma_f32_16x16x32_bf16 v[30:33], v[186:189], v[210:213], v[30:33]
	v_mfma_f32_16x16x32_bf16 v[22:25], v[194:197], v[210:213], v[22:25]
	v_mfma_f32_16x16x32_bf16 v[14:17], v[186:189], v[218:221], v[14:17]
	v_mfma_f32_16x16x32_bf16 v[10:13], v[194:197], v[218:221], v[10:13]
	v_mfma_f32_16x16x32_bf16 v[6:9], v[186:189], v[226:229], v[6:9]
	v_mfma_f32_16x16x32_bf16 v[2:5], v[194:197], v[226:229], v[2:5]
	v_mfma_f32_16x16x32_bf16 v[46:49], v[190:193], v[206:209], v[46:49]
	v_mfma_f32_16x16x32_bf16 v[38:41], v[198:201], v[206:209], v[38:41]
	v_mfma_f32_16x16x32_bf16 v[30:33], v[190:193], v[214:217], v[30:33]
	v_mfma_f32_16x16x32_bf16 v[22:25], v[198:201], v[214:217], v[22:25]
	v_mfma_f32_16x16x32_bf16 v[14:17], v[190:193], v[222:225], v[14:17]
	v_mfma_f32_16x16x32_bf16 v[10:13], v[198:201], v[222:225], v[10:13]
	v_mfma_f32_16x16x32_bf16 v[6:9], v[190:193], v[230:233], v[6:9]
	v_mfma_f32_16x16x32_bf16 v[2:5], v[198:201], v[230:233], v[2:5]
	s_barrier
	s_add_i32 s63, 0, 0x18000
	v_add_u32_e32 v178, s63, v167
	s_add_i32 s64, 0, 0x1c000
	ds_read_b128 v[154:157], v178
	ds_read_b128 v[158:161], v178 offset:1024
	ds_read_b128 v[162:165], v178 offset:2048
	ds_read_b128 v[182:185], v178 offset:3072
	v_add_u32_e32 v178, s64, v167
	ds_read_b128 v[186:189], v178
	ds_read_b128 v[190:193], v178 offset:1024
	ds_read_b128 v[194:197], v178 offset:2048
	ds_read_b128 v[198:201], v178 offset:3072
	s_add_u32 s20, s20, s6
	s_addc_u32 s21, s21, s7
	s_mov_b32 m0, s40
	v_lshl_add_u64 v[244:245], s[20:21], 0, v[0:1]
	ds_read_b128 v[202:205], v180 offset:32768
	ds_read_b128 v[206:209], v180 offset:33792
	ds_read_b128 v[210:213], v180 offset:34816
	ds_read_b128 v[214:217], v180 offset:35840
	ds_read_b128 v[218:221], v180 offset:36864
	ds_read_b128 v[222:225], v180 offset:37888
	ds_read_b128 v[226:229], v180 offset:38912
	ds_read_b128 v[230:233], v180 offset:39936
	global_load_lds_dwordx4 v[244:245], off
	v_lshl_add_u64 v[244:245], s[20:21], 0, v[148:149]
	s_mov_b32 m0, s41
	s_nop 0
	global_load_lds_dwordx4 v[244:245], off
	s_waitcnt vmcnt(8)
	s_waitcnt lgkmcnt(0)
	s_barrier
	s_waitcnt lgkmcnt(0)
	v_mfma_f32_16x16x32_bf16 v[126:129], v[154:157], v[202:205], v[126:129]
	v_mfma_f32_16x16x32_bf16 v[122:125], v[162:165], v[202:205], v[122:125]
	v_mfma_f32_16x16x32_bf16 v[118:121], v[154:157], v[210:213], v[118:121]
	v_mfma_f32_16x16x32_bf16 v[114:117], v[162:165], v[210:213], v[114:117]
	v_mfma_f32_16x16x32_bf16 v[106:109], v[154:157], v[218:221], v[106:109]
	v_mfma_f32_16x16x32_bf16 v[98:101], v[162:165], v[218:221], v[98:101]
	v_mfma_f32_16x16x32_bf16 v[90:93], v[154:157], v[226:229], v[90:93]
	v_mfma_f32_16x16x32_bf16 v[82:85], v[162:165], v[226:229], v[82:85]
	v_mfma_f32_16x16x32_bf16 v[126:129], v[158:161], v[206:209], v[126:129]
	v_mfma_f32_16x16x32_bf16 v[122:125], v[182:185], v[206:209], v[122:125]
	v_mfma_f32_16x16x32_bf16 v[118:121], v[158:161], v[214:217], v[118:121]
	v_mfma_f32_16x16x32_bf16 v[114:117], v[182:185], v[214:217], v[114:117]
	v_mfma_f32_16x16x32_bf16 v[106:109], v[158:161], v[222:225], v[106:109]
	v_mfma_f32_16x16x32_bf16 v[98:101], v[182:185], v[222:225], v[98:101]
	v_mfma_f32_16x16x32_bf16 v[90:93], v[158:161], v[230:233], v[90:93]
	v_mfma_f32_16x16x32_bf16 v[82:85], v[182:185], v[230:233], v[82:85]
	v_mfma_f32_16x16x32_bf16 v[110:113], v[186:189], v[202:205], v[110:113]
	v_mfma_f32_16x16x32_bf16 v[102:105], v[194:197], v[202:205], v[102:105]
	v_mfma_f32_16x16x32_bf16 v[94:97], v[186:189], v[210:213], v[94:97]
	v_mfma_f32_16x16x32_bf16 v[86:89], v[194:197], v[210:213], v[86:89]
	v_mfma_f32_16x16x32_bf16 v[78:81], v[186:189], v[218:221], v[78:81]
	v_mfma_f32_16x16x32_bf16 v[74:77], v[194:197], v[218:221], v[74:77]
	v_mfma_f32_16x16x32_bf16 v[70:73], v[186:189], v[226:229], v[70:73]
	v_mfma_f32_16x16x32_bf16 v[66:69], v[194:197], v[226:229], v[66:69]
	v_mfma_f32_16x16x32_bf16 v[110:113], v[190:193], v[206:209], v[110:113]
	v_mfma_f32_16x16x32_bf16 v[102:105], v[198:201], v[206:209], v[102:105]
	v_mfma_f32_16x16x32_bf16 v[94:97], v[190:193], v[214:217], v[94:97]
	v_mfma_f32_16x16x32_bf16 v[86:89], v[198:201], v[214:217], v[86:89]
	v_mfma_f32_16x16x32_bf16 v[78:81], v[190:193], v[222:225], v[78:81]
	v_mfma_f32_16x16x32_bf16 v[74:77], v[198:201], v[222:225], v[74:77]
	v_mfma_f32_16x16x32_bf16 v[70:73], v[190:193], v[230:233], v[70:73]
	v_mfma_f32_16x16x32_bf16 v[66:69], v[198:201], v[230:233], v[66:69]
	s_barrier
; #define PG8_STAGE(bufoff, gbase, voff) do { _Pragma("unroll") for (int _i = 0; _i < 2; ++_i) \
;         __builtin_amdgcn_global_load_lds((const unsigned*)((const char*)(gbase) + (voff)[_i]), (LAS unsigned*)(lds + (bufoff) + ldsw + _i * 8192), 16, 0, 0); } while (0)
; #define PG8_LDA(dst, b, h) do { _Pragma("unroll") for (int m = 0; m < 4; ++m) _Pragma("unroll") for (int k = 0; k < 2; ++k) dst[m][k] = *(const LAS bf16x8*)(lds + PG8_SA(b, h) + aoff + m * 2048 + k * 1024); } while (0)
; #define PG8_MMA(ai, bj, At, Bt) do { __builtin_amdgcn_s_setprio(1); _Pragma("unroll") for (int m = 0; m < 4; ++m) _Pragma("unroll") for (int n = 0; n < 2; ++n) _Pragma("unroll") for (int k = 0; k < 2; ++k) \
;         acc[ai][bj][m][n] = __builtin_amdgcn_mfma_f32_16x16x32_bf16(Bt[n][k], At[m][k], acc[ai][bj][m][n], 0, 0, 0); __builtin_amdgcn_s_setprio(0); } while (0)
; #define PG8_WAIT_V(n) asm volatile("s_waitcnt vmcnt(" #n ")" ::: "memory")
; #define PG8_WAIT_L(n) asm volatile("s_waitcnt lgkmcnt(" #n ")" ::: "memory")
; #define PG8_BAR __builtin_amdgcn_s_barrier()
; #define PG8_SCHED __builtin_amdgcn_sched_barrier(0)
; template <class Epi, class Sched, bool HALFN = false>
; __device__ __forceinline__ void gemm_phase(LAS unsigned char* lds, const Gemm g, const Sched& S, const Epi& E) {
;     ...
;             PG8_LDA(At, 1, 1); PG8_STAGE(PG8_SB(1, 0), b3, voffB); PG8_STAGE(PG8_SB(1, 1), b3 + hstep, voffB); PG8_STAGE(PG8_SA(1, 0), a3, voffA);
;             PG8_WAIT_V(8); PG8_WAIT_L(0); PG8_BAR; PG8_MMA(1, 0, At, B0); PG8_MMA(1, 1, At, B1); PG8_BAR; PG8_SCHED;
;             }
;         }
	s_add_i32 s20, s63, s25
	v_lshl_add_u64 v[138:139], v[138:139], 0, s[26:27]
	s_mov_b32 m0, s20
	ds_read_b128 v[202:205], v180 offset:49152
	ds_read_b128 v[206:209], v180 offset:50176
	ds_read_b128 v[210:213], v180 offset:51200
	ds_read_b128 v[214:217], v180 offset:52224
	ds_read_b128 v[218:221], v180 offset:53248
	ds_read_b128 v[222:225], v180 offset:54272
	ds_read_b128 v[226:229], v180 offset:55296
	ds_read_b128 v[230:233], v180 offset:56320
	global_load_lds_dwordx4 v[138:139], off
	v_lshl_add_u64 v[138:139], v[234:235], 0, s[26:27]
	s_add_i32 m0, s20, 0x2000
	s_add_i32 s20, s64, s25
	global_load_lds_dwordx4 v[138:139], off
	v_lshl_add_u64 v[138:139], v[236:237], 0, s[26:27]
	s_mov_b32 m0, s20
	s_nop 0
	global_load_lds_dwordx4 v[138:139], off
	v_lshl_add_u64 v[138:139], v[238:239], 0, s[26:27]
	s_add_i32 m0, s20, 0x2000
	s_nop 0
	global_load_lds_dwordx4 v[138:139], off
	v_lshl_add_u64 v[138:139], v[240:241], 0, s[26:27]
	s_mov_b32 m0, s43
	s_nop 0
	global_load_lds_dwordx4 v[138:139], off
	v_lshl_add_u64 v[138:139], v[242:243], 0, s[26:27]
	s_mov_b32 m0, s44
	s_nop 0
	global_load_lds_dwordx4 v[138:139], off
	s_waitcnt vmcnt(8)
	s_waitcnt lgkmcnt(0)
	s_barrier
	s_waitcnt lgkmcnt(0)
	v_mfma_f32_16x16x32_bf16 v[62:65], v[154:157], v[202:205], v[62:65]
	v_mfma_f32_16x16x32_bf16 v[58:61], v[162:165], v[202:205], v[58:61]
	v_mfma_f32_16x16x32_bf16 v[54:57], v[154:157], v[210:213], v[54:57]
	v_mfma_f32_16x16x32_bf16 v[50:53], v[162:165], v[210:213], v[50:53]
	v_mfma_f32_16x16x32_bf16 v[42:45], v[154:157], v[218:221], v[42:45]
	v_mfma_f32_16x16x32_bf16 v[34:37], v[162:165], v[218:221], v[34:37]
	v_mfma_f32_16x16x32_bf16 v[26:29], v[154:157], v[226:229], v[26:29]
	v_mfma_f32_16x16x32_bf16 v[18:21], v[162:165], v[226:229], v[18:21]
	v_mfma_f32_16x16x32_bf16 v[62:65], v[158:161], v[206:209], v[62:65]
	v_mfma_f32_16x16x32_bf16 v[58:61], v[182:185], v[206:209], v[58:61]
	v_mfma_f32_16x16x32_bf16 v[54:57], v[158:161], v[214:217], v[54:57]
	v_mfma_f32_16x16x32_bf16 v[50:53], v[182:185], v[214:217], v[50:53]
	v_mfma_f32_16x16x32_bf16 v[42:45], v[158:161], v[222:225], v[42:45]
	v_mfma_f32_16x16x32_bf16 v[34:37], v[182:185], v[222:225], v[34:37]
	v_mfma_f32_16x16x32_bf16 v[26:29], v[158:161], v[230:233], v[26:29]
	v_mfma_f32_16x16x32_bf16 v[18:21], v[182:185], v[230:233], v[18:21]
	v_mfma_f32_16x16x32_bf16 v[46:49], v[186:189], v[202:205], v[46:49]
	v_mfma_f32_16x16x32_bf16 v[38:41], v[194:197], v[202:205], v[38:41]
	v_mfma_f32_16x16x32_bf16 v[30:33], v[186:189], v[210:213], v[30:33]
	v_mfma_f32_16x16x32_bf16 v[22:25], v[194:197], v[210:213], v[22:25]
	v_mfma_f32_16x16x32_bf16 v[14:17], v[186:189], v[218:221], v[14:17]
	v_mfma_f32_16x16x32_bf16 v[10:13], v[194:197], v[218:221], v[10:13]
	v_mfma_f32_16x16x32_bf16 v[6:9], v[186:189], v[226:229], v[6:9]
	v_mfma_f32_16x16x32_bf16 v[2:5], v[194:197], v[226:229], v[2:5]
	v_mfma_f32_16x16x32_bf16 v[46:49], v[190:193], v[206:209], v[46:49]
	v_mfma_f32_16x16x32_bf16 v[38:41], v[198:201], v[206:209], v[38:41]
	v_mfma_f32_16x16x32_bf16 v[30:33], v[190:193], v[214:217], v[30:33]
	v_mfma_f32_16x16x32_bf16 v[22:25], v[198:201], v[214:217], v[22:25]
	v_mfma_f32_16x16x32_bf16 v[14:17], v[190:193], v[222:225], v[14:17]
	v_mfma_f32_16x16x32_bf16 v[10:13], v[198:201], v[222:225], v[10:13]
	v_mfma_f32_16x16x32_bf16 v[6:9], v[190:193], v[230:233], v[6:9]
	v_mfma_f32_16x16x32_bf16 v[2:5], v[198:201], v[230:233], v[2:5]
	s_barrier
	s_add_u32 s60, s60, 0x100
	s_addc_u32 s61, s61, 0
	s_add_u32 s18, s18, 0x100
	s_addc_u32 s19, s19, 0
	s_cmp_ge_i32 s62, s42
	s_mov_b32 s20, s62
	s_cbranch_scc0 .LBB0_45
;     __device__ __forceinline__ void operator()(AccT acc, const Unit& u, int wr, int wc, int fr, int fq) const {
;         const int row0 = u.pm * BM + wr * 64 + fr, col0 = u.pn * BM + wc * 32 + 4 * fq;
; #pragma unroll
;         for (int ai = 0; ai < 2; ++ai)
; #pragma unroll
;             for (int m = 0; m < 4; ++m) { const size_t off = (size_t)(row0 + ai * HALF + m * 16) * D_ + col0;
; #pragma unroll
;                 for (int bj = 0; bj < 2; ++bj)
; #pragma unroll
;                     for (int n = 0; n < 2; ++n) { const f32x4 bs = *(const f32x4*)(xin + off + bj * HALF + n * 16); *(f32x4*)(xout + off + bj * HALF + n * 16) = bs + acc[ai][bj][m][n] * scale; }
	v_pk_mul_f32 v[162:163], v[128:129], 0.5 op_sel_hi:[1,0]
	v_pk_mul_f32 v[164:165], v[126:127], 0.5 op_sel_hi:[1,0]
	v_pk_mul_f32 v[154:155], v[124:125], 0.5 op_sel_hi:[1,0]
	v_pk_mul_f32 v[156:157], v[122:123], 0.5 op_sel_hi:[1,0]
	v_pk_mul_f32 v[158:159], v[112:113], 0.5 op_sel_hi:[1,0]
	v_pk_mul_f32 v[160:161], v[110:111], 0.5 op_sel_hi:[1,0]
	v_pk_mul_f32 v[126:127], v[104:105], 0.5 op_sel_hi:[1,0]
	v_pk_mul_f32 v[128:129], v[102:103], 0.5 op_sel_hi:[1,0]
	v_pk_mul_f32 v[122:123], v[120:121], 0.5 op_sel_hi:[1,0]
	v_pk_mul_f32 v[124:125], v[118:119], 0.5 op_sel_hi:[1,0]
	v_pk_mul_f32 v[116:117], v[116:117], 0.5 op_sel_hi:[1,0]
	v_pk_mul_f32 v[114:115], v[114:115], 0.5 op_sel_hi:[1,0]
	v_pk_mul_f32 v[118:119], v[96:97], 0.5 op_sel_hi:[1,0]
	v_pk_mul_f32 v[120:121], v[94:95], 0.5 op_sel_hi:[1,0]
	v_pk_mul_f32 v[110:111], v[88:89], 0.5 op_sel_hi:[1,0]
	v_pk_mul_f32 v[112:113], v[86:87], 0.5 op_sel_hi:[1,0]
	v_pk_mul_f32 v[108:109], v[108:109], 0.5 op_sel_hi:[1,0]
	v_pk_mul_f32 v[106:107], v[106:107], 0.5 op_sel_hi:[1,0]
	v_pk_mul_f32 v[100:101], v[100:101], 0.5 op_sel_hi:[1,0]
	v_pk_mul_f32 v[98:99], v[98:99], 0.5 op_sel_hi:[1,0]
	v_pk_mul_f32 v[102:103], v[80:81], 0.5 op_sel_hi:[1,0]
	v_pk_mul_f32 v[104:105], v[78:79], 0.5 op_sel_hi:[1,0]
	v_pk_mul_f32 v[94:95], v[76:77], 0.5 op_sel_hi:[1,0]
	v_pk_mul_f32 v[96:97], v[74:75], 0.5 op_sel_hi:[1,0]
	v_pk_mul_f32 v[92:93], v[92:93], 0.5 op_sel_hi:[1,0]
	v_pk_mul_f32 v[90:91], v[90:91], 0.5 op_sel_hi:[1,0]
	v_pk_mul_f32 v[84:85], v[84:85], 0.5 op_sel_hi:[1,0]
	v_pk_mul_f32 v[82:83], v[82:83], 0.5 op_sel_hi:[1,0]
	v_pk_mul_f32 v[86:87], v[72:73], 0.5 op_sel_hi:[1,0]
	v_pk_mul_f32 v[88:89], v[70:71], 0.5 op_sel_hi:[1,0]
	v_pk_mul_f32 v[78:79], v[68:69], 0.5 op_sel_hi:[1,0]
	v_pk_mul_f32 v[80:81], v[66:67], 0.5 op_sel_hi:[1,0]
	v_pk_mul_f32 v[74:75], v[64:65], 0.5 op_sel_hi:[1,0]
	v_pk_mul_f32 v[76:77], v[62:63], 0.5 op_sel_hi:[1,0]
	v_pk_mul_f32 v[66:67], v[60:61], 0.5 op_sel_hi:[1,0]
	v_pk_mul_f32 v[68:69], v[58:59], 0.5 op_sel_hi:[1,0]
	v_pk_mul_f32 v[70:71], v[48:49], 0.5 op_sel_hi:[1,0]
	v_pk_mul_f32 v[72:73], v[46:47], 0.5 op_sel_hi:[1,0]
	v_pk_mul_f32 v[62:63], v[40:41], 0.5 op_sel_hi:[1,0]
	v_pk_mul_f32 v[64:65], v[38:39], 0.5 op_sel_hi:[1,0]
	v_pk_mul_f32 v[58:59], v[56:57], 0.5 op_sel_hi:[1,0]
	v_pk_mul_f32 v[60:61], v[54:55], 0.5 op_sel_hi:[1,0]
	v_pk_mul_f32 v[52:53], v[52:53], 0.5 op_sel_hi:[1,0]
	v_pk_mul_f32 v[50:51], v[50:51], 0.5 op_sel_hi:[1,0]
	v_pk_mul_f32 v[54:55], v[32:33], 0.5 op_sel_hi:[1,0]
	v_pk_mul_f32 v[56:57], v[30:31], 0.5 op_sel_hi:[1,0]
	v_pk_mul_f32 v[46:47], v[24:25], 0.5 op_sel_hi:[1,0]
	v_pk_mul_f32 v[48:49], v[22:23], 0.5 op_sel_hi:[1,0]
	v_pk_mul_f32 v[38:39], v[44:45], 0.5 op_sel_hi:[1,0]
	v_pk_mul_f32 v[40:41], v[42:43], 0.5 op_sel_hi:[1,0]
	v_pk_mul_f32 v[30:31], v[36:37], 0.5 op_sel_hi:[1,0]
	v_pk_mul_f32 v[32:33], v[34:35], 0.5 op_sel_hi:[1,0]
	v_pk_mul_f32 v[34:35], v[16:17], 0.5 op_sel_hi:[1,0]
	v_pk_mul_f32 v[36:37], v[14:15], 0.5 op_sel_hi:[1,0]
	v_pk_mul_f32 v[22:23], v[12:13], 0.5 op_sel_hi:[1,0]
	v_pk_mul_f32 v[24:25], v[10:11], 0.5 op_sel_hi:[1,0]
	v_pk_mul_f32 v[14:15], v[28:29], 0.5 op_sel_hi:[1,0]
	v_pk_mul_f32 v[16:17], v[26:27], 0.5 op_sel_hi:[1,0]
	v_pk_mul_f32 v[10:11], v[20:21], 0.5 op_sel_hi:[1,0]
	v_pk_mul_f32 v[12:13], v[18:19], 0.5 op_sel_hi:[1,0]
	v_pk_mul_f32 v[8:9], v[8:9], 0.5 op_sel_hi:[1,0]
	v_pk_mul_f32 v[6:7], v[6:7], 0.5 op_sel_hi:[1,0]
	v_pk_mul_f32 v[4:5], v[4:5], 0.5 op_sel_hi:[1,0]
	v_pk_mul_f32 v[2:3], v[2:3], 0.5 op_sel_hi:[1,0]

; #define PG8_STAGE(bufoff, gbase, voff) do { _Pragma("unroll") for (int _i = 0; _i < 2; ++_i) \
;         __builtin_amdgcn_global_load_lds((const unsigned*)((const char*)(gbase) + (voff)[_i]), (LAS unsigned*)(lds + (bufoff) + ldsw + _i * 8192), 16, 0, 0); } while (0)
; #define PG8_LDA(dst, b, h) do { _Pragma("unroll") for (int m = 0; m < 4; ++m) _Pragma("unroll") for (int k = 0; k < 2; ++k) dst[m][k] = *(const LAS bf16x8*)(lds + PG8_SA(b, h) + aoff + m * 2048 + k * 1024); } while (0)
; template <class Epi, class Sched, bool HALFN = false>
; __device__ __forceinline__ void gemm_phase(LAS unsigned char* lds, const Gemm g, const Sched& S, const Epi& E) {
;     ...
;         for (int t = 0; t < nt; t += 2) {
;             const bool last = (t == nt - 2);
;             const char* a1 = cA + (size_t)(t + 1) * kstep;
;             const char* a2 = last ? nA : cA + (size_t)(t + 2) * kstep; const char* b2 = last ? nB : cB + (size_t)(t + 2) * kstep;
;             const char* a3 = a2 + kstep; const char* b3 = b2 + kstep;
;             if constexpr (HALFN) {
;             PG8_LDB(B0, 0, 0); PG8_SCHED; PG8_LDA(At, 0, 0); PG8_STAGE(PG8_SA(1, 1), a1 + hstep, voffA);
;             PG8_WAIT_V(6); PG8_WAIT_L(0); PG8_BAR; PG8_MMA(0, 0, At, B0); PG8_BAR; PG8_SCHED;
;             PG8_LDA(At, 0, 1); PG8_STAGE(PG8_SB(0, 0), b2, voffB); PG8_STAGE(PG8_SA(0, 0), a2, voffA);
;             PG8_WAIT_V(6); PG8_WAIT_L(0); PG8_BAR; PG8_MMA(1, 0, At, B0); PG8_BAR; PG8_SCHED;
;             PG8_LDB(B0, 1, 0); PG8_SCHED; PG8_LDA(At, 1, 0); PG8_STAGE(PG8_SA(0, 1), a2 + hstep, voffA);
;             PG8_WAIT_V(6); PG8_WAIT_L(0); PG8_BAR; PG8_MMA(0, 0, At, B0); PG8_BAR; PG8_SCHED;
;             PG8_LDA(At, 1, 1); PG8_STAGE(PG8_SB(1, 0), b3, voffB); PG8_STAGE(PG8_SA(1, 0), a3, voffA);
;             PG8_WAIT_V(6); PG8_WAIT_L(0); PG8_BAR; PG8_MMA(1, 0, At, B0); PG8_BAR; PG8_SCHED;
;             } else {
;             PG8_LDB(B0, 0, 0); PG8_LDB(B1, 0, 1); PG8_SCHED; PG8_LDA(At, 0, 0); PG8_STAGE(PG8_SA(1, 1), a1 + hstep, voffA);
;             PG8_WAIT_V(8); PG8_WAIT_L(0); PG8_BAR; PG8_MMA(0, 0, At, B0); PG8_MMA(0, 1, At, B1); PG8_BAR; PG8_SCHED;
;             PG8_LDA(At, 0, 1); PG8_STAGE(PG8_SB(0, 0), b2, voffB); PG8_STAGE(PG8_SB(0, 1), b2 + hstep, voffB); PG8_STAGE(PG8_SA(0, 0), a2, voffA);
;             PG8_WAIT_V(8); PG8_WAIT_L(0); PG8_BAR; PG8_MMA(1, 0, At, B0); PG8_MMA(1, 1, At, B1); PG8_BAR; PG8_SCHED;
.LBB0_69:
	s_add_i32 s62, s20, 2
	s_add_u32 s63, s18, 0x80
	s_addc_u32 s21, s19, 0
	s_add_i32 s66, 0, 0x10000
	s_cmp_eq_u32 s45, s20
	s_cselect_b32 s21, s5, s21
	s_cselect_b32 s20, s4, s63
	v_add_u32_e32 v138, s66, v161
	s_cselect_b32 s65, s17, s61
	s_cselect_b32 s64, s16, s60
	s_add_i32 s63, 0, 0x14000
	ds_read_b128 v[164:167], v138
	ds_read_b128 v[180:183], v138 offset:1024
	ds_read_b128 v[184:187], v138 offset:2048
	ds_read_b128 v[188:191], v138 offset:3072
	v_add_u32_e32 v138, s63, v161
	ds_read_b128 v[192:195], v138
	ds_read_b128 v[196:199], v138 offset:1024
	ds_read_b128 v[200:203], v138 offset:2048
	ds_read_b128 v[204:207], v138 offset:3072
	v_lshl_add_u64 v[138:139], s[18:19], 0, v[156:157]
	s_add_i32 m0, s34, 0xc000
	ds_read_b128 v[208:211], v163
	ds_read_b128 v[212:215], v163 offset:1024
	ds_read_b128 v[216:219], v163 offset:2048
	ds_read_b128 v[220:223], v163 offset:3072
	ds_read_b128 v[224:227], v163 offset:4096
	ds_read_b128 v[228:231], v163 offset:5120
	ds_read_b128 v[232:235], v163 offset:6144
	ds_read_b128 v[236:239], v163 offset:7168
	global_load_lds_dwordx4 v[138:139], off
	v_lshl_add_u64 v[138:139], s[18:19], 0, v[154:155]
	s_add_i32 m0, s34, 0xe000
	s_nop 0
	global_load_lds_dwordx4 v[138:139], off
	s_waitcnt vmcnt(8)
	s_waitcnt lgkmcnt(0)
	s_barrier
	s_waitcnt lgkmcnt(0)
	v_mfma_f32_16x16x32_bf16 v[126:129], v[164:167], v[208:211], v[126:129]
	v_mfma_f32_16x16x32_bf16 v[118:121], v[184:187], v[208:211], v[118:121]
	v_mfma_f32_16x16x32_bf16 v[110:113], v[164:167], v[216:219], v[110:113]
	v_mfma_f32_16x16x32_bf16 v[102:105], v[184:187], v[216:219], v[102:105]
	v_mfma_f32_16x16x32_bf16 v[94:97], v[164:167], v[224:227], v[94:97]
	v_mfma_f32_16x16x32_bf16 v[86:89], v[184:187], v[224:227], v[86:89]
	v_mfma_f32_16x16x32_bf16 v[78:81], v[164:167], v[232:235], v[78:81]
	v_mfma_f32_16x16x32_bf16 v[70:73], v[184:187], v[232:235], v[70:73]
	v_mfma_f32_16x16x32_bf16 v[126:129], v[180:183], v[212:215], v[126:129]
	v_mfma_f32_16x16x32_bf16 v[118:121], v[188:191], v[212:215], v[118:121]
	v_mfma_f32_16x16x32_bf16 v[110:113], v[180:183], v[220:223], v[110:113]
	v_mfma_f32_16x16x32_bf16 v[102:105], v[188:191], v[220:223], v[102:105]
	v_mfma_f32_16x16x32_bf16 v[94:97], v[180:183], v[228:231], v[94:97]
	v_mfma_f32_16x16x32_bf16 v[86:89], v[188:191], v[228:231], v[86:89]
	v_mfma_f32_16x16x32_bf16 v[78:81], v[180:183], v[236:239], v[78:81]
	v_mfma_f32_16x16x32_bf16 v[70:73], v[188:191], v[236:239], v[70:73]
	v_mfma_f32_16x16x32_bf16 v[122:125], v[192:195], v[208:211], v[122:125]
	v_mfma_f32_16x16x32_bf16 v[114:117], v[200:203], v[208:211], v[114:117]
	v_mfma_f32_16x16x32_bf16 v[106:109], v[192:195], v[216:219], v[106:109]
	v_mfma_f32_16x16x32_bf16 v[98:101], v[200:203], v[216:219], v[98:101]
	v_mfma_f32_16x16x32_bf16 v[90:93], v[192:195], v[224:227], v[90:93]
	v_mfma_f32_16x16x32_bf16 v[82:85], v[200:203], v[224:227], v[82:85]
	v_mfma_f32_16x16x32_bf16 v[74:77], v[192:195], v[232:235], v[74:77]
	v_mfma_f32_16x16x32_bf16 v[66:69], v[200:203], v[232:235], v[66:69]
	v_mfma_f32_16x16x32_bf16 v[122:125], v[196:199], v[212:215], v[122:125]
	v_mfma_f32_16x16x32_bf16 v[114:117], v[204:207], v[212:215], v[114:117]
	v_mfma_f32_16x16x32_bf16 v[106:109], v[196:199], v[220:223], v[106:109]
	v_mfma_f32_16x16x32_bf16 v[98:101], v[204:207], v[220:223], v[98:101]
	v_mfma_f32_16x16x32_bf16 v[90:93], v[196:199], v[228:231], v[90:93]
	v_mfma_f32_16x16x32_bf16 v[82:85], v[204:207], v[228:231], v[82:85]
	v_mfma_f32_16x16x32_bf16 v[74:77], v[196:199], v[236:239], v[74:77]
	v_mfma_f32_16x16x32_bf16 v[66:69], v[204:207], v[236:239], v[66:69]
	s_barrier
	s_add_i32 s66, s66, s24
	v_lshl_add_u64 v[138:139], s[64:65], 0, v[0:1]
	s_mov_b32 m0, s66
	ds_read_b128 v[208:211], v163 offset:16384
	ds_read_b128 v[212:215], v163 offset:17408
	ds_read_b128 v[216:219], v163 offset:18432
	ds_read_b128 v[220:223], v163 offset:19456
	ds_read_b128 v[224:227], v163 offset:20480
	ds_read_b128 v[228:231], v163 offset:21504
	ds_read_b128 v[232:235], v163 offset:22528
	ds_read_b128 v[236:239], v163 offset:23552
	global_load_lds_dwordx4 v[138:139], off
	s_add_i32 m0, s66, 0x2000
	v_lshl_add_u64 v[158:159], s[64:65], 0, v[148:149]
	s_add_u32 s64, s64, s6
	s_addc_u32 s65, s65, s7
	s_add_i32 s63, s63, s24
	global_load_lds_dwordx4 v[158:159], off
	v_lshl_add_u64 v[178:179], s[64:65], 0, v[0:1]
	s_mov_b32 m0, s63
	v_lshl_add_u64 v[240:241], s[64:65], 0, v[148:149]
	global_load_lds_dwordx4 v[178:179], off
	s_add_i32 m0, s63, 0x2000
	v_lshl_add_u64 v[242:243], s[20:21], 0, v[152:153]
	global_load_lds_dwordx4 v[240:241], off
	s_mov_b32 m0, s34
	v_lshl_add_u64 v[244:245], s[20:21], 0, v[150:151]
	global_load_lds_dwordx4 v[242:243], off
	s_mov_b32 m0, s35
	s_nop 0
	global_load_lds_dwordx4 v[244:245], off
	s_waitcnt vmcnt(8)
	s_waitcnt lgkmcnt(0)
	s_barrier
; #define PG8_STAGE(bufoff, gbase, voff) do { _Pragma("unroll") for (int _i = 0; _i < 2; ++_i) \
;         __builtin_amdgcn_global_load_lds((const unsigned*)((const char*)(gbase) + (voff)[_i]), (LAS unsigned*)(lds + (bufoff) + ldsw + _i * 8192), 16, 0, 0); } while (0)
; #define PG8_LDA(dst, b, h) do { _Pragma("unroll") for (int m = 0; m < 4; ++m) _Pragma("unroll") for (int k = 0; k < 2; ++k) dst[m][k] = *(const LAS bf16x8*)(lds + PG8_SA(b, h) + aoff + m * 2048 + k * 1024); } while (0)
; #define PG8_LDB(dst, b, h) do { _Pragma("unroll") for (int n = 0; n < 2; ++n) _Pragma("unroll") for (int k = 0; k < 2; ++k) dst[n][k] = *(const LAS bf16x8*)(lds + PG8_SB(b, h) + boff + n * 2048 + k * 1024); } while (0)
; #define PG8_MMA(ai, bj, At, Bt) do { __builtin_amdgcn_s_setprio(1); _Pragma("unroll") for (int m = 0; m < 4; ++m) _Pragma("unroll") for (int n = 0; n < 2; ++n) _Pragma("unroll") for (int k = 0; k < 2; ++k) \
;         acc[ai][bj][m][n] = __builtin_amdgcn_mfma_f32_16x16x32_bf16(Bt[n][k], At[m][k], acc[ai][bj][m][n], 0, 0, 0); __builtin_amdgcn_s_setprio(0); } while (0)
; #define PG8_WAIT_V(n) asm volatile("s_waitcnt vmcnt(" #n ")" ::: "memory")
; #define PG8_WAIT_L(n) asm volatile("s_waitcnt lgkmcnt(" #n ")" ::: "memory")
; #define PG8_BAR __builtin_amdgcn_s_barrier()
; #define PG8_SCHED __builtin_amdgcn_sched_barrier(0)
; template <class Epi, class Sched, bool HALFN = false>
; __device__ __forceinline__ void gemm_phase(LAS unsigned char* lds, const Gemm g, const Sched& S, const Epi& E) {
;     ...
;             PG8_WAIT_V(8); PG8_WAIT_L(0); PG8_BAR; PG8_MMA(1, 0, At, B0); PG8_MMA(1, 1, At, B1); PG8_BAR; PG8_SCHED;
;             PG8_LDB(B0, 1, 0); PG8_LDB(B1, 1, 1); PG8_SCHED; PG8_LDA(At, 1, 0); PG8_STAGE(PG8_SA(0, 1), a2 + hstep, voffA);
;             PG8_WAIT_V(8); PG8_WAIT_L(0); PG8_BAR; PG8_MMA(0, 0, At, B0); PG8_MMA(0, 1, At, B1); PG8_BAR; PG8_SCHED;
	s_waitcnt lgkmcnt(0)
	v_mfma_f32_16x16x32_bf16 v[62:65], v[164:167], v[208:211], v[62:65]
	v_mfma_f32_16x16x32_bf16 v[54:57], v[184:187], v[208:211], v[54:57]
	v_mfma_f32_16x16x32_bf16 v[46:49], v[164:167], v[216:219], v[46:49]
	v_mfma_f32_16x16x32_bf16 v[38:41], v[184:187], v[216:219], v[38:41]
	v_mfma_f32_16x16x32_bf16 v[30:33], v[164:167], v[224:227], v[30:33]
	v_mfma_f32_16x16x32_bf16 v[22:25], v[184:187], v[224:227], v[22:25]
	v_mfma_f32_16x16x32_bf16 v[14:17], v[164:167], v[232:235], v[14:17]
	v_mfma_f32_16x16x32_bf16 v[6:9], v[184:187], v[232:235], v[6:9]
	v_mfma_f32_16x16x32_bf16 v[62:65], v[180:183], v[212:215], v[62:65]
	v_mfma_f32_16x16x32_bf16 v[54:57], v[188:191], v[212:215], v[54:57]
	v_mfma_f32_16x16x32_bf16 v[46:49], v[180:183], v[220:223], v[46:49]
	v_mfma_f32_16x16x32_bf16 v[38:41], v[188:191], v[220:223], v[38:41]
	v_mfma_f32_16x16x32_bf16 v[30:33], v[180:183], v[228:231], v[30:33]
	v_mfma_f32_16x16x32_bf16 v[22:25], v[188:191], v[228:231], v[22:25]
	v_mfma_f32_16x16x32_bf16 v[14:17], v[180:183], v[236:239], v[14:17]
	v_mfma_f32_16x16x32_bf16 v[6:9], v[188:191], v[236:239], v[6:9]
	v_mfma_f32_16x16x32_bf16 v[58:61], v[192:195], v[208:211], v[58:61]
	v_mfma_f32_16x16x32_bf16 v[50:53], v[200:203], v[208:211], v[50:53]
	v_mfma_f32_16x16x32_bf16 v[42:45], v[192:195], v[216:219], v[42:45]
	v_mfma_f32_16x16x32_bf16 v[34:37], v[200:203], v[216:219], v[34:37]
	v_mfma_f32_16x16x32_bf16 v[26:29], v[192:195], v[224:227], v[26:29]
	v_mfma_f32_16x16x32_bf16 v[18:21], v[200:203], v[224:227], v[18:21]
	v_mfma_f32_16x16x32_bf16 v[10:13], v[192:195], v[232:235], v[10:13]
	v_mfma_f32_16x16x32_bf16 v[2:5], v[200:203], v[232:235], v[2:5]
	v_mfma_f32_16x16x32_bf16 v[58:61], v[196:199], v[212:215], v[58:61]
	v_mfma_f32_16x16x32_bf16 v[50:53], v[204:207], v[212:215], v[50:53]
	v_mfma_f32_16x16x32_bf16 v[42:45], v[196:199], v[220:223], v[42:45]
	v_mfma_f32_16x16x32_bf16 v[34:37], v[204:207], v[220:223], v[34:37]
	v_mfma_f32_16x16x32_bf16 v[26:29], v[196:199], v[228:231], v[26:29]
	v_mfma_f32_16x16x32_bf16 v[18:21], v[204:207], v[228:231], v[18:21]
	v_mfma_f32_16x16x32_bf16 v[10:13], v[196:199], v[236:239], v[10:13]
	v_mfma_f32_16x16x32_bf16 v[2:5], v[204:207], v[236:239], v[2:5]
	s_barrier
	s_add_i32 s63, 0, 0x18000
	s_add_i32 s64, 0, 0x1c000
	v_add_u32_e32 v188, s63, v161
	v_add_u32_e32 v204, s64, v161
	ds_read_b128 v[164:167], v188
	ds_read_b128 v[180:183], v188 offset:1024
	ds_read_b128 v[184:187], v188 offset:2048
	ds_read_b128 v[188:191], v188 offset:3072
	ds_read_b128 v[192:195], v204
	ds_read_b128 v[196:199], v204 offset:1024
	ds_read_b128 v[200:203], v204 offset:2048
	ds_read_b128 v[204:207], v204 offset:3072
	s_add_u32 s20, s20, s6
	s_addc_u32 s21, s21, s7
	s_mov_b32 m0, s40
	v_lshl_add_u64 v[246:247], s[20:21], 0, v[152:153]
	ds_read_b128 v[208:211], v163 offset:32768
	ds_read_b128 v[212:215], v163 offset:33792
	ds_read_b128 v[216:219], v163 offset:34816
	ds_read_b128 v[220:223], v163 offset:35840
	ds_read_b128 v[224:227], v163 offset:36864
	ds_read_b128 v[228:231], v163 offset:37888
	ds_read_b128 v[232:235], v163 offset:38912
	ds_read_b128 v[236:239], v163 offset:39936
	global_load_lds_dwordx4 v[246:247], off
	v_lshl_add_u64 v[246:247], s[20:21], 0, v[150:151]
	s_mov_b32 m0, s41
	s_nop 0
	global_load_lds_dwordx4 v[246:247], off
	s_waitcnt vmcnt(8)
	s_waitcnt lgkmcnt(0)
	s_barrier
	s_waitcnt lgkmcnt(0)
	v_mfma_f32_16x16x32_bf16 v[126:129], v[164:167], v[208:211], v[126:129]
	v_mfma_f32_16x16x32_bf16 v[118:121], v[184:187], v[208:211], v[118:121]
	v_mfma_f32_16x16x32_bf16 v[110:113], v[164:167], v[216:219], v[110:113]
	v_mfma_f32_16x16x32_bf16 v[102:105], v[184:187], v[216:219], v[102:105]
	v_mfma_f32_16x16x32_bf16 v[94:97], v[164:167], v[224:227], v[94:97]
	v_mfma_f32_16x16x32_bf16 v[86:89], v[184:187], v[224:227], v[86:89]
	v_mfma_f32_16x16x32_bf16 v[78:81], v[164:167], v[232:235], v[78:81]
	v_mfma_f32_16x16x32_bf16 v[70:73], v[184:187], v[232:235], v[70:73]
	v_mfma_f32_16x16x32_bf16 v[126:129], v[180:183], v[212:215], v[126:129]
	v_mfma_f32_16x16x32_bf16 v[118:121], v[188:191], v[212:215], v[118:121]
	v_mfma_f32_16x16x32_bf16 v[110:113], v[180:183], v[220:223], v[110:113]
	v_mfma_f32_16x16x32_bf16 v[102:105], v[188:191], v[220:223], v[102:105]
	v_mfma_f32_16x16x32_bf16 v[94:97], v[180:183], v[228:231], v[94:97]
	v_mfma_f32_16x16x32_bf16 v[86:89], v[188:191], v[228:231], v[86:89]
	v_mfma_f32_16x16x32_bf16 v[78:81], v[180:183], v[236:239], v[78:81]
	v_mfma_f32_16x16x32_bf16 v[70:73], v[188:191], v[236:239], v[70:73]
	v_mfma_f32_16x16x32_bf16 v[122:125], v[192:195], v[208:211], v[122:125]
	v_mfma_f32_16x16x32_bf16 v[114:117], v[200:203], v[208:211], v[114:117]
	v_mfma_f32_16x16x32_bf16 v[106:109], v[192:195], v[216:219], v[106:109]
	v_mfma_f32_16x16x32_bf16 v[98:101], v[200:203], v[216:219], v[98:101]
	v_mfma_f32_16x16x32_bf16 v[90:93], v[192:195], v[224:227], v[90:93]
	v_mfma_f32_16x16x32_bf16 v[82:85], v[200:203], v[224:227], v[82:85]
	v_mfma_f32_16x16x32_bf16 v[74:77], v[192:195], v[232:235], v[74:77]
	v_mfma_f32_16x16x32_bf16 v[66:69], v[200:203], v[232:235], v[66:69]
	v_mfma_f32_16x16x32_bf16 v[122:125], v[196:199], v[212:215], v[122:125]
	v_mfma_f32_16x16x32_bf16 v[114:117], v[204:207], v[212:215], v[114:117]
	v_mfma_f32_16x16x32_bf16 v[106:109], v[196:199], v[220:223], v[106:109]
	v_mfma_f32_16x16x32_bf16 v[98:101], v[204:207], v[220:223], v[98:101]
	v_mfma_f32_16x16x32_bf16 v[90:93], v[196:199], v[228:231], v[90:93]
	v_mfma_f32_16x16x32_bf16 v[82:85], v[204:207], v[228:231], v[82:85]
	v_mfma_f32_16x16x32_bf16 v[74:77], v[196:199], v[236:239], v[74:77]
	v_mfma_f32_16x16x32_bf16 v[66:69], v[204:207], v[236:239], v[66:69]
	s_barrier
; #define PG8_STAGE(bufoff, gbase, voff) do { _Pragma("unroll") for (int _i = 0; _i < 2; ++_i) \
;         __builtin_amdgcn_global_load_lds((const unsigned*)((const char*)(gbase) + (voff)[_i]), (LAS unsigned*)(lds + (bufoff) + ldsw + _i * 8192), 16, 0, 0); } while (0)
; #define PG8_LDA(dst, b, h) do { _Pragma("unroll") for (int m = 0; m < 4; ++m) _Pragma("unroll") for (int k = 0; k < 2; ++k) dst[m][k] = *(const LAS bf16x8*)(lds + PG8_SA(b, h) + aoff + m * 2048 + k * 1024); } while (0)
; #define PG8_MMA(ai, bj, At, Bt) do { __builtin_amdgcn_s_setprio(1); _Pragma("unroll") for (int m = 0; m < 4; ++m) _Pragma("unroll") for (int n = 0; n < 2; ++n) _Pragma("unroll") for (int k = 0; k < 2; ++k) \
;         acc[ai][bj][m][n] = __builtin_amdgcn_mfma_f32_16x16x32_bf16(Bt[n][k], At[m][k], acc[ai][bj][m][n], 0, 0, 0); __builtin_amdgcn_s_setprio(0); } while (0)
; #define PG8_WAIT_V(n) asm volatile("s_waitcnt vmcnt(" #n ")" ::: "memory")
; #define PG8_WAIT_L(n) asm volatile("s_waitcnt lgkmcnt(" #n ")" ::: "memory")
; #define PG8_BAR __builtin_amdgcn_s_barrier()
; #define PG8_SCHED __builtin_amdgcn_sched_barrier(0)
; template <class Epi, class Sched, bool HALFN = false>
; __device__ __forceinline__ void gemm_phase(LAS unsigned char* lds, const Gemm g, const Sched& S, const Epi& E) {
;     ...
;             PG8_LDA(At, 1, 1); PG8_STAGE(PG8_SB(1, 0), b3, voffB); PG8_STAGE(PG8_SB(1, 1), b3 + hstep, voffB); PG8_STAGE(PG8_SA(1, 0), a3, voffA);
;             PG8_WAIT_V(8); PG8_WAIT_L(0); PG8_BAR; PG8_MMA(1, 0, At, B0); PG8_MMA(1, 1, At, B1); PG8_BAR; PG8_SCHED;
;             }
;         }
	s_add_i32 s20, s63, s24
	v_lshl_add_u64 v[138:139], v[138:139], 0, s[26:27]
	s_mov_b32 m0, s20
	ds_read_b128 v[208:211], v163 offset:49152
	ds_read_b128 v[212:215], v163 offset:50176
	ds_read_b128 v[216:219], v163 offset:51200
	ds_read_b128 v[220:223], v163 offset:52224
	ds_read_b128 v[224:227], v163 offset:53248
	ds_read_b128 v[228:231], v163 offset:54272
	ds_read_b128 v[232:235], v163 offset:55296
	ds_read_b128 v[236:239], v163 offset:56320
	global_load_lds_dwordx4 v[138:139], off
	v_lshl_add_u64 v[138:139], v[158:159], 0, s[26:27]
	s_add_i32 m0, s20, 0x2000
	s_add_i32 s20, s64, s24
	global_load_lds_dwordx4 v[138:139], off
	v_lshl_add_u64 v[138:139], v[178:179], 0, s[26:27]
	s_mov_b32 m0, s20
	s_nop 0
	global_load_lds_dwordx4 v[138:139], off
	v_lshl_add_u64 v[138:139], v[240:241], 0, s[26:27]
	s_add_i32 m0, s20, 0x2000
	s_nop 0
	global_load_lds_dwordx4 v[138:139], off
	v_lshl_add_u64 v[138:139], v[242:243], 0, s[26:27]
	s_mov_b32 m0, s42
	s_nop 0
	global_load_lds_dwordx4 v[138:139], off
	v_lshl_add_u64 v[138:139], v[244:245], 0, s[26:27]
	s_mov_b32 m0, s43
	s_nop 0
	global_load_lds_dwordx4 v[138:139], off
	s_waitcnt vmcnt(8)
	s_waitcnt lgkmcnt(0)
	s_barrier
	s_waitcnt lgkmcnt(0)
	v_mfma_f32_16x16x32_bf16 v[62:65], v[164:167], v[208:211], v[62:65]
	v_mfma_f32_16x16x32_bf16 v[54:57], v[184:187], v[208:211], v[54:57]
	v_mfma_f32_16x16x32_bf16 v[46:49], v[164:167], v[216:219], v[46:49]
	v_mfma_f32_16x16x32_bf16 v[38:41], v[184:187], v[216:219], v[38:41]
	v_mfma_f32_16x16x32_bf16 v[30:33], v[164:167], v[224:227], v[30:33]
	v_mfma_f32_16x16x32_bf16 v[22:25], v[184:187], v[224:227], v[22:25]
	v_mfma_f32_16x16x32_bf16 v[14:17], v[164:167], v[232:235], v[14:17]
	v_mfma_f32_16x16x32_bf16 v[6:9], v[184:187], v[232:235], v[6:9]
	v_mfma_f32_16x16x32_bf16 v[62:65], v[180:183], v[212:215], v[62:65]
	v_mfma_f32_16x16x32_bf16 v[54:57], v[188:191], v[212:215], v[54:57]
	v_mfma_f32_16x16x32_bf16 v[46:49], v[180:183], v[220:223], v[46:49]
	v_mfma_f32_16x16x32_bf16 v[38:41], v[188:191], v[220:223], v[38:41]
	v_mfma_f32_16x16x32_bf16 v[30:33], v[180:183], v[228:231], v[30:33]
	v_mfma_f32_16x16x32_bf16 v[22:25], v[188:191], v[228:231], v[22:25]
	v_mfma_f32_16x16x32_bf16 v[14:17], v[180:183], v[236:239], v[14:17]
	v_mfma_f32_16x16x32_bf16 v[6:9], v[188:191], v[236:239], v[6:9]
	v_mfma_f32_16x16x32_bf16 v[58:61], v[192:195], v[208:211], v[58:61]
	v_mfma_f32_16x16x32_bf16 v[50:53], v[200:203], v[208:211], v[50:53]
	v_mfma_f32_16x16x32_bf16 v[42:45], v[192:195], v[216:219], v[42:45]
	v_mfma_f32_16x16x32_bf16 v[34:37], v[200:203], v[216:219], v[34:37]
	v_mfma_f32_16x16x32_bf16 v[26:29], v[192:195], v[224:227], v[26:29]
	v_mfma_f32_16x16x32_bf16 v[18:21], v[200:203], v[224:227], v[18:21]
	v_mfma_f32_16x16x32_bf16 v[10:13], v[192:195], v[232:235], v[10:13]
	v_mfma_f32_16x16x32_bf16 v[2:5], v[200:203], v[232:235], v[2:5]
	v_mfma_f32_16x16x32_bf16 v[58:61], v[196:199], v[212:215], v[58:61]
	v_mfma_f32_16x16x32_bf16 v[50:53], v[204:207], v[212:215], v[50:53]
	v_mfma_f32_16x16x32_bf16 v[42:45], v[196:199], v[220:223], v[42:45]
	v_mfma_f32_16x16x32_bf16 v[34:37], v[204:207], v[220:223], v[34:37]
	v_mfma_f32_16x16x32_bf16 v[26:29], v[196:199], v[228:231], v[26:29]
	v_mfma_f32_16x16x32_bf16 v[18:21], v[204:207], v[228:231], v[18:21]
	v_mfma_f32_16x16x32_bf16 v[10:13], v[196:199], v[236:239], v[10:13]
	v_mfma_f32_16x16x32_bf16 v[2:5], v[204:207], v[236:239], v[2:5]
	s_barrier
	s_add_u32 s60, s60, 0x100
	s_addc_u32 s61, s61, 0
	s_add_u32 s18, s18, 0x100
	s_addc_u32 s19, s19, 0
	s_cmp_ge_i32 s62, s44
	s_mov_b32 s20, s62
	s_cbranch_scc0 .LBB0_69

; #define PG8_STAGE(bufoff, gbase, voff) do { _Pragma("unroll") for (int _i = 0; _i < 2; ++_i) \
;         __builtin_amdgcn_global_load_lds((const unsigned*)((const char*)(gbase) + (voff)[_i]), (LAS unsigned*)(lds + (bufoff) + ldsw + _i * 8192), 16, 0, 0); } while (0)
; #define PG8_LDA(dst, b, h) do { _Pragma("unroll") for (int m = 0; m < 4; ++m) _Pragma("unroll") for (int k = 0; k < 2; ++k) dst[m][k] = *(const LAS bf16x8*)(lds + PG8_SA(b, h) + aoff + m * 2048 + k * 1024); } while (0)
; template <class Epi, class Sched, bool HALFN = false>
; __device__ __forceinline__ void gemm_phase(LAS unsigned char* lds, const Gemm g, const Sched& S, const Epi& E) {
;     ...
;         for (int t = 0; t < nt; t += 2) {
;             const bool last = (t == nt - 2);
;             const char* a1 = cA + (size_t)(t + 1) * kstep;
;             const char* a2 = last ? nA : cA + (size_t)(t + 2) * kstep; const char* b2 = last ? nB : cB + (size_t)(t + 2) * kstep;
;             const char* a3 = a2 + kstep; const char* b3 = b2 + kstep;
;             if constexpr (HALFN) {
;             PG8_LDB(B0, 0, 0); PG8_SCHED; PG8_LDA(At, 0, 0); PG8_STAGE(PG8_SA(1, 1), a1 + hstep, voffA);
;             PG8_WAIT_V(6); PG8_WAIT_L(0); PG8_BAR; PG8_MMA(0, 0, At, B0); PG8_BAR; PG8_SCHED;
;             PG8_LDA(At, 0, 1); PG8_STAGE(PG8_SB(0, 0), b2, voffB); PG8_STAGE(PG8_SA(0, 0), a2, voffA);
;             PG8_WAIT_V(6); PG8_WAIT_L(0); PG8_BAR; PG8_MMA(1, 0, At, B0); PG8_BAR; PG8_SCHED;
;             PG8_LDB(B0, 1, 0); PG8_SCHED; PG8_LDA(At, 1, 0); PG8_STAGE(PG8_SA(0, 1), a2 + hstep, voffA);
;             PG8_WAIT_V(6); PG8_WAIT_L(0); PG8_BAR; PG8_MMA(0, 0, At, B0); PG8_BAR; PG8_SCHED;
;             PG8_LDA(At, 1, 1); PG8_STAGE(PG8_SB(1, 0), b3, voffB); PG8_STAGE(PG8_SA(1, 0), a3, voffA);
;             PG8_WAIT_V(6); PG8_WAIT_L(0); PG8_BAR; PG8_MMA(1, 0, At, B0); PG8_BAR; PG8_SCHED;
;             } else {
;             PG8_LDB(B0, 0, 0); PG8_LDB(B1, 0, 1); PG8_SCHED; PG8_LDA(At, 0, 0); PG8_STAGE(PG8_SA(1, 1), a1 + hstep, voffA);
;             PG8_WAIT_V(8); PG8_WAIT_L(0); PG8_BAR; PG8_MMA(0, 0, At, B0); PG8_MMA(0, 1, At, B1); PG8_BAR; PG8_SCHED;
;             PG8_LDA(At, 0, 1); PG8_STAGE(PG8_SB(0, 0), b2, voffB); PG8_STAGE(PG8_SB(0, 1), b2 + hstep, voffB); PG8_STAGE(PG8_SA(0, 0), a2, voffA);
;             PG8_WAIT_V(8); PG8_WAIT_L(0); PG8_BAR; PG8_MMA(1, 0, At, B0); PG8_MMA(1, 1, At, B1); PG8_BAR; PG8_SCHED;
.LBB0_106:
	s_add_i32 s62, s20, 2
	s_add_u32 s63, s18, 0x80
	s_addc_u32 s21, s19, 0
	s_add_i32 s66, 0, 0x10000
	s_cmp_eq_u32 s45, s20
	s_cselect_b32 s21, s5, s21
	s_cselect_b32 s20, s4, s63
	v_add_u32_e32 v138, s66, v161
	s_cselect_b32 s65, s17, s61
	s_cselect_b32 s64, s16, s60
	s_add_i32 s63, 0, 0x14000
	ds_read_b128 v[154:157], v138
	ds_read_b128 v[164:167], v138 offset:1024
	ds_read_b128 v[180:183], v138 offset:2048
	ds_read_b128 v[184:187], v138 offset:3072
	v_add_u32_e32 v138, s63, v161
	ds_read_b128 v[188:191], v138
	ds_read_b128 v[192:195], v138 offset:1024
	ds_read_b128 v[196:199], v138 offset:2048
	ds_read_b128 v[200:203], v138 offset:3072
	v_lshl_add_u64 v[138:139], s[18:19], 0, v[152:153]
	s_add_i32 m0, s34, 0xc000
	ds_read_b128 v[204:207], v163
	ds_read_b128 v[208:211], v163 offset:1024
	ds_read_b128 v[212:215], v163 offset:2048
	ds_read_b128 v[216:219], v163 offset:3072
	ds_read_b128 v[220:223], v163 offset:4096
	ds_read_b128 v[224:227], v163 offset:5120
	ds_read_b128 v[228:231], v163 offset:6144
	ds_read_b128 v[232:235], v163 offset:7168
	global_load_lds_dwordx4 v[138:139], off
	v_lshl_add_u64 v[138:139], s[18:19], 0, v[150:151]
	s_add_i32 m0, s34, 0xe000
	s_nop 0
	global_load_lds_dwordx4 v[138:139], off
	s_waitcnt vmcnt(8)
	s_waitcnt lgkmcnt(0)
	s_barrier
	s_waitcnt lgkmcnt(0)
	v_mfma_f32_16x16x32_bf16 v[126:129], v[154:157], v[204:207], v[126:129]
	v_mfma_f32_16x16x32_bf16 v[122:125], v[180:183], v[204:207], v[122:125]
	v_mfma_f32_16x16x32_bf16 v[110:113], v[154:157], v[212:215], v[110:113]
	v_mfma_f32_16x16x32_bf16 v[106:109], v[180:183], v[212:215], v[106:109]
	v_mfma_f32_16x16x32_bf16 v[94:97], v[154:157], v[220:223], v[94:97]
	v_mfma_f32_16x16x32_bf16 v[90:93], v[180:183], v[220:223], v[90:93]
	v_mfma_f32_16x16x32_bf16 v[78:81], v[154:157], v[228:231], v[78:81]
	v_mfma_f32_16x16x32_bf16 v[74:77], v[180:183], v[228:231], v[74:77]
	v_mfma_f32_16x16x32_bf16 v[126:129], v[164:167], v[208:211], v[126:129]
	v_mfma_f32_16x16x32_bf16 v[122:125], v[184:187], v[208:211], v[122:125]
	v_mfma_f32_16x16x32_bf16 v[110:113], v[164:167], v[216:219], v[110:113]
	v_mfma_f32_16x16x32_bf16 v[106:109], v[184:187], v[216:219], v[106:109]
	v_mfma_f32_16x16x32_bf16 v[94:97], v[164:167], v[224:227], v[94:97]
	v_mfma_f32_16x16x32_bf16 v[90:93], v[184:187], v[224:227], v[90:93]
	v_mfma_f32_16x16x32_bf16 v[78:81], v[164:167], v[232:235], v[78:81]
	v_mfma_f32_16x16x32_bf16 v[74:77], v[184:187], v[232:235], v[74:77]
	v_mfma_f32_16x16x32_bf16 v[118:121], v[188:191], v[204:207], v[118:121]
	v_mfma_f32_16x16x32_bf16 v[114:117], v[196:199], v[204:207], v[114:117]
	v_mfma_f32_16x16x32_bf16 v[102:105], v[188:191], v[212:215], v[102:105]
	v_mfma_f32_16x16x32_bf16 v[98:101], v[196:199], v[212:215], v[98:101]
	v_mfma_f32_16x16x32_bf16 v[86:89], v[188:191], v[220:223], v[86:89]
	v_mfma_f32_16x16x32_bf16 v[82:85], v[196:199], v[220:223], v[82:85]
	v_mfma_f32_16x16x32_bf16 v[70:73], v[188:191], v[228:231], v[70:73]
	v_mfma_f32_16x16x32_bf16 v[66:69], v[196:199], v[228:231], v[66:69]
	v_mfma_f32_16x16x32_bf16 v[118:121], v[192:195], v[208:211], v[118:121]
	v_mfma_f32_16x16x32_bf16 v[114:117], v[200:203], v[208:211], v[114:117]
	v_mfma_f32_16x16x32_bf16 v[102:105], v[192:195], v[216:219], v[102:105]
	v_mfma_f32_16x16x32_bf16 v[98:101], v[200:203], v[216:219], v[98:101]
	v_mfma_f32_16x16x32_bf16 v[86:89], v[192:195], v[224:227], v[86:89]
	v_mfma_f32_16x16x32_bf16 v[82:85], v[200:203], v[224:227], v[82:85]
	v_mfma_f32_16x16x32_bf16 v[70:73], v[192:195], v[232:235], v[70:73]
	v_mfma_f32_16x16x32_bf16 v[66:69], v[200:203], v[232:235], v[66:69]
	s_barrier
	s_add_i32 s66, s66, s25
	v_lshl_add_u64 v[138:139], s[64:65], 0, v[0:1]
	s_mov_b32 m0, s66
	ds_read_b128 v[204:207], v163 offset:16384
	ds_read_b128 v[208:211], v163 offset:17408
	ds_read_b128 v[212:215], v163 offset:18432
	ds_read_b128 v[216:219], v163 offset:19456
	ds_read_b128 v[220:223], v163 offset:20480
	ds_read_b128 v[224:227], v163 offset:21504
	ds_read_b128 v[228:231], v163 offset:22528
	ds_read_b128 v[232:235], v163 offset:23552
	global_load_lds_dwordx4 v[138:139], off
	s_add_i32 m0, s66, 0x2000
	v_lshl_add_u64 v[158:159], s[64:65], 0, v[148:149]
	s_add_u32 s64, s64, s6
	s_addc_u32 s65, s65, s7
	s_add_i32 s63, s63, s25
	global_load_lds_dwordx4 v[158:159], off
	v_lshl_add_u64 v[178:179], s[64:65], 0, v[0:1]
	s_mov_b32 m0, s63
	v_lshl_add_u64 v[236:237], s[64:65], 0, v[148:149]
	global_load_lds_dwordx4 v[178:179], off
	s_add_i32 m0, s63, 0x2000
	v_lshl_add_u64 v[238:239], s[20:21], 0, v[0:1]
	global_load_lds_dwordx4 v[236:237], off
	s_mov_b32 m0, s34
	v_lshl_add_u64 v[240:241], s[20:21], 0, v[148:149]
	global_load_lds_dwordx4 v[238:239], off
	s_mov_b32 m0, s35
	s_nop 0
	global_load_lds_dwordx4 v[240:241], off
	s_waitcnt vmcnt(8)
	s_waitcnt lgkmcnt(0)
	s_barrier
; #define PG8_STAGE(bufoff, gbase, voff) do { _Pragma("unroll") for (int _i = 0; _i < 2; ++_i) \
;         __builtin_amdgcn_global_load_lds((const unsigned*)((const char*)(gbase) + (voff)[_i]), (LAS unsigned*)(lds + (bufoff) + ldsw + _i * 8192), 16, 0, 0); } while (0)
; #define PG8_LDA(dst, b, h) do { _Pragma("unroll") for (int m = 0; m < 4; ++m) _Pragma("unroll") for (int k = 0; k < 2; ++k) dst[m][k] = *(const LAS bf16x8*)(lds + PG8_SA(b, h) + aoff + m * 2048 + k * 1024); } while (0)
; #define PG8_LDB(dst, b, h) do { _Pragma("unroll") for (int n = 0; n < 2; ++n) _Pragma("unroll") for (int k = 0; k < 2; ++k) dst[n][k] = *(const LAS bf16x8*)(lds + PG8_SB(b, h) + boff + n * 2048 + k * 1024); } while (0)
; #define PG8_MMA(ai, bj, At, Bt) do { __builtin_amdgcn_s_setprio(1); _Pragma("unroll") for (int m = 0; m < 4; ++m) _Pragma("unroll") for (int n = 0; n < 2; ++n) _Pragma("unroll") for (int k = 0; k < 2; ++k) \
;         acc[ai][bj][m][n] = __builtin_amdgcn_mfma_f32_16x16x32_bf16(Bt[n][k], At[m][k], acc[ai][bj][m][n], 0, 0, 0); __builtin_amdgcn_s_setprio(0); } while (0)
; #define PG8_WAIT_V(n) asm volatile("s_waitcnt vmcnt(" #n ")" ::: "memory")
; #define PG8_WAIT_L(n) asm volatile("s_waitcnt lgkmcnt(" #n ")" ::: "memory")
; #define PG8_BAR __builtin_amdgcn_s_barrier()
; #define PG8_SCHED __builtin_amdgcn_sched_barrier(0)
; template <class Epi, class Sched, bool HALFN = false>
; __device__ __forceinline__ void gemm_phase(LAS unsigned char* lds, const Gemm g, const Sched& S, const Epi& E) {
;     ...
;             PG8_WAIT_V(8); PG8_WAIT_L(0); PG8_BAR; PG8_MMA(1, 0, At, B0); PG8_MMA(1, 1, At, B1); PG8_BAR; PG8_SCHED;
;             PG8_LDB(B0, 1, 0); PG8_LDB(B1, 1, 1); PG8_SCHED; PG8_LDA(At, 1, 0); PG8_STAGE(PG8_SA(0, 1), a2 + hstep, voffA);
;             PG8_WAIT_V(8); PG8_WAIT_L(0); PG8_BAR; PG8_MMA(0, 0, At, B0); PG8_MMA(0, 1, At, B1); PG8_BAR; PG8_SCHED;
	s_waitcnt lgkmcnt(0)
	v_mfma_f32_16x16x32_bf16 v[62:65], v[154:157], v[204:207], v[62:65]
	v_mfma_f32_16x16x32_bf16 v[58:61], v[180:183], v[204:207], v[58:61]
	v_mfma_f32_16x16x32_bf16 v[46:49], v[154:157], v[212:215], v[46:49]
	v_mfma_f32_16x16x32_bf16 v[42:45], v[180:183], v[212:215], v[42:45]
	v_mfma_f32_16x16x32_bf16 v[30:33], v[154:157], v[220:223], v[30:33]
	v_mfma_f32_16x16x32_bf16 v[26:29], v[180:183], v[220:223], v[26:29]
	v_mfma_f32_16x16x32_bf16 v[14:17], v[154:157], v[228:231], v[14:17]
	v_mfma_f32_16x16x32_bf16 v[10:13], v[180:183], v[228:231], v[10:13]
	v_mfma_f32_16x16x32_bf16 v[62:65], v[164:167], v[208:211], v[62:65]
	v_mfma_f32_16x16x32_bf16 v[58:61], v[184:187], v[208:211], v[58:61]
	v_mfma_f32_16x16x32_bf16 v[46:49], v[164:167], v[216:219], v[46:49]
	v_mfma_f32_16x16x32_bf16 v[42:45], v[184:187], v[216:219], v[42:45]
	v_mfma_f32_16x16x32_bf16 v[30:33], v[164:167], v[224:227], v[30:33]
	v_mfma_f32_16x16x32_bf16 v[26:29], v[184:187], v[224:227], v[26:29]
	v_mfma_f32_16x16x32_bf16 v[14:17], v[164:167], v[232:235], v[14:17]
	v_mfma_f32_16x16x32_bf16 v[10:13], v[184:187], v[232:235], v[10:13]
	v_mfma_f32_16x16x32_bf16 v[54:57], v[188:191], v[204:207], v[54:57]
	v_mfma_f32_16x16x32_bf16 v[50:53], v[196:199], v[204:207], v[50:53]
	v_mfma_f32_16x16x32_bf16 v[38:41], v[188:191], v[212:215], v[38:41]
	v_mfma_f32_16x16x32_bf16 v[34:37], v[196:199], v[212:215], v[34:37]
	v_mfma_f32_16x16x32_bf16 v[22:25], v[188:191], v[220:223], v[22:25]
	v_mfma_f32_16x16x32_bf16 v[18:21], v[196:199], v[220:223], v[18:21]
	v_mfma_f32_16x16x32_bf16 v[6:9], v[188:191], v[228:231], v[6:9]
	v_mfma_f32_16x16x32_bf16 v[2:5], v[196:199], v[228:231], v[2:5]
	v_mfma_f32_16x16x32_bf16 v[54:57], v[192:195], v[208:211], v[54:57]
	v_mfma_f32_16x16x32_bf16 v[50:53], v[200:203], v[208:211], v[50:53]
	v_mfma_f32_16x16x32_bf16 v[38:41], v[192:195], v[216:219], v[38:41]
	v_mfma_f32_16x16x32_bf16 v[34:37], v[200:203], v[216:219], v[34:37]
	v_mfma_f32_16x16x32_bf16 v[22:25], v[192:195], v[224:227], v[22:25]
	v_mfma_f32_16x16x32_bf16 v[18:21], v[200:203], v[224:227], v[18:21]
	v_mfma_f32_16x16x32_bf16 v[6:9], v[192:195], v[232:235], v[6:9]
	v_mfma_f32_16x16x32_bf16 v[2:5], v[200:203], v[232:235], v[2:5]
	s_barrier
	s_add_i32 s63, 0, 0x18000
	s_add_i32 s64, 0, 0x1c000
	v_add_u32_e32 v184, s63, v161
	v_add_u32_e32 v200, s64, v161
	ds_read_b128 v[154:157], v184
	ds_read_b128 v[164:167], v184 offset:1024
	ds_read_b128 v[180:183], v184 offset:2048
	ds_read_b128 v[184:187], v184 offset:3072
	ds_read_b128 v[188:191], v200
	ds_read_b128 v[192:195], v200 offset:1024
	ds_read_b128 v[196:199], v200 offset:2048
	ds_read_b128 v[200:203], v200 offset:3072
	s_add_u32 s20, s20, s6
	s_addc_u32 s21, s21, s7
	s_mov_b32 m0, s40
	v_lshl_add_u64 v[242:243], s[20:21], 0, v[0:1]
	ds_read_b128 v[204:207], v163 offset:32768
	ds_read_b128 v[208:211], v163 offset:33792
	ds_read_b128 v[212:215], v163 offset:34816
	ds_read_b128 v[216:219], v163 offset:35840
	ds_read_b128 v[220:223], v163 offset:36864
	ds_read_b128 v[224:227], v163 offset:37888
	ds_read_b128 v[228:231], v163 offset:38912
	ds_read_b128 v[232:235], v163 offset:39936
	global_load_lds_dwordx4 v[242:243], off
	v_lshl_add_u64 v[242:243], s[20:21], 0, v[148:149]
	s_mov_b32 m0, s41
	s_nop 0
	global_load_lds_dwordx4 v[242:243], off
	s_waitcnt vmcnt(8)
	s_waitcnt lgkmcnt(0)
	s_barrier
	s_waitcnt lgkmcnt(0)
	v_mfma_f32_16x16x32_bf16 v[126:129], v[154:157], v[204:207], v[126:129]
	v_mfma_f32_16x16x32_bf16 v[122:125], v[180:183], v[204:207], v[122:125]
	v_mfma_f32_16x16x32_bf16 v[110:113], v[154:157], v[212:215], v[110:113]
	v_mfma_f32_16x16x32_bf16 v[106:109], v[180:183], v[212:215], v[106:109]
	v_mfma_f32_16x16x32_bf16 v[94:97], v[154:157], v[220:223], v[94:97]
	v_mfma_f32_16x16x32_bf16 v[90:93], v[180:183], v[220:223], v[90:93]
	v_mfma_f32_16x16x32_bf16 v[78:81], v[154:157], v[228:231], v[78:81]
	v_mfma_f32_16x16x32_bf16 v[74:77], v[180:183], v[228:231], v[74:77]
	v_mfma_f32_16x16x32_bf16 v[126:129], v[164:167], v[208:211], v[126:129]
	v_mfma_f32_16x16x32_bf16 v[122:125], v[184:187], v[208:211], v[122:125]
	v_mfma_f32_16x16x32_bf16 v[110:113], v[164:167], v[216:219], v[110:113]
	v_mfma_f32_16x16x32_bf16 v[106:109], v[184:187], v[216:219], v[106:109]
	v_mfma_f32_16x16x32_bf16 v[94:97], v[164:167], v[224:227], v[94:97]
	v_mfma_f32_16x16x32_bf16 v[90:93], v[184:187], v[224:227], v[90:93]
	v_mfma_f32_16x16x32_bf16 v[78:81], v[164:167], v[232:235], v[78:81]
	v_mfma_f32_16x16x32_bf16 v[74:77], v[184:187], v[232:235], v[74:77]
	v_mfma_f32_16x16x32_bf16 v[118:121], v[188:191], v[204:207], v[118:121]
	v_mfma_f32_16x16x32_bf16 v[114:117], v[196:199], v[204:207], v[114:117]
	v_mfma_f32_16x16x32_bf16 v[102:105], v[188:191], v[212:215], v[102:105]
	v_mfma_f32_16x16x32_bf16 v[98:101], v[196:199], v[212:215], v[98:101]
	v_mfma_f32_16x16x32_bf16 v[86:89], v[188:191], v[220:223], v[86:89]
	v_mfma_f32_16x16x32_bf16 v[82:85], v[196:199], v[220:223], v[82:85]
	v_mfma_f32_16x16x32_bf16 v[70:73], v[188:191], v[228:231], v[70:73]
	v_mfma_f32_16x16x32_bf16 v[66:69], v[196:199], v[228:231], v[66:69]
	v_mfma_f32_16x16x32_bf16 v[118:121], v[192:195], v[208:211], v[118:121]
	v_mfma_f32_16x16x32_bf16 v[114:117], v[200:203], v[208:211], v[114:117]
	v_mfma_f32_16x16x32_bf16 v[102:105], v[192:195], v[216:219], v[102:105]
	v_mfma_f32_16x16x32_bf16 v[98:101], v[200:203], v[216:219], v[98:101]
	v_mfma_f32_16x16x32_bf16 v[86:89], v[192:195], v[224:227], v[86:89]
	v_mfma_f32_16x16x32_bf16 v[82:85], v[200:203], v[224:227], v[82:85]
	v_mfma_f32_16x16x32_bf16 v[70:73], v[192:195], v[232:235], v[70:73]
	v_mfma_f32_16x16x32_bf16 v[66:69], v[200:203], v[232:235], v[66:69]
	s_barrier
; #define PG8_STAGE(bufoff, gbase, voff) do { _Pragma("unroll") for (int _i = 0; _i < 2; ++_i) \
;         __builtin_amdgcn_global_load_lds((const unsigned*)((const char*)(gbase) + (voff)[_i]), (LAS unsigned*)(lds + (bufoff) + ldsw + _i * 8192), 16, 0, 0); } while (0)
; #define PG8_LDA(dst, b, h) do { _Pragma("unroll") for (int m = 0; m < 4; ++m) _Pragma("unroll") for (int k = 0; k < 2; ++k) dst[m][k] = *(const LAS bf16x8*)(lds + PG8_SA(b, h) + aoff + m * 2048 + k * 1024); } while (0)
; #define PG8_MMA(ai, bj, At, Bt) do { __builtin_amdgcn_s_setprio(1); _Pragma("unroll") for (int m = 0; m < 4; ++m) _Pragma("unroll") for (int n = 0; n < 2; ++n) _Pragma("unroll") for (int k = 0; k < 2; ++k) \
;         acc[ai][bj][m][n] = __builtin_amdgcn_mfma_f32_16x16x32_bf16(Bt[n][k], At[m][k], acc[ai][bj][m][n], 0, 0, 0); __builtin_amdgcn_s_setprio(0); } while (0)
; #define PG8_WAIT_V(n) asm volatile("s_waitcnt vmcnt(" #n ")" ::: "memory")
; #define PG8_WAIT_L(n) asm volatile("s_waitcnt lgkmcnt(" #n ")" ::: "memory")
; #define PG8_BAR __builtin_amdgcn_s_barrier()
; #define PG8_SCHED __builtin_amdgcn_sched_barrier(0)
; template <class Epi, class Sched, bool HALFN = false>
; __device__ __forceinline__ void gemm_phase(LAS unsigned char* lds, const Gemm g, const Sched& S, const Epi& E) {
;     ...
;             PG8_LDA(At, 1, 1); PG8_STAGE(PG8_SB(1, 0), b3, voffB); PG8_STAGE(PG8_SB(1, 1), b3 + hstep, voffB); PG8_STAGE(PG8_SA(1, 0), a3, voffA);
;             PG8_WAIT_V(8); PG8_WAIT_L(0); PG8_BAR; PG8_MMA(1, 0, At, B0); PG8_MMA(1, 1, At, B1); PG8_BAR; PG8_SCHED;
;             }
;         }
	s_add_i32 s20, s63, s25
	v_lshl_add_u64 v[138:139], v[138:139], 0, s[26:27]
	s_mov_b32 m0, s20
	ds_read_b128 v[204:207], v163 offset:49152
	ds_read_b128 v[208:211], v163 offset:50176
	ds_read_b128 v[212:215], v163 offset:51200
	ds_read_b128 v[216:219], v163 offset:52224
	ds_read_b128 v[220:223], v163 offset:53248
	ds_read_b128 v[224:227], v163 offset:54272
	ds_read_b128 v[228:231], v163 offset:55296
	ds_read_b128 v[232:235], v163 offset:56320
	global_load_lds_dwordx4 v[138:139], off
	v_lshl_add_u64 v[138:139], v[158:159], 0, s[26:27]
	s_add_i32 m0, s20, 0x2000
	s_add_i32 s20, s64, s25
	global_load_lds_dwordx4 v[138:139], off
	v_lshl_add_u64 v[138:139], v[178:179], 0, s[26:27]
	s_mov_b32 m0, s20
	s_nop 0
	global_load_lds_dwordx4 v[138:139], off
	v_lshl_add_u64 v[138:139], v[236:237], 0, s[26:27]
	s_add_i32 m0, s20, 0x2000
	s_nop 0
	global_load_lds_dwordx4 v[138:139], off
	v_lshl_add_u64 v[138:139], v[238:239], 0, s[26:27]
	s_mov_b32 m0, s43
	s_nop 0
	global_load_lds_dwordx4 v[138:139], off
	v_lshl_add_u64 v[138:139], v[240:241], 0, s[26:27]
	s_mov_b32 m0, s44
	s_nop 0
	global_load_lds_dwordx4 v[138:139], off
	s_waitcnt vmcnt(8)
	s_waitcnt lgkmcnt(0)
	s_barrier
	s_waitcnt lgkmcnt(0)
	v_mfma_f32_16x16x32_bf16 v[62:65], v[154:157], v[204:207], v[62:65]
	v_mfma_f32_16x16x32_bf16 v[58:61], v[180:183], v[204:207], v[58:61]
	v_mfma_f32_16x16x32_bf16 v[46:49], v[154:157], v[212:215], v[46:49]
	v_mfma_f32_16x16x32_bf16 v[42:45], v[180:183], v[212:215], v[42:45]
	v_mfma_f32_16x16x32_bf16 v[30:33], v[154:157], v[220:223], v[30:33]
	v_mfma_f32_16x16x32_bf16 v[26:29], v[180:183], v[220:223], v[26:29]
	v_mfma_f32_16x16x32_bf16 v[14:17], v[154:157], v[228:231], v[14:17]
	v_mfma_f32_16x16x32_bf16 v[10:13], v[180:183], v[228:231], v[10:13]
	v_mfma_f32_16x16x32_bf16 v[62:65], v[164:167], v[208:211], v[62:65]
	v_mfma_f32_16x16x32_bf16 v[58:61], v[184:187], v[208:211], v[58:61]
	v_mfma_f32_16x16x32_bf16 v[46:49], v[164:167], v[216:219], v[46:49]
	v_mfma_f32_16x16x32_bf16 v[42:45], v[184:187], v[216:219], v[42:45]
	v_mfma_f32_16x16x32_bf16 v[30:33], v[164:167], v[224:227], v[30:33]
	v_mfma_f32_16x16x32_bf16 v[26:29], v[184:187], v[224:227], v[26:29]
	v_mfma_f32_16x16x32_bf16 v[14:17], v[164:167], v[232:235], v[14:17]
	v_mfma_f32_16x16x32_bf16 v[10:13], v[184:187], v[232:235], v[10:13]
	v_mfma_f32_16x16x32_bf16 v[54:57], v[188:191], v[204:207], v[54:57]
	v_mfma_f32_16x16x32_bf16 v[50:53], v[196:199], v[204:207], v[50:53]
	v_mfma_f32_16x16x32_bf16 v[38:41], v[188:191], v[212:215], v[38:41]
	v_mfma_f32_16x16x32_bf16 v[34:37], v[196:199], v[212:215], v[34:37]
	v_mfma_f32_16x16x32_bf16 v[22:25], v[188:191], v[220:223], v[22:25]
	v_mfma_f32_16x16x32_bf16 v[18:21], v[196:199], v[220:223], v[18:21]
	v_mfma_f32_16x16x32_bf16 v[6:9], v[188:191], v[228:231], v[6:9]
	v_mfma_f32_16x16x32_bf16 v[2:5], v[196:199], v[228:231], v[2:5]
	v_mfma_f32_16x16x32_bf16 v[54:57], v[192:195], v[208:211], v[54:57]
	v_mfma_f32_16x16x32_bf16 v[50:53], v[200:203], v[208:211], v[50:53]
	v_mfma_f32_16x16x32_bf16 v[38:41], v[192:195], v[216:219], v[38:41]
	v_mfma_f32_16x16x32_bf16 v[34:37], v[200:203], v[216:219], v[34:37]
	v_mfma_f32_16x16x32_bf16 v[22:25], v[192:195], v[224:227], v[22:25]
	v_mfma_f32_16x16x32_bf16 v[18:21], v[200:203], v[224:227], v[18:21]
	v_mfma_f32_16x16x32_bf16 v[6:9], v[192:195], v[232:235], v[6:9]
	v_mfma_f32_16x16x32_bf16 v[2:5], v[200:203], v[232:235], v[2:5]
	s_barrier
	s_add_u32 s60, s60, 0x100
	s_addc_u32 s61, s61, 0
	s_add_u32 s18, s18, 0x100
	s_addc_u32 s19, s19, 0
	s_cmp_ge_i32 s62, s42
	s_mov_b32 s20, s62
	s_cbranch_scc0 .LBB0_106

; #define PG8_STAGE(bufoff, gbase, voff) do { _Pragma("unroll") for (int _i = 0; _i < 2; ++_i) \
;         __builtin_amdgcn_global_load_lds((const unsigned*)((const char*)(gbase) + (voff)[_i]), (LAS unsigned*)(lds + (bufoff) + ldsw + _i * 8192), 16, 0, 0); } while (0)
; #define PG8_LDA(dst, b, h) do { _Pragma("unroll") for (int m = 0; m < 4; ++m) _Pragma("unroll") for (int k = 0; k < 2; ++k) dst[m][k] = *(const LAS bf16x8*)(lds + PG8_SA(b, h) + aoff + m * 2048 + k * 1024); } while (0)
; #define PG8_LDB(dst, b, h) do { _Pragma("unroll") for (int n = 0; n < 2; ++n) _Pragma("unroll") for (int k = 0; k < 2; ++k) dst[n][k] = *(const LAS bf16x8*)(lds + PG8_SB(b, h) + boff + n * 2048 + k * 1024); } while (0)
; #define PG8_MMA(ai, bj, At, Bt) do { __builtin_amdgcn_s_setprio(1); _Pragma("unroll") for (int m = 0; m < 4; ++m) _Pragma("unroll") for (int n = 0; n < 2; ++n) _Pragma("unroll") for (int k = 0; k < 2; ++k) \
;         acc[ai][bj][m][n] = __builtin_amdgcn_mfma_f32_16x16x32_bf16(Bt[n][k], At[m][k], acc[ai][bj][m][n], 0, 0, 0); __builtin_amdgcn_s_setprio(0); } while (0)
; #define PG8_WAIT_V(n) asm volatile("s_waitcnt vmcnt(" #n ")" ::: "memory")
; #define PG8_WAIT_L(n) asm volatile("s_waitcnt lgkmcnt(" #n ")" ::: "memory")
; #define PG8_BAR __builtin_amdgcn_s_barrier()
; #define PG8_SCHED __builtin_amdgcn_sched_barrier(0)
; template <class Epi, class Sched, bool HALFN = false>
; __device__ __forceinline__ void gemm_phase(LAS unsigned char* lds, const Gemm g, const Sched& S, const Epi& E) {
;     ...
;             if constexpr (HALFN) {
;             PG8_LDB(B0, 0, 0); PG8_SCHED; PG8_LDA(At, 0, 0); PG8_STAGE(PG8_SA(1, 1), a1 + hstep, voffA);
;             PG8_WAIT_V(6); PG8_WAIT_L(0); PG8_BAR; PG8_MMA(0, 0, At, B0); PG8_BAR; PG8_SCHED;
;             PG8_LDA(At, 0, 1); PG8_STAGE(PG8_SB(0, 0), b2, voffB); PG8_STAGE(PG8_SA(0, 0), a2, voffA);
;             PG8_WAIT_V(6); PG8_WAIT_L(0); PG8_BAR; PG8_MMA(1, 0, At, B0); PG8_BAR; PG8_SCHED;
.LBB0_137:
	s_add_i32 s24, s6, 2
	s_add_u32 s25, s4, 0x80
	s_addc_u32 s7, s5, 0
	s_add_i32 s67, 0, 0x10000
	v_add_u32_e32 v138, s67, v163
	ds_read_b128 v[158:161], v138
	ds_read_b128 v[180:183], v138 offset:1024
	ds_read_b128 v[184:187], v138 offset:2048
	ds_read_b128 v[188:191], v138 offset:3072
	s_cmp_eq_u32 s59, s6
	s_cselect_b32 s6, s20, s25
	s_cselect_b32 s7, s21, s7
	s_cselect_b32 s69, s23, s66
	s_cselect_b32 s68, s22, s19
	v_lshl_add_u64 v[138:139], s[4:5], 0, v[74:75]
	s_add_i32 m0, s43, 0xc000
	ds_read_b128 v[192:195], v165
	ds_read_b128 v[196:199], v165 offset:1024
	ds_read_b128 v[200:203], v165 offset:2048
	ds_read_b128 v[204:207], v165 offset:3072
	ds_read_b128 v[208:211], v165 offset:4096
	ds_read_b128 v[212:215], v165 offset:5120
	ds_read_b128 v[216:219], v165 offset:6144
	ds_read_b128 v[220:223], v165 offset:7168
	global_load_lds_dwordx4 v[138:139], off
	v_lshl_add_u64 v[138:139], s[4:5], 0, v[72:73]
	s_add_i32 m0, s43, 0xe000
	s_nop 0
	global_load_lds_dwordx4 v[138:139], off
	s_waitcnt vmcnt(6)
	s_waitcnt lgkmcnt(0)
	s_barrier
	s_waitcnt lgkmcnt(0)
	v_mfma_f32_16x16x32_bf16 v[58:61], v[158:161], v[192:195], v[58:61]
	v_mfma_f32_16x16x32_bf16 v[62:65], v[184:187], v[192:195], v[62:65]
	v_mfma_f32_16x16x32_bf16 v[54:57], v[158:161], v[200:203], v[54:57]
	v_mfma_f32_16x16x32_bf16 v[50:53], v[184:187], v[200:203], v[50:53]
	v_mfma_f32_16x16x32_bf16 v[46:49], v[158:161], v[208:211], v[46:49]
	v_mfma_f32_16x16x32_bf16 v[42:45], v[184:187], v[208:211], v[42:45]
	v_mfma_f32_16x16x32_bf16 v[38:41], v[158:161], v[216:219], v[38:41]
	v_mfma_f32_16x16x32_bf16 v[34:37], v[184:187], v[216:219], v[34:37]
	v_mfma_f32_16x16x32_bf16 v[58:61], v[180:183], v[196:199], v[58:61]
	v_mfma_f32_16x16x32_bf16 v[62:65], v[188:191], v[196:199], v[62:65]
	v_mfma_f32_16x16x32_bf16 v[54:57], v[180:183], v[204:207], v[54:57]
	v_mfma_f32_16x16x32_bf16 v[50:53], v[188:191], v[204:207], v[50:53]
	v_mfma_f32_16x16x32_bf16 v[46:49], v[180:183], v[212:215], v[46:49]
	v_mfma_f32_16x16x32_bf16 v[42:45], v[188:191], v[212:215], v[42:45]
	v_mfma_f32_16x16x32_bf16 v[38:41], v[180:183], v[220:223], v[38:41]
	v_mfma_f32_16x16x32_bf16 v[34:37], v[188:191], v[220:223], v[34:37]
	s_barrier
	s_add_i32 s25, s67, s42
	v_lshl_add_u64 v[138:139], s[68:69], 0, v[0:1]
	s_mov_b32 m0, s25
	ds_read_b128 v[192:195], v165 offset:16384
	ds_read_b128 v[196:199], v165 offset:17408
	ds_read_b128 v[200:203], v165 offset:18432
	ds_read_b128 v[204:207], v165 offset:19456
	ds_read_b128 v[208:211], v165 offset:20480
	ds_read_b128 v[212:215], v165 offset:21504
	ds_read_b128 v[216:219], v165 offset:22528
	ds_read_b128 v[220:223], v165 offset:23552
	global_load_lds_dwordx4 v[138:139], off
	v_lshl_add_u64 v[166:167], s[68:69], 0, v[70:71]
	s_add_i32 m0, s25, 0x2000
	v_lshl_add_u64 v[178:179], s[6:7], 0, v[66:67]
	global_load_lds_dwordx4 v[166:167], off
	s_mov_b32 m0, s43
	v_lshl_add_u64 v[224:225], s[6:7], 0, v[68:69]
	global_load_lds_dwordx4 v[178:179], off
	s_mov_b32 m0, s44
	s_nop 0
	global_load_lds_dwordx4 v[224:225], off
	s_waitcnt vmcnt(6)
	s_waitcnt lgkmcnt(0)
	s_barrier
	s_waitcnt lgkmcnt(0)
	v_mfma_f32_16x16x32_bf16 v[30:33], v[158:161], v[192:195], v[30:33]
	v_mfma_f32_16x16x32_bf16 v[26:29], v[184:187], v[192:195], v[26:29]
	v_mfma_f32_16x16x32_bf16 v[22:25], v[158:161], v[200:203], v[22:25]
	v_mfma_f32_16x16x32_bf16 v[18:21], v[184:187], v[200:203], v[18:21]
	v_mfma_f32_16x16x32_bf16 v[14:17], v[158:161], v[208:211], v[14:17]
	v_mfma_f32_16x16x32_bf16 v[10:13], v[184:187], v[208:211], v[10:13]
	v_mfma_f32_16x16x32_bf16 v[6:9], v[158:161], v[216:219], v[6:9]
	v_mfma_f32_16x16x32_bf16 v[2:5], v[184:187], v[216:219], v[2:5]
	v_mfma_f32_16x16x32_bf16 v[30:33], v[180:183], v[196:199], v[30:33]
	v_mfma_f32_16x16x32_bf16 v[26:29], v[188:191], v[196:199], v[26:29]
	v_mfma_f32_16x16x32_bf16 v[22:25], v[180:183], v[204:207], v[22:25]
	v_mfma_f32_16x16x32_bf16 v[18:21], v[188:191], v[204:207], v[18:21]
	v_mfma_f32_16x16x32_bf16 v[14:17], v[180:183], v[212:215], v[14:17]
	v_mfma_f32_16x16x32_bf16 v[10:13], v[188:191], v[212:215], v[10:13]
	v_mfma_f32_16x16x32_bf16 v[6:9], v[180:183], v[220:223], v[6:9]
	v_mfma_f32_16x16x32_bf16 v[2:5], v[188:191], v[220:223], v[2:5]
	s_barrier
; #define PG8_STAGE(bufoff, gbase, voff) do { _Pragma("unroll") for (int _i = 0; _i < 2; ++_i) \
;         __builtin_amdgcn_global_load_lds((const unsigned*)((const char*)(gbase) + (voff)[_i]), (LAS unsigned*)(lds + (bufoff) + ldsw + _i * 8192), 16, 0, 0); } while (0)
; #define PG8_LDA(dst, b, h) do { _Pragma("unroll") for (int m = 0; m < 4; ++m) _Pragma("unroll") for (int k = 0; k < 2; ++k) dst[m][k] = *(const LAS bf16x8*)(lds + PG8_SA(b, h) + aoff + m * 2048 + k * 1024); } while (0)
; #define PG8_LDB(dst, b, h) do { _Pragma("unroll") for (int n = 0; n < 2; ++n) _Pragma("unroll") for (int k = 0; k < 2; ++k) dst[n][k] = *(const LAS bf16x8*)(lds + PG8_SB(b, h) + boff + n * 2048 + k * 1024); } while (0)
; #define PG8_MMA(ai, bj, At, Bt) do { __builtin_amdgcn_s_setprio(1); _Pragma("unroll") for (int m = 0; m < 4; ++m) _Pragma("unroll") for (int n = 0; n < 2; ++n) _Pragma("unroll") for (int k = 0; k < 2; ++k) \
;         acc[ai][bj][m][n] = __builtin_amdgcn_mfma_f32_16x16x32_bf16(Bt[n][k], At[m][k], acc[ai][bj][m][n], 0, 0, 0); __builtin_amdgcn_s_setprio(0); } while (0)
; #define PG8_WAIT_V(n) asm volatile("s_waitcnt vmcnt(" #n ")" ::: "memory")
; #define PG8_WAIT_L(n) asm volatile("s_waitcnt lgkmcnt(" #n ")" ::: "memory")
; #define PG8_BAR __builtin_amdgcn_s_barrier()
; #define PG8_SCHED __builtin_amdgcn_sched_barrier(0)
; template <class Epi, class Sched, bool HALFN = false>
; __device__ __forceinline__ void gemm_phase(LAS unsigned char* lds, const Gemm g, const Sched& S, const Epi& E) {
;     ...
;             PG8_LDB(B0, 1, 0); PG8_SCHED; PG8_LDA(At, 1, 0); PG8_STAGE(PG8_SA(0, 1), a2 + hstep, voffA);
;             PG8_WAIT_V(6); PG8_WAIT_L(0); PG8_BAR; PG8_MMA(0, 0, At, B0); PG8_BAR; PG8_SCHED;
;             PG8_LDA(At, 1, 1); PG8_STAGE(PG8_SB(1, 0), b3, voffB); PG8_STAGE(PG8_SA(1, 0), a3, voffA);
;             PG8_WAIT_V(6); PG8_WAIT_L(0); PG8_BAR; PG8_MMA(1, 0, At, B0); PG8_BAR; PG8_SCHED;
	s_add_i32 s25, 0, 0x18000
	v_add_u32_e32 v188, s25, v163
	ds_read_b128 v[158:161], v188
	ds_read_b128 v[180:183], v188 offset:1024
	ds_read_b128 v[184:187], v188 offset:2048
	ds_read_b128 v[188:191], v188 offset:3072
	s_add_u32 s6, s6, s8
	s_addc_u32 s7, s7, s9
	s_mov_b32 m0, s45
	v_lshl_add_u64 v[226:227], s[6:7], 0, v[66:67]
	ds_read_b128 v[192:195], v165 offset:32768
	ds_read_b128 v[196:199], v165 offset:33792
	ds_read_b128 v[200:203], v165 offset:34816
	ds_read_b128 v[204:207], v165 offset:35840
	ds_read_b128 v[208:211], v165 offset:36864
	ds_read_b128 v[212:215], v165 offset:37888
	ds_read_b128 v[216:219], v165 offset:38912
	ds_read_b128 v[220:223], v165 offset:39936
	global_load_lds_dwordx4 v[226:227], off
	v_lshl_add_u64 v[226:227], s[6:7], 0, v[68:69]
	s_mov_b32 m0, s54
	s_nop 0
	global_load_lds_dwordx4 v[226:227], off
	s_waitcnt vmcnt(6)
	s_waitcnt lgkmcnt(0)
	s_barrier
	s_waitcnt lgkmcnt(0)
	v_mfma_f32_16x16x32_bf16 v[58:61], v[158:161], v[192:195], v[58:61]
	v_mfma_f32_16x16x32_bf16 v[62:65], v[184:187], v[192:195], v[62:65]
	v_mfma_f32_16x16x32_bf16 v[54:57], v[158:161], v[200:203], v[54:57]
	v_mfma_f32_16x16x32_bf16 v[50:53], v[184:187], v[200:203], v[50:53]
	v_mfma_f32_16x16x32_bf16 v[46:49], v[158:161], v[208:211], v[46:49]
	v_mfma_f32_16x16x32_bf16 v[42:45], v[184:187], v[208:211], v[42:45]
	v_mfma_f32_16x16x32_bf16 v[38:41], v[158:161], v[216:219], v[38:41]
	v_mfma_f32_16x16x32_bf16 v[34:37], v[184:187], v[216:219], v[34:37]
	v_mfma_f32_16x16x32_bf16 v[58:61], v[180:183], v[196:199], v[58:61]
	v_mfma_f32_16x16x32_bf16 v[62:65], v[188:191], v[196:199], v[62:65]
	v_mfma_f32_16x16x32_bf16 v[54:57], v[180:183], v[204:207], v[54:57]
	v_mfma_f32_16x16x32_bf16 v[50:53], v[188:191], v[204:207], v[50:53]
	v_mfma_f32_16x16x32_bf16 v[46:49], v[180:183], v[212:215], v[46:49]
	v_mfma_f32_16x16x32_bf16 v[42:45], v[188:191], v[212:215], v[42:45]
	v_mfma_f32_16x16x32_bf16 v[38:41], v[180:183], v[220:223], v[38:41]
	v_mfma_f32_16x16x32_bf16 v[34:37], v[188:191], v[220:223], v[34:37]
	s_barrier
	s_add_i32 s6, s25, s42
	v_lshl_add_u64 v[138:139], v[138:139], 0, s[26:27]
	s_mov_b32 m0, s6
	ds_read_b128 v[192:195], v165 offset:49152
	ds_read_b128 v[196:199], v165 offset:50176
	ds_read_b128 v[200:203], v165 offset:51200
	ds_read_b128 v[204:207], v165 offset:52224
	ds_read_b128 v[208:211], v165 offset:53248
	ds_read_b128 v[212:215], v165 offset:54272
	ds_read_b128 v[216:219], v165 offset:55296
	ds_read_b128 v[220:223], v165 offset:56320
	global_load_lds_dwordx4 v[138:139], off
	v_lshl_add_u64 v[138:139], v[166:167], 0, s[26:27]
	s_add_i32 m0, s6, 0x2000
	s_nop 0
	global_load_lds_dwordx4 v[138:139], off
	v_lshl_add_u64 v[138:139], v[178:179], 0, s[26:27]
	s_mov_b32 m0, s57
	s_nop 0
	global_load_lds_dwordx4 v[138:139], off
	v_lshl_add_u64 v[138:139], v[224:225], 0, s[26:27]
	s_mov_b32 m0, s58
	s_nop 0
	global_load_lds_dwordx4 v[138:139], off
	s_waitcnt vmcnt(6)
	s_waitcnt lgkmcnt(0)
	s_barrier
	s_waitcnt lgkmcnt(0)
	v_mfma_f32_16x16x32_bf16 v[30:33], v[158:161], v[192:195], v[30:33]
	v_mfma_f32_16x16x32_bf16 v[26:29], v[184:187], v[192:195], v[26:29]
	v_mfma_f32_16x16x32_bf16 v[22:25], v[158:161], v[200:203], v[22:25]
	v_mfma_f32_16x16x32_bf16 v[18:21], v[184:187], v[200:203], v[18:21]
	v_mfma_f32_16x16x32_bf16 v[14:17], v[158:161], v[208:211], v[14:17]
	v_mfma_f32_16x16x32_bf16 v[10:13], v[184:187], v[208:211], v[10:13]
	v_mfma_f32_16x16x32_bf16 v[6:9], v[158:161], v[216:219], v[6:9]
	v_mfma_f32_16x16x32_bf16 v[2:5], v[184:187], v[216:219], v[2:5]
	v_mfma_f32_16x16x32_bf16 v[30:33], v[180:183], v[196:199], v[30:33]
	v_mfma_f32_16x16x32_bf16 v[26:29], v[188:191], v[196:199], v[26:29]
	v_mfma_f32_16x16x32_bf16 v[22:25], v[180:183], v[204:207], v[22:25]
	v_mfma_f32_16x16x32_bf16 v[18:21], v[188:191], v[204:207], v[18:21]
	v_mfma_f32_16x16x32_bf16 v[14:17], v[180:183], v[212:215], v[14:17]
	v_mfma_f32_16x16x32_bf16 v[10:13], v[188:191], v[212:215], v[10:13]
	v_mfma_f32_16x16x32_bf16 v[6:9], v[180:183], v[220:223], v[6:9]
	v_mfma_f32_16x16x32_bf16 v[2:5], v[188:191], v[220:223], v[2:5]
	s_barrier
	s_add_u32 s19, s19, 0x100
	s_addc_u32 s66, s66, 0
	s_add_u32 s4, s4, 0x100
	s_addc_u32 s5, s5, 0
	s_cmp_ge_i32 s24, s56
	s_mov_b32 s6, s24
	s_cbranch_scc0 .LBB0_137
	s_movk_i32 s67, 0x1600
	s_movk_i32 s69, 0x6c00
	v_readlane_b32 s68, v254, 38

; #define PG8_STAGE(bufoff, gbase, voff) do { _Pragma("unroll") for (int _i = 0; _i < 2; ++_i) \
;         __builtin_amdgcn_global_load_lds((const unsigned*)((const char*)(gbase) + (voff)[_i]), (LAS unsigned*)(lds + (bufoff) + ldsw + _i * 8192), 16, 0, 0); } while (0)
; #define PG8_LDA(dst, b, h) do { _Pragma("unroll") for (int m = 0; m < 4; ++m) _Pragma("unroll") for (int k = 0; k < 2; ++k) dst[m][k] = *(const LAS bf16x8*)(lds + PG8_SA(b, h) + aoff + m * 2048 + k * 1024); } while (0)
; template <class Epi, class Sched, bool HALFN = false>
; __device__ __forceinline__ void gemm_phase(LAS unsigned char* lds, const Gemm g, const Sched& S, const Epi& E) {
;     ...
;         for (int t = 0; t < nt; t += 2) {
;             const bool last = (t == nt - 2);
;             const char* a1 = cA + (size_t)(t + 1) * kstep;
;             const char* a2 = last ? nA : cA + (size_t)(t + 2) * kstep; const char* b2 = last ? nB : cB + (size_t)(t + 2) * kstep;
;             const char* a3 = a2 + kstep; const char* b3 = b2 + kstep;
;             if constexpr (HALFN) {
;             PG8_LDB(B0, 0, 0); PG8_SCHED; PG8_LDA(At, 0, 0); PG8_STAGE(PG8_SA(1, 1), a1 + hstep, voffA);
;             PG8_WAIT_V(6); PG8_WAIT_L(0); PG8_BAR; PG8_MMA(0, 0, At, B0); PG8_BAR; PG8_SCHED;
;             PG8_LDA(At, 0, 1); PG8_STAGE(PG8_SB(0, 0), b2, voffB); PG8_STAGE(PG8_SA(0, 0), a2, voffA);
;             PG8_WAIT_V(6); PG8_WAIT_L(0); PG8_BAR; PG8_MMA(1, 0, At, B0); PG8_BAR; PG8_SCHED;
;             PG8_LDB(B0, 1, 0); PG8_SCHED; PG8_LDA(At, 1, 0); PG8_STAGE(PG8_SA(0, 1), a2 + hstep, voffA);
;             PG8_WAIT_V(6); PG8_WAIT_L(0); PG8_BAR; PG8_MMA(0, 0, At, B0); PG8_BAR; PG8_SCHED;
;             PG8_LDA(At, 1, 1); PG8_STAGE(PG8_SB(1, 0), b3, voffB); PG8_STAGE(PG8_SA(1, 0), a3, voffA);
;             PG8_WAIT_V(6); PG8_WAIT_L(0); PG8_BAR; PG8_MMA(1, 0, At, B0); PG8_BAR; PG8_SCHED;
;             } else {
;             PG8_LDB(B0, 0, 0); PG8_LDB(B1, 0, 1); PG8_SCHED; PG8_LDA(At, 0, 0); PG8_STAGE(PG8_SA(1, 1), a1 + hstep, voffA);
;             PG8_WAIT_V(8); PG8_WAIT_L(0); PG8_BAR; PG8_MMA(0, 0, At, B0); PG8_MMA(0, 1, At, B1); PG8_BAR; PG8_SCHED;
;             PG8_LDA(At, 0, 1); PG8_STAGE(PG8_SB(0, 0), b2, voffB); PG8_STAGE(PG8_SB(0, 1), b2 + hstep, voffB); PG8_STAGE(PG8_SA(0, 0), a2, voffA);
;             PG8_WAIT_V(8); PG8_WAIT_L(0); PG8_BAR; PG8_MMA(1, 0, At, B0); PG8_MMA(1, 1, At, B1); PG8_BAR; PG8_SCHED;
.LBB0_177:
	s_add_i32 s62, s20, 2
	s_add_u32 s63, s18, 0x80
	s_addc_u32 s21, s19, 0
	s_add_i32 s66, 0, 0x10000
	s_cmp_eq_u32 s54, s20
	s_cselect_b32 s21, s5, s21
	s_cselect_b32 s20, s4, s63
	v_add_u32_e32 v138, s66, v159
	s_cselect_b32 s65, s17, s61
	s_cselect_b32 s64, s16, s60
	s_add_i32 s63, 0, 0x14000
	ds_read_b128 v[162:165], v138
	ds_read_b128 v[180:183], v138 offset:1024
	ds_read_b128 v[184:187], v138 offset:2048
	ds_read_b128 v[188:191], v138 offset:3072
	v_add_u32_e32 v138, s63, v159
	ds_read_b128 v[192:195], v138
	ds_read_b128 v[196:199], v138 offset:1024
	ds_read_b128 v[200:203], v138 offset:2048
	ds_read_b128 v[204:207], v138 offset:3072
	v_lshl_add_u64 v[138:139], s[18:19], 0, v[156:157]
	s_add_i32 m0, s34, 0xc000
	ds_read_b128 v[208:211], v161
	ds_read_b128 v[212:215], v161 offset:1024
	ds_read_b128 v[216:219], v161 offset:2048
	ds_read_b128 v[220:223], v161 offset:3072
	ds_read_b128 v[224:227], v161 offset:4096
	ds_read_b128 v[228:231], v161 offset:5120
	ds_read_b128 v[232:235], v161 offset:6144
	ds_read_b128 v[236:239], v161 offset:7168
	global_load_lds_dwordx4 v[138:139], off
	v_lshl_add_u64 v[138:139], s[18:19], 0, v[154:155]
	s_add_i32 m0, s34, 0xe000
	s_nop 0
	global_load_lds_dwordx4 v[138:139], off
	s_waitcnt vmcnt(8)
	s_waitcnt lgkmcnt(0)
	s_barrier
	s_waitcnt lgkmcnt(0)
	v_mfma_f32_16x16x32_bf16 v[126:129], v[162:165], v[208:211], v[126:129]
	v_mfma_f32_16x16x32_bf16 v[122:125], v[184:187], v[208:211], v[122:125]
	v_mfma_f32_16x16x32_bf16 v[110:113], v[162:165], v[216:219], v[110:113]
	v_mfma_f32_16x16x32_bf16 v[106:109], v[184:187], v[216:219], v[106:109]
	v_mfma_f32_16x16x32_bf16 v[94:97], v[162:165], v[224:227], v[94:97]
	v_mfma_f32_16x16x32_bf16 v[90:93], v[184:187], v[224:227], v[90:93]
	v_mfma_f32_16x16x32_bf16 v[78:81], v[162:165], v[232:235], v[78:81]
	v_mfma_f32_16x16x32_bf16 v[74:77], v[184:187], v[232:235], v[74:77]
	v_mfma_f32_16x16x32_bf16 v[126:129], v[180:183], v[212:215], v[126:129]
	v_mfma_f32_16x16x32_bf16 v[122:125], v[188:191], v[212:215], v[122:125]
	v_mfma_f32_16x16x32_bf16 v[110:113], v[180:183], v[220:223], v[110:113]
	v_mfma_f32_16x16x32_bf16 v[106:109], v[188:191], v[220:223], v[106:109]
	v_mfma_f32_16x16x32_bf16 v[94:97], v[180:183], v[228:231], v[94:97]
	v_mfma_f32_16x16x32_bf16 v[90:93], v[188:191], v[228:231], v[90:93]
	v_mfma_f32_16x16x32_bf16 v[78:81], v[180:183], v[236:239], v[78:81]
	v_mfma_f32_16x16x32_bf16 v[74:77], v[188:191], v[236:239], v[74:77]
	v_mfma_f32_16x16x32_bf16 v[118:121], v[192:195], v[208:211], v[118:121]
	v_mfma_f32_16x16x32_bf16 v[114:117], v[200:203], v[208:211], v[114:117]
	v_mfma_f32_16x16x32_bf16 v[102:105], v[192:195], v[216:219], v[102:105]
	v_mfma_f32_16x16x32_bf16 v[98:101], v[200:203], v[216:219], v[98:101]
	v_mfma_f32_16x16x32_bf16 v[86:89], v[192:195], v[224:227], v[86:89]
	v_mfma_f32_16x16x32_bf16 v[82:85], v[200:203], v[224:227], v[82:85]
	v_mfma_f32_16x16x32_bf16 v[70:73], v[192:195], v[232:235], v[70:73]
	v_mfma_f32_16x16x32_bf16 v[66:69], v[200:203], v[232:235], v[66:69]
	v_mfma_f32_16x16x32_bf16 v[118:121], v[196:199], v[212:215], v[118:121]
	v_mfma_f32_16x16x32_bf16 v[114:117], v[204:207], v[212:215], v[114:117]
	v_mfma_f32_16x16x32_bf16 v[102:105], v[196:199], v[220:223], v[102:105]
	v_mfma_f32_16x16x32_bf16 v[98:101], v[204:207], v[220:223], v[98:101]
	v_mfma_f32_16x16x32_bf16 v[86:89], v[196:199], v[228:231], v[86:89]
	v_mfma_f32_16x16x32_bf16 v[82:85], v[204:207], v[228:231], v[82:85]
	v_mfma_f32_16x16x32_bf16 v[70:73], v[196:199], v[236:239], v[70:73]
	v_mfma_f32_16x16x32_bf16 v[66:69], v[204:207], v[236:239], v[66:69]
	s_barrier
	s_add_i32 s66, s66, s24
	v_lshl_add_u64 v[138:139], s[64:65], 0, v[0:1]
	s_mov_b32 m0, s66
	ds_read_b128 v[208:211], v161 offset:16384
	ds_read_b128 v[212:215], v161 offset:17408
	ds_read_b128 v[216:219], v161 offset:18432
	ds_read_b128 v[220:223], v161 offset:19456
	ds_read_b128 v[224:227], v161 offset:20480
	ds_read_b128 v[228:231], v161 offset:21504
	ds_read_b128 v[232:235], v161 offset:22528
	ds_read_b128 v[236:239], v161 offset:23552
	global_load_lds_dwordx4 v[138:139], off
	s_add_i32 m0, s66, 0x2000
	v_lshl_add_u64 v[166:167], s[64:65], 0, v[148:149]
	s_add_u32 s64, s64, s6
	s_addc_u32 s65, s65, s7
	s_add_i32 s63, s63, s24
	global_load_lds_dwordx4 v[166:167], off
	v_lshl_add_u64 v[178:179], s[64:65], 0, v[0:1]
	s_mov_b32 m0, s63
	v_lshl_add_u64 v[240:241], s[64:65], 0, v[148:149]
	global_load_lds_dwordx4 v[178:179], off
	s_add_i32 m0, s63, 0x2000
	v_lshl_add_u64 v[242:243], s[20:21], 0, v[152:153]
	global_load_lds_dwordx4 v[240:241], off
	s_mov_b32 m0, s34
	v_lshl_add_u64 v[244:245], s[20:21], 0, v[150:151]
	global_load_lds_dwordx4 v[242:243], off
	s_mov_b32 m0, s35
	s_nop 0
	global_load_lds_dwordx4 v[244:245], off
	s_waitcnt vmcnt(8)
	s_waitcnt lgkmcnt(0)
	s_barrier
; #define PG8_STAGE(bufoff, gbase, voff) do { _Pragma("unroll") for (int _i = 0; _i < 2; ++_i) \
;         __builtin_amdgcn_global_load_lds((const unsigned*)((const char*)(gbase) + (voff)[_i]), (LAS unsigned*)(lds + (bufoff) + ldsw + _i * 8192), 16, 0, 0); } while (0)
; #define PG8_LDA(dst, b, h) do { _Pragma("unroll") for (int m = 0; m < 4; ++m) _Pragma("unroll") for (int k = 0; k < 2; ++k) dst[m][k] = *(const LAS bf16x8*)(lds + PG8_SA(b, h) + aoff + m * 2048 + k * 1024); } while (0)
; #define PG8_LDB(dst, b, h) do { _Pragma("unroll") for (int n = 0; n < 2; ++n) _Pragma("unroll") for (int k = 0; k < 2; ++k) dst[n][k] = *(const LAS bf16x8*)(lds + PG8_SB(b, h) + boff + n * 2048 + k * 1024); } while (0)
; #define PG8_MMA(ai, bj, At, Bt) do { __builtin_amdgcn_s_setprio(1); _Pragma("unroll") for (int m = 0; m < 4; ++m) _Pragma("unroll") for (int n = 0; n < 2; ++n) _Pragma("unroll") for (int k = 0; k < 2; ++k) \
;         acc[ai][bj][m][n] = __builtin_amdgcn_mfma_f32_16x16x32_bf16(Bt[n][k], At[m][k], acc[ai][bj][m][n], 0, 0, 0); __builtin_amdgcn_s_setprio(0); } while (0)
; #define PG8_WAIT_V(n) asm volatile("s_waitcnt vmcnt(" #n ")" ::: "memory")
; #define PG8_WAIT_L(n) asm volatile("s_waitcnt lgkmcnt(" #n ")" ::: "memory")
; #define PG8_BAR __builtin_amdgcn_s_barrier()
; #define PG8_SCHED __builtin_amdgcn_sched_barrier(0)
; template <class Epi, class Sched, bool HALFN = false>
; __device__ __forceinline__ void gemm_phase(LAS unsigned char* lds, const Gemm g, const Sched& S, const Epi& E) {
;     ...
;             PG8_WAIT_V(8); PG8_WAIT_L(0); PG8_BAR; PG8_MMA(1, 0, At, B0); PG8_MMA(1, 1, At, B1); PG8_BAR; PG8_SCHED;
;             PG8_LDB(B0, 1, 0); PG8_LDB(B1, 1, 1); PG8_SCHED; PG8_LDA(At, 1, 0); PG8_STAGE(PG8_SA(0, 1), a2 + hstep, voffA);
;             PG8_WAIT_V(8); PG8_WAIT_L(0); PG8_BAR; PG8_MMA(0, 0, At, B0); PG8_MMA(0, 1, At, B1); PG8_BAR; PG8_SCHED;
	s_waitcnt lgkmcnt(0)
	v_mfma_f32_16x16x32_bf16 v[62:65], v[162:165], v[208:211], v[62:65]
	v_mfma_f32_16x16x32_bf16 v[58:61], v[184:187], v[208:211], v[58:61]
	v_mfma_f32_16x16x32_bf16 v[46:49], v[162:165], v[216:219], v[46:49]
	v_mfma_f32_16x16x32_bf16 v[42:45], v[184:187], v[216:219], v[42:45]
	v_mfma_f32_16x16x32_bf16 v[30:33], v[162:165], v[224:227], v[30:33]
	v_mfma_f32_16x16x32_bf16 v[26:29], v[184:187], v[224:227], v[26:29]
	v_mfma_f32_16x16x32_bf16 v[14:17], v[162:165], v[232:235], v[14:17]
	v_mfma_f32_16x16x32_bf16 v[10:13], v[184:187], v[232:235], v[10:13]
	v_mfma_f32_16x16x32_bf16 v[62:65], v[180:183], v[212:215], v[62:65]
	v_mfma_f32_16x16x32_bf16 v[58:61], v[188:191], v[212:215], v[58:61]
	v_mfma_f32_16x16x32_bf16 v[46:49], v[180:183], v[220:223], v[46:49]
	v_mfma_f32_16x16x32_bf16 v[42:45], v[188:191], v[220:223], v[42:45]
	v_mfma_f32_16x16x32_bf16 v[30:33], v[180:183], v[228:231], v[30:33]
	v_mfma_f32_16x16x32_bf16 v[26:29], v[188:191], v[228:231], v[26:29]
	v_mfma_f32_16x16x32_bf16 v[14:17], v[180:183], v[236:239], v[14:17]
	v_mfma_f32_16x16x32_bf16 v[10:13], v[188:191], v[236:239], v[10:13]
	v_mfma_f32_16x16x32_bf16 v[54:57], v[192:195], v[208:211], v[54:57]
	v_mfma_f32_16x16x32_bf16 v[50:53], v[200:203], v[208:211], v[50:53]
	v_mfma_f32_16x16x32_bf16 v[38:41], v[192:195], v[216:219], v[38:41]
	v_mfma_f32_16x16x32_bf16 v[34:37], v[200:203], v[216:219], v[34:37]
	v_mfma_f32_16x16x32_bf16 v[22:25], v[192:195], v[224:227], v[22:25]
	v_mfma_f32_16x16x32_bf16 v[18:21], v[200:203], v[224:227], v[18:21]
	v_mfma_f32_16x16x32_bf16 v[6:9], v[192:195], v[232:235], v[6:9]
	v_mfma_f32_16x16x32_bf16 v[2:5], v[200:203], v[232:235], v[2:5]
	v_mfma_f32_16x16x32_bf16 v[54:57], v[196:199], v[212:215], v[54:57]
	v_mfma_f32_16x16x32_bf16 v[50:53], v[204:207], v[212:215], v[50:53]
	v_mfma_f32_16x16x32_bf16 v[38:41], v[196:199], v[220:223], v[38:41]
	v_mfma_f32_16x16x32_bf16 v[34:37], v[204:207], v[220:223], v[34:37]
	v_mfma_f32_16x16x32_bf16 v[22:25], v[196:199], v[228:231], v[22:25]
	v_mfma_f32_16x16x32_bf16 v[18:21], v[204:207], v[228:231], v[18:21]
	v_mfma_f32_16x16x32_bf16 v[6:9], v[196:199], v[236:239], v[6:9]
	v_mfma_f32_16x16x32_bf16 v[2:5], v[204:207], v[236:239], v[2:5]
	s_barrier
	s_add_i32 s63, 0, 0x18000
	s_add_i32 s64, 0, 0x1c000
	v_add_u32_e32 v188, s63, v159
	v_add_u32_e32 v204, s64, v159
	ds_read_b128 v[162:165], v188
	ds_read_b128 v[180:183], v188 offset:1024
	ds_read_b128 v[184:187], v188 offset:2048
	ds_read_b128 v[188:191], v188 offset:3072
	ds_read_b128 v[192:195], v204
	ds_read_b128 v[196:199], v204 offset:1024
	ds_read_b128 v[200:203], v204 offset:2048
	ds_read_b128 v[204:207], v204 offset:3072
	s_add_u32 s20, s20, s6
	s_addc_u32 s21, s21, s7
	s_mov_b32 m0, s40
	v_lshl_add_u64 v[246:247], s[20:21], 0, v[152:153]
	ds_read_b128 v[208:211], v161 offset:32768
	ds_read_b128 v[212:215], v161 offset:33792
	ds_read_b128 v[216:219], v161 offset:34816
	ds_read_b128 v[220:223], v161 offset:35840
	ds_read_b128 v[224:227], v161 offset:36864
	ds_read_b128 v[228:231], v161 offset:37888
	ds_read_b128 v[232:235], v161 offset:38912
	ds_read_b128 v[236:239], v161 offset:39936
	global_load_lds_dwordx4 v[246:247], off
	v_lshl_add_u64 v[246:247], s[20:21], 0, v[150:151]
	s_mov_b32 m0, s41
	s_nop 0
	global_load_lds_dwordx4 v[246:247], off
	s_waitcnt vmcnt(8)
	s_waitcnt lgkmcnt(0)
	s_barrier
	s_waitcnt lgkmcnt(0)
	v_mfma_f32_16x16x32_bf16 v[126:129], v[162:165], v[208:211], v[126:129]
	v_mfma_f32_16x16x32_bf16 v[122:125], v[184:187], v[208:211], v[122:125]
	v_mfma_f32_16x16x32_bf16 v[110:113], v[162:165], v[216:219], v[110:113]
	v_mfma_f32_16x16x32_bf16 v[106:109], v[184:187], v[216:219], v[106:109]
	v_mfma_f32_16x16x32_bf16 v[94:97], v[162:165], v[224:227], v[94:97]
	v_mfma_f32_16x16x32_bf16 v[90:93], v[184:187], v[224:227], v[90:93]
	v_mfma_f32_16x16x32_bf16 v[78:81], v[162:165], v[232:235], v[78:81]
	v_mfma_f32_16x16x32_bf16 v[74:77], v[184:187], v[232:235], v[74:77]
	v_mfma_f32_16x16x32_bf16 v[126:129], v[180:183], v[212:215], v[126:129]
	v_mfma_f32_16x16x32_bf16 v[122:125], v[188:191], v[212:215], v[122:125]
	v_mfma_f32_16x16x32_bf16 v[110:113], v[180:183], v[220:223], v[110:113]
	v_mfma_f32_16x16x32_bf16 v[106:109], v[188:191], v[220:223], v[106:109]
	v_mfma_f32_16x16x32_bf16 v[94:97], v[180:183], v[228:231], v[94:97]
	v_mfma_f32_16x16x32_bf16 v[90:93], v[188:191], v[228:231], v[90:93]
	v_mfma_f32_16x16x32_bf16 v[78:81], v[180:183], v[236:239], v[78:81]
	v_mfma_f32_16x16x32_bf16 v[74:77], v[188:191], v[236:239], v[74:77]
	v_mfma_f32_16x16x32_bf16 v[118:121], v[192:195], v[208:211], v[118:121]
	v_mfma_f32_16x16x32_bf16 v[114:117], v[200:203], v[208:211], v[114:117]
	v_mfma_f32_16x16x32_bf16 v[102:105], v[192:195], v[216:219], v[102:105]
	v_mfma_f32_16x16x32_bf16 v[98:101], v[200:203], v[216:219], v[98:101]
	v_mfma_f32_16x16x32_bf16 v[86:89], v[192:195], v[224:227], v[86:89]
	v_mfma_f32_16x16x32_bf16 v[82:85], v[200:203], v[224:227], v[82:85]
	v_mfma_f32_16x16x32_bf16 v[70:73], v[192:195], v[232:235], v[70:73]
	v_mfma_f32_16x16x32_bf16 v[66:69], v[200:203], v[232:235], v[66:69]
	v_mfma_f32_16x16x32_bf16 v[118:121], v[196:199], v[212:215], v[118:121]
	v_mfma_f32_16x16x32_bf16 v[114:117], v[204:207], v[212:215], v[114:117]
	v_mfma_f32_16x16x32_bf16 v[102:105], v[196:199], v[220:223], v[102:105]
	v_mfma_f32_16x16x32_bf16 v[98:101], v[204:207], v[220:223], v[98:101]
	v_mfma_f32_16x16x32_bf16 v[86:89], v[196:199], v[228:231], v[86:89]
	v_mfma_f32_16x16x32_bf16 v[82:85], v[204:207], v[228:231], v[82:85]
	v_mfma_f32_16x16x32_bf16 v[70:73], v[196:199], v[236:239], v[70:73]
	v_mfma_f32_16x16x32_bf16 v[66:69], v[204:207], v[236:239], v[66:69]
	s_barrier
; #define PG8_STAGE(bufoff, gbase, voff) do { _Pragma("unroll") for (int _i = 0; _i < 2; ++_i) \
;         __builtin_amdgcn_global_load_lds((const unsigned*)((const char*)(gbase) + (voff)[_i]), (LAS unsigned*)(lds + (bufoff) + ldsw + _i * 8192), 16, 0, 0); } while (0)
; #define PG8_LDA(dst, b, h) do { _Pragma("unroll") for (int m = 0; m < 4; ++m) _Pragma("unroll") for (int k = 0; k < 2; ++k) dst[m][k] = *(const LAS bf16x8*)(lds + PG8_SA(b, h) + aoff + m * 2048 + k * 1024); } while (0)
; #define PG8_MMA(ai, bj, At, Bt) do { __builtin_amdgcn_s_setprio(1); _Pragma("unroll") for (int m = 0; m < 4; ++m) _Pragma("unroll") for (int n = 0; n < 2; ++n) _Pragma("unroll") for (int k = 0; k < 2; ++k) \
;         acc[ai][bj][m][n] = __builtin_amdgcn_mfma_f32_16x16x32_bf16(Bt[n][k], At[m][k], acc[ai][bj][m][n], 0, 0, 0); __builtin_amdgcn_s_setprio(0); } while (0)
; #define PG8_WAIT_V(n) asm volatile("s_waitcnt vmcnt(" #n ")" ::: "memory")
; #define PG8_WAIT_L(n) asm volatile("s_waitcnt lgkmcnt(" #n ")" ::: "memory")
; #define PG8_BAR __builtin_amdgcn_s_barrier()
; #define PG8_SCHED __builtin_amdgcn_sched_barrier(0)
; template <class Epi, class Sched, bool HALFN = false>
; __device__ __forceinline__ void gemm_phase(LAS unsigned char* lds, const Gemm g, const Sched& S, const Epi& E) {
;     ...
;             PG8_LDA(At, 1, 1); PG8_STAGE(PG8_SB(1, 0), b3, voffB); PG8_STAGE(PG8_SB(1, 1), b3 + hstep, voffB); PG8_STAGE(PG8_SA(1, 0), a3, voffA);
;             PG8_WAIT_V(8); PG8_WAIT_L(0); PG8_BAR; PG8_MMA(1, 0, At, B0); PG8_MMA(1, 1, At, B1); PG8_BAR; PG8_SCHED;
;             }
;         }
	s_add_i32 s20, s63, s24
	v_lshl_add_u64 v[138:139], v[138:139], 0, s[26:27]
	s_mov_b32 m0, s20
	ds_read_b128 v[208:211], v161 offset:49152
	ds_read_b128 v[212:215], v161 offset:50176
	ds_read_b128 v[216:219], v161 offset:51200
	ds_read_b128 v[220:223], v161 offset:52224
	ds_read_b128 v[224:227], v161 offset:53248
	ds_read_b128 v[228:231], v161 offset:54272
	ds_read_b128 v[232:235], v161 offset:55296
	ds_read_b128 v[236:239], v161 offset:56320
	global_load_lds_dwordx4 v[138:139], off
	v_lshl_add_u64 v[138:139], v[166:167], 0, s[26:27]
	s_add_i32 m0, s20, 0x2000
	s_add_i32 s20, s64, s24
	global_load_lds_dwordx4 v[138:139], off
	v_lshl_add_u64 v[138:139], v[178:179], 0, s[26:27]
	s_mov_b32 m0, s20
	s_nop 0
	global_load_lds_dwordx4 v[138:139], off
	v_lshl_add_u64 v[138:139], v[240:241], 0, s[26:27]
	s_add_i32 m0, s20, 0x2000
	s_nop 0
	global_load_lds_dwordx4 v[138:139], off
	v_lshl_add_u64 v[138:139], v[242:243], 0, s[26:27]
	s_mov_b32 m0, s42
	s_nop 0
	global_load_lds_dwordx4 v[138:139], off
	v_lshl_add_u64 v[138:139], v[244:245], 0, s[26:27]
	s_mov_b32 m0, s43
	s_nop 0
	global_load_lds_dwordx4 v[138:139], off
	s_waitcnt vmcnt(8)
	s_waitcnt lgkmcnt(0)
	s_barrier
	s_waitcnt lgkmcnt(0)
	v_mfma_f32_16x16x32_bf16 v[62:65], v[162:165], v[208:211], v[62:65]
	v_mfma_f32_16x16x32_bf16 v[58:61], v[184:187], v[208:211], v[58:61]
	v_mfma_f32_16x16x32_bf16 v[46:49], v[162:165], v[216:219], v[46:49]
	v_mfma_f32_16x16x32_bf16 v[42:45], v[184:187], v[216:219], v[42:45]
	v_mfma_f32_16x16x32_bf16 v[30:33], v[162:165], v[224:227], v[30:33]
	v_mfma_f32_16x16x32_bf16 v[26:29], v[184:187], v[224:227], v[26:29]
	v_mfma_f32_16x16x32_bf16 v[14:17], v[162:165], v[232:235], v[14:17]
	v_mfma_f32_16x16x32_bf16 v[10:13], v[184:187], v[232:235], v[10:13]
	v_mfma_f32_16x16x32_bf16 v[62:65], v[180:183], v[212:215], v[62:65]
	v_mfma_f32_16x16x32_bf16 v[58:61], v[188:191], v[212:215], v[58:61]
	v_mfma_f32_16x16x32_bf16 v[46:49], v[180:183], v[220:223], v[46:49]
	v_mfma_f32_16x16x32_bf16 v[42:45], v[188:191], v[220:223], v[42:45]
	v_mfma_f32_16x16x32_bf16 v[30:33], v[180:183], v[228:231], v[30:33]
	v_mfma_f32_16x16x32_bf16 v[26:29], v[188:191], v[228:231], v[26:29]
	v_mfma_f32_16x16x32_bf16 v[14:17], v[180:183], v[236:239], v[14:17]
	v_mfma_f32_16x16x32_bf16 v[10:13], v[188:191], v[236:239], v[10:13]
	v_mfma_f32_16x16x32_bf16 v[54:57], v[192:195], v[208:211], v[54:57]
	v_mfma_f32_16x16x32_bf16 v[50:53], v[200:203], v[208:211], v[50:53]
	v_mfma_f32_16x16x32_bf16 v[38:41], v[192:195], v[216:219], v[38:41]
	v_mfma_f32_16x16x32_bf16 v[34:37], v[200:203], v[216:219], v[34:37]
	v_mfma_f32_16x16x32_bf16 v[22:25], v[192:195], v[224:227], v[22:25]
	v_mfma_f32_16x16x32_bf16 v[18:21], v[200:203], v[224:227], v[18:21]
	v_mfma_f32_16x16x32_bf16 v[6:9], v[192:195], v[232:235], v[6:9]
	v_mfma_f32_16x16x32_bf16 v[2:5], v[200:203], v[232:235], v[2:5]
	v_mfma_f32_16x16x32_bf16 v[54:57], v[196:199], v[212:215], v[54:57]
	v_mfma_f32_16x16x32_bf16 v[50:53], v[204:207], v[212:215], v[50:53]
	v_mfma_f32_16x16x32_bf16 v[38:41], v[196:199], v[220:223], v[38:41]
	v_mfma_f32_16x16x32_bf16 v[34:37], v[204:207], v[220:223], v[34:37]
	v_mfma_f32_16x16x32_bf16 v[22:25], v[196:199], v[228:231], v[22:25]
	v_mfma_f32_16x16x32_bf16 v[18:21], v[204:207], v[228:231], v[18:21]
	v_mfma_f32_16x16x32_bf16 v[6:9], v[196:199], v[236:239], v[6:9]
	v_mfma_f32_16x16x32_bf16 v[2:5], v[204:207], v[236:239], v[2:5]
	s_barrier
	s_add_u32 s60, s60, 0x100
	s_addc_u32 s61, s61, 0
	s_add_u32 s18, s18, 0x100
	s_addc_u32 s19, s19, 0
	s_cmp_ge_i32 s62, s45
	s_mov_b32 s20, s62
	s_cbranch_scc0 .LBB0_177

; #define PG8_STAGE(bufoff, gbase, voff) do { _Pragma("unroll") for (int _i = 0; _i < 2; ++_i) \
;         __builtin_amdgcn_global_load_lds((const unsigned*)((const char*)(gbase) + (voff)[_i]), (LAS unsigned*)(lds + (bufoff) + ldsw + _i * 8192), 16, 0, 0); } while (0)
; #define PG8_LDA(dst, b, h) do { _Pragma("unroll") for (int m = 0; m < 4; ++m) _Pragma("unroll") for (int k = 0; k < 2; ++k) dst[m][k] = *(const LAS bf16x8*)(lds + PG8_SA(b, h) + aoff + m * 2048 + k * 1024); } while (0)
; template <class Epi, class Sched, bool HALFN = false>
; __device__ __forceinline__ void gemm_phase(LAS unsigned char* lds, const Gemm g, const Sched& S, const Epi& E) {
;     ...
;         for (int t = 0; t < nt; t += 2) {
;             const bool last = (t == nt - 2);
;             const char* a1 = cA + (size_t)(t + 1) * kstep;
;             const char* a2 = last ? nA : cA + (size_t)(t + 2) * kstep; const char* b2 = last ? nB : cB + (size_t)(t + 2) * kstep;
;             const char* a3 = a2 + kstep; const char* b3 = b2 + kstep;
;             if constexpr (HALFN) {
;             PG8_LDB(B0, 0, 0); PG8_SCHED; PG8_LDA(At, 0, 0); PG8_STAGE(PG8_SA(1, 1), a1 + hstep, voffA);
;             PG8_WAIT_V(6); PG8_WAIT_L(0); PG8_BAR; PG8_MMA(0, 0, At, B0); PG8_BAR; PG8_SCHED;
;             PG8_LDA(At, 0, 1); PG8_STAGE(PG8_SB(0, 0), b2, voffB); PG8_STAGE(PG8_SA(0, 0), a2, voffA);
;             PG8_WAIT_V(6); PG8_WAIT_L(0); PG8_BAR; PG8_MMA(1, 0, At, B0); PG8_BAR; PG8_SCHED;
;             PG8_LDB(B0, 1, 0); PG8_SCHED; PG8_LDA(At, 1, 0); PG8_STAGE(PG8_SA(0, 1), a2 + hstep, voffA);
;             PG8_WAIT_V(6); PG8_WAIT_L(0); PG8_BAR; PG8_MMA(0, 0, At, B0); PG8_BAR; PG8_SCHED;
;             PG8_LDA(At, 1, 1); PG8_STAGE(PG8_SB(1, 0), b3, voffB); PG8_STAGE(PG8_SA(1, 0), a3, voffA);
;             PG8_WAIT_V(6); PG8_WAIT_L(0); PG8_BAR; PG8_MMA(1, 0, At, B0); PG8_BAR; PG8_SCHED;
;             } else {
;             PG8_LDB(B0, 0, 0); PG8_LDB(B1, 0, 1); PG8_SCHED; PG8_LDA(At, 0, 0); PG8_STAGE(PG8_SA(1, 1), a1 + hstep, voffA);
;             PG8_WAIT_V(8); PG8_WAIT_L(0); PG8_BAR; PG8_MMA(0, 0, At, B0); PG8_MMA(0, 1, At, B1); PG8_BAR; PG8_SCHED;
;             PG8_LDA(At, 0, 1); PG8_STAGE(PG8_SB(0, 0), b2, voffB); PG8_STAGE(PG8_SB(0, 1), b2 + hstep, voffB); PG8_STAGE(PG8_SA(0, 0), a2, voffA);
;             PG8_WAIT_V(8); PG8_WAIT_L(0); PG8_BAR; PG8_MMA(1, 0, At, B0); PG8_MMA(1, 1, At, B1); PG8_BAR; PG8_SCHED;
.LBB0_383:
	s_add_i32 s68, s24, 2
	s_add_u32 s69, s22, 0x80
	s_addc_u32 s25, s23, 0
	s_add_i32 s72, 0, 0x10000
	s_cmp_eq_u32 s62, s24
	s_cselect_b32 s25, s5, s25
	s_cselect_b32 s24, s4, s69
	v_add_u32_e32 v138, s72, v161
	s_cselect_b32 s71, s21, s67
	s_cselect_b32 s70, s20, s17
	s_add_i32 s69, 0, 0x14000
	ds_read_b128 v[164:167], v138
	ds_read_b128 v[180:183], v138 offset:1024
	ds_read_b128 v[184:187], v138 offset:2048
	ds_read_b128 v[188:191], v138 offset:3072
	v_add_u32_e32 v138, s69, v161
	ds_read_b128 v[192:195], v138
	ds_read_b128 v[196:199], v138 offset:1024
	ds_read_b128 v[200:203], v138 offset:2048
	ds_read_b128 v[204:207], v138 offset:3072
	v_lshl_add_u64 v[138:139], s[22:23], 0, v[156:157]
	s_add_i32 m0, s44, 0xc000
	ds_read_b128 v[208:211], v163
	ds_read_b128 v[212:215], v163 offset:1024
	ds_read_b128 v[216:219], v163 offset:2048
	ds_read_b128 v[220:223], v163 offset:3072
	ds_read_b128 v[224:227], v163 offset:4096
	ds_read_b128 v[228:231], v163 offset:5120
	ds_read_b128 v[232:235], v163 offset:6144
	ds_read_b128 v[236:239], v163 offset:7168
	global_load_lds_dwordx4 v[138:139], off
	v_lshl_add_u64 v[138:139], s[22:23], 0, v[154:155]
	s_add_i32 m0, s44, 0xe000
	s_nop 0
	global_load_lds_dwordx4 v[138:139], off
	s_waitcnt vmcnt(8)
	s_waitcnt lgkmcnt(0)
	s_barrier
	s_waitcnt lgkmcnt(0)
	v_mfma_f32_16x16x32_bf16 v[126:129], v[164:167], v[208:211], v[126:129]
	v_mfma_f32_16x16x32_bf16 v[122:125], v[184:187], v[208:211], v[122:125]
	v_mfma_f32_16x16x32_bf16 v[110:113], v[164:167], v[216:219], v[110:113]
	v_mfma_f32_16x16x32_bf16 v[106:109], v[184:187], v[216:219], v[106:109]
	v_mfma_f32_16x16x32_bf16 v[94:97], v[164:167], v[224:227], v[94:97]
	v_mfma_f32_16x16x32_bf16 v[90:93], v[184:187], v[224:227], v[90:93]
	v_mfma_f32_16x16x32_bf16 v[78:81], v[164:167], v[232:235], v[78:81]
	v_mfma_f32_16x16x32_bf16 v[74:77], v[184:187], v[232:235], v[74:77]
	v_mfma_f32_16x16x32_bf16 v[126:129], v[180:183], v[212:215], v[126:129]
	v_mfma_f32_16x16x32_bf16 v[122:125], v[188:191], v[212:215], v[122:125]
	v_mfma_f32_16x16x32_bf16 v[110:113], v[180:183], v[220:223], v[110:113]
	v_mfma_f32_16x16x32_bf16 v[106:109], v[188:191], v[220:223], v[106:109]
	v_mfma_f32_16x16x32_bf16 v[94:97], v[180:183], v[228:231], v[94:97]
	v_mfma_f32_16x16x32_bf16 v[90:93], v[188:191], v[228:231], v[90:93]
	v_mfma_f32_16x16x32_bf16 v[78:81], v[180:183], v[236:239], v[78:81]
	v_mfma_f32_16x16x32_bf16 v[74:77], v[188:191], v[236:239], v[74:77]
	v_mfma_f32_16x16x32_bf16 v[118:121], v[192:195], v[208:211], v[118:121]
	v_mfma_f32_16x16x32_bf16 v[114:117], v[200:203], v[208:211], v[114:117]
	v_mfma_f32_16x16x32_bf16 v[102:105], v[192:195], v[216:219], v[102:105]
	v_mfma_f32_16x16x32_bf16 v[98:101], v[200:203], v[216:219], v[98:101]
	v_mfma_f32_16x16x32_bf16 v[86:89], v[192:195], v[224:227], v[86:89]
	v_mfma_f32_16x16x32_bf16 v[82:85], v[200:203], v[224:227], v[82:85]
	v_mfma_f32_16x16x32_bf16 v[70:73], v[192:195], v[232:235], v[70:73]
	v_mfma_f32_16x16x32_bf16 v[66:69], v[200:203], v[232:235], v[66:69]
	v_mfma_f32_16x16x32_bf16 v[118:121], v[196:199], v[212:215], v[118:121]
	v_mfma_f32_16x16x32_bf16 v[114:117], v[204:207], v[212:215], v[114:117]
	v_mfma_f32_16x16x32_bf16 v[102:105], v[196:199], v[220:223], v[102:105]
	v_mfma_f32_16x16x32_bf16 v[98:101], v[204:207], v[220:223], v[98:101]
	v_mfma_f32_16x16x32_bf16 v[86:89], v[196:199], v[228:231], v[86:89]
	v_mfma_f32_16x16x32_bf16 v[82:85], v[204:207], v[228:231], v[82:85]
	v_mfma_f32_16x16x32_bf16 v[70:73], v[196:199], v[236:239], v[70:73]
	v_mfma_f32_16x16x32_bf16 v[66:69], v[204:207], v[236:239], v[66:69]
	s_barrier
	s_add_i32 s72, s72, s43
	v_lshl_add_u64 v[138:139], s[70:71], 0, v[0:1]
	s_mov_b32 m0, s72
	ds_read_b128 v[208:211], v163 offset:16384
	ds_read_b128 v[212:215], v163 offset:17408
	ds_read_b128 v[216:219], v163 offset:18432
	ds_read_b128 v[220:223], v163 offset:19456
	ds_read_b128 v[224:227], v163 offset:20480
	ds_read_b128 v[228:231], v163 offset:21504
	ds_read_b128 v[232:235], v163 offset:22528
	ds_read_b128 v[236:239], v163 offset:23552
	global_load_lds_dwordx4 v[138:139], off
	s_add_i32 m0, s72, 0x2000
	v_lshl_add_u64 v[158:159], s[70:71], 0, v[148:149]
	s_add_u32 s70, s70, s6
	s_addc_u32 s71, s71, s7
	s_add_i32 s69, s69, s43
	global_load_lds_dwordx4 v[158:159], off
	v_lshl_add_u64 v[178:179], s[70:71], 0, v[0:1]
	s_mov_b32 m0, s69
	v_lshl_add_u64 v[240:241], s[70:71], 0, v[148:149]
	global_load_lds_dwordx4 v[178:179], off
	s_add_i32 m0, s69, 0x2000
	v_lshl_add_u64 v[242:243], s[24:25], 0, v[152:153]
	global_load_lds_dwordx4 v[240:241], off
	s_mov_b32 m0, s44
	v_lshl_add_u64 v[244:245], s[24:25], 0, v[150:151]
	global_load_lds_dwordx4 v[242:243], off
	s_mov_b32 m0, s45
	s_nop 0
	global_load_lds_dwordx4 v[244:245], off
	s_waitcnt vmcnt(8)
	s_waitcnt lgkmcnt(0)
	s_barrier
; #define PG8_STAGE(bufoff, gbase, voff) do { _Pragma("unroll") for (int _i = 0; _i < 2; ++_i) \
;         __builtin_amdgcn_global_load_lds((const unsigned*)((const char*)(gbase) + (voff)[_i]), (LAS unsigned*)(lds + (bufoff) + ldsw + _i * 8192), 16, 0, 0); } while (0)
; #define PG8_LDA(dst, b, h) do { _Pragma("unroll") for (int m = 0; m < 4; ++m) _Pragma("unroll") for (int k = 0; k < 2; ++k) dst[m][k] = *(const LAS bf16x8*)(lds + PG8_SA(b, h) + aoff + m * 2048 + k * 1024); } while (0)
; #define PG8_LDB(dst, b, h) do { _Pragma("unroll") for (int n = 0; n < 2; ++n) _Pragma("unroll") for (int k = 0; k < 2; ++k) dst[n][k] = *(const LAS bf16x8*)(lds + PG8_SB(b, h) + boff + n * 2048 + k * 1024); } while (0)
; #define PG8_MMA(ai, bj, At, Bt) do { __builtin_amdgcn_s_setprio(1); _Pragma("unroll") for (int m = 0; m < 4; ++m) _Pragma("unroll") for (int n = 0; n < 2; ++n) _Pragma("unroll") for (int k = 0; k < 2; ++k) \
;         acc[ai][bj][m][n] = __builtin_amdgcn_mfma_f32_16x16x32_bf16(Bt[n][k], At[m][k], acc[ai][bj][m][n], 0, 0, 0); __builtin_amdgcn_s_setprio(0); } while (0)
; #define PG8_WAIT_V(n) asm volatile("s_waitcnt vmcnt(" #n ")" ::: "memory")
; #define PG8_WAIT_L(n) asm volatile("s_waitcnt lgkmcnt(" #n ")" ::: "memory")
; #define PG8_BAR __builtin_amdgcn_s_barrier()
; #define PG8_SCHED __builtin_amdgcn_sched_barrier(0)
; template <class Epi, class Sched, bool HALFN = false>
; __device__ __forceinline__ void gemm_phase(LAS unsigned char* lds, const Gemm g, const Sched& S, const Epi& E) {
;     ...
;             PG8_WAIT_V(8); PG8_WAIT_L(0); PG8_BAR; PG8_MMA(1, 0, At, B0); PG8_MMA(1, 1, At, B1); PG8_BAR; PG8_SCHED;
;             PG8_LDB(B0, 1, 0); PG8_LDB(B1, 1, 1); PG8_SCHED; PG8_LDA(At, 1, 0); PG8_STAGE(PG8_SA(0, 1), a2 + hstep, voffA);
;             PG8_WAIT_V(8); PG8_WAIT_L(0); PG8_BAR; PG8_MMA(0, 0, At, B0); PG8_MMA(0, 1, At, B1); PG8_BAR; PG8_SCHED;
	s_waitcnt lgkmcnt(0)
	v_mfma_f32_16x16x32_bf16 v[62:65], v[164:167], v[208:211], v[62:65]
	v_mfma_f32_16x16x32_bf16 v[58:61], v[184:187], v[208:211], v[58:61]
	v_mfma_f32_16x16x32_bf16 v[46:49], v[164:167], v[216:219], v[46:49]
	v_mfma_f32_16x16x32_bf16 v[42:45], v[184:187], v[216:219], v[42:45]
	v_mfma_f32_16x16x32_bf16 v[30:33], v[164:167], v[224:227], v[30:33]
	v_mfma_f32_16x16x32_bf16 v[26:29], v[184:187], v[224:227], v[26:29]
	v_mfma_f32_16x16x32_bf16 v[14:17], v[164:167], v[232:235], v[14:17]
	v_mfma_f32_16x16x32_bf16 v[10:13], v[184:187], v[232:235], v[10:13]
	v_mfma_f32_16x16x32_bf16 v[62:65], v[180:183], v[212:215], v[62:65]
	v_mfma_f32_16x16x32_bf16 v[58:61], v[188:191], v[212:215], v[58:61]
	v_mfma_f32_16x16x32_bf16 v[46:49], v[180:183], v[220:223], v[46:49]
	v_mfma_f32_16x16x32_bf16 v[42:45], v[188:191], v[220:223], v[42:45]
	v_mfma_f32_16x16x32_bf16 v[30:33], v[180:183], v[228:231], v[30:33]
	v_mfma_f32_16x16x32_bf16 v[26:29], v[188:191], v[228:231], v[26:29]
	v_mfma_f32_16x16x32_bf16 v[14:17], v[180:183], v[236:239], v[14:17]
	v_mfma_f32_16x16x32_bf16 v[10:13], v[188:191], v[236:239], v[10:13]
	v_mfma_f32_16x16x32_bf16 v[54:57], v[192:195], v[208:211], v[54:57]
	v_mfma_f32_16x16x32_bf16 v[50:53], v[200:203], v[208:211], v[50:53]
	v_mfma_f32_16x16x32_bf16 v[38:41], v[192:195], v[216:219], v[38:41]
	v_mfma_f32_16x16x32_bf16 v[34:37], v[200:203], v[216:219], v[34:37]
	v_mfma_f32_16x16x32_bf16 v[22:25], v[192:195], v[224:227], v[22:25]
	v_mfma_f32_16x16x32_bf16 v[18:21], v[200:203], v[224:227], v[18:21]
	v_mfma_f32_16x16x32_bf16 v[6:9], v[192:195], v[232:235], v[6:9]
	v_mfma_f32_16x16x32_bf16 v[2:5], v[200:203], v[232:235], v[2:5]
	v_mfma_f32_16x16x32_bf16 v[54:57], v[196:199], v[212:215], v[54:57]
	v_mfma_f32_16x16x32_bf16 v[50:53], v[204:207], v[212:215], v[50:53]
	v_mfma_f32_16x16x32_bf16 v[38:41], v[196:199], v[220:223], v[38:41]
	v_mfma_f32_16x16x32_bf16 v[34:37], v[204:207], v[220:223], v[34:37]
	v_mfma_f32_16x16x32_bf16 v[22:25], v[196:199], v[228:231], v[22:25]
	v_mfma_f32_16x16x32_bf16 v[18:21], v[204:207], v[228:231], v[18:21]
	v_mfma_f32_16x16x32_bf16 v[6:9], v[196:199], v[236:239], v[6:9]
	v_mfma_f32_16x16x32_bf16 v[2:5], v[204:207], v[236:239], v[2:5]
	s_barrier
	s_add_i32 s69, 0, 0x18000
	s_add_i32 s70, 0, 0x1c000
	v_add_u32_e32 v188, s69, v161
	v_add_u32_e32 v204, s70, v161
	ds_read_b128 v[164:167], v188
	ds_read_b128 v[180:183], v188 offset:1024
	ds_read_b128 v[184:187], v188 offset:2048
	ds_read_b128 v[188:191], v188 offset:3072
	ds_read_b128 v[192:195], v204
	ds_read_b128 v[196:199], v204 offset:1024
	ds_read_b128 v[200:203], v204 offset:2048
	ds_read_b128 v[204:207], v204 offset:3072
	s_add_u32 s24, s24, s6
	s_addc_u32 s25, s25, s7
	s_mov_b32 m0, s54
	v_lshl_add_u64 v[246:247], s[24:25], 0, v[152:153]
	ds_read_b128 v[208:211], v163 offset:32768
	ds_read_b128 v[212:215], v163 offset:33792
	ds_read_b128 v[216:219], v163 offset:34816
	ds_read_b128 v[220:223], v163 offset:35840
	ds_read_b128 v[224:227], v163 offset:36864
	ds_read_b128 v[228:231], v163 offset:37888
	ds_read_b128 v[232:235], v163 offset:38912
	ds_read_b128 v[236:239], v163 offset:39936
	global_load_lds_dwordx4 v[246:247], off
	v_lshl_add_u64 v[246:247], s[24:25], 0, v[150:151]
	s_mov_b32 m0, s55
	s_nop 0
	global_load_lds_dwordx4 v[246:247], off
	s_waitcnt vmcnt(8)
	s_waitcnt lgkmcnt(0)
	s_barrier
	s_waitcnt lgkmcnt(0)
	v_mfma_f32_16x16x32_bf16 v[126:129], v[164:167], v[208:211], v[126:129]
	v_mfma_f32_16x16x32_bf16 v[122:125], v[184:187], v[208:211], v[122:125]
	v_mfma_f32_16x16x32_bf16 v[110:113], v[164:167], v[216:219], v[110:113]
	v_mfma_f32_16x16x32_bf16 v[106:109], v[184:187], v[216:219], v[106:109]
	v_mfma_f32_16x16x32_bf16 v[94:97], v[164:167], v[224:227], v[94:97]
	v_mfma_f32_16x16x32_bf16 v[90:93], v[184:187], v[224:227], v[90:93]
	v_mfma_f32_16x16x32_bf16 v[78:81], v[164:167], v[232:235], v[78:81]
	v_mfma_f32_16x16x32_bf16 v[74:77], v[184:187], v[232:235], v[74:77]
	v_mfma_f32_16x16x32_bf16 v[126:129], v[180:183], v[212:215], v[126:129]
	v_mfma_f32_16x16x32_bf16 v[122:125], v[188:191], v[212:215], v[122:125]
	v_mfma_f32_16x16x32_bf16 v[110:113], v[180:183], v[220:223], v[110:113]
	v_mfma_f32_16x16x32_bf16 v[106:109], v[188:191], v[220:223], v[106:109]
	v_mfma_f32_16x16x32_bf16 v[94:97], v[180:183], v[228:231], v[94:97]
	v_mfma_f32_16x16x32_bf16 v[90:93], v[188:191], v[228:231], v[90:93]
	v_mfma_f32_16x16x32_bf16 v[78:81], v[180:183], v[236:239], v[78:81]
	v_mfma_f32_16x16x32_bf16 v[74:77], v[188:191], v[236:239], v[74:77]
	v_mfma_f32_16x16x32_bf16 v[118:121], v[192:195], v[208:211], v[118:121]
	v_mfma_f32_16x16x32_bf16 v[114:117], v[200:203], v[208:211], v[114:117]
	v_mfma_f32_16x16x32_bf16 v[102:105], v[192:195], v[216:219], v[102:105]
	v_mfma_f32_16x16x32_bf16 v[98:101], v[200:203], v[216:219], v[98:101]
	v_mfma_f32_16x16x32_bf16 v[86:89], v[192:195], v[224:227], v[86:89]
	v_mfma_f32_16x16x32_bf16 v[82:85], v[200:203], v[224:227], v[82:85]
	v_mfma_f32_16x16x32_bf16 v[70:73], v[192:195], v[232:235], v[70:73]
	v_mfma_f32_16x16x32_bf16 v[66:69], v[200:203], v[232:235], v[66:69]
	v_mfma_f32_16x16x32_bf16 v[118:121], v[196:199], v[212:215], v[118:121]
	v_mfma_f32_16x16x32_bf16 v[114:117], v[204:207], v[212:215], v[114:117]
	v_mfma_f32_16x16x32_bf16 v[102:105], v[196:199], v[220:223], v[102:105]
	v_mfma_f32_16x16x32_bf16 v[98:101], v[204:207], v[220:223], v[98:101]
	v_mfma_f32_16x16x32_bf16 v[86:89], v[196:199], v[228:231], v[86:89]
	v_mfma_f32_16x16x32_bf16 v[82:85], v[204:207], v[228:231], v[82:85]
	v_mfma_f32_16x16x32_bf16 v[70:73], v[196:199], v[236:239], v[70:73]
	v_mfma_f32_16x16x32_bf16 v[66:69], v[204:207], v[236:239], v[66:69]
	s_barrier
; #define PG8_STAGE(bufoff, gbase, voff) do { _Pragma("unroll") for (int _i = 0; _i < 2; ++_i) \
;         __builtin_amdgcn_global_load_lds((const unsigned*)((const char*)(gbase) + (voff)[_i]), (LAS unsigned*)(lds + (bufoff) + ldsw + _i * 8192), 16, 0, 0); } while (0)
; #define PG8_LDA(dst, b, h) do { _Pragma("unroll") for (int m = 0; m < 4; ++m) _Pragma("unroll") for (int k = 0; k < 2; ++k) dst[m][k] = *(const LAS bf16x8*)(lds + PG8_SA(b, h) + aoff + m * 2048 + k * 1024); } while (0)
; #define PG8_MMA(ai, bj, At, Bt) do { __builtin_amdgcn_s_setprio(1); _Pragma("unroll") for (int m = 0; m < 4; ++m) _Pragma("unroll") for (int n = 0; n < 2; ++n) _Pragma("unroll") for (int k = 0; k < 2; ++k) \
;         acc[ai][bj][m][n] = __builtin_amdgcn_mfma_f32_16x16x32_bf16(Bt[n][k], At[m][k], acc[ai][bj][m][n], 0, 0, 0); __builtin_amdgcn_s_setprio(0); } while (0)
; #define PG8_WAIT_V(n) asm volatile("s_waitcnt vmcnt(" #n ")" ::: "memory")
; #define PG8_WAIT_L(n) asm volatile("s_waitcnt lgkmcnt(" #n ")" ::: "memory")
; #define PG8_BAR __builtin_amdgcn_s_barrier()
; #define PG8_SCHED __builtin_amdgcn_sched_barrier(0)
; template <class Epi, class Sched, bool HALFN = false>
; __device__ __forceinline__ void gemm_phase(LAS unsigned char* lds, const Gemm g, const Sched& S, const Epi& E) {
;     ...
;             PG8_LDA(At, 1, 1); PG8_STAGE(PG8_SB(1, 0), b3, voffB); PG8_STAGE(PG8_SB(1, 1), b3 + hstep, voffB); PG8_STAGE(PG8_SA(1, 0), a3, voffA);
;             PG8_WAIT_V(8); PG8_WAIT_L(0); PG8_BAR; PG8_MMA(1, 0, At, B0); PG8_MMA(1, 1, At, B1); PG8_BAR; PG8_SCHED;
;             }
;         }
	s_add_i32 s24, s69, s43
	v_lshl_add_u64 v[138:139], v[138:139], 0, s[26:27]
	s_mov_b32 m0, s24
	ds_read_b128 v[208:211], v163 offset:49152
	ds_read_b128 v[212:215], v163 offset:50176
	ds_read_b128 v[216:219], v163 offset:51200
	ds_read_b128 v[220:223], v163 offset:52224
	ds_read_b128 v[224:227], v163 offset:53248
	ds_read_b128 v[228:231], v163 offset:54272
	ds_read_b128 v[232:235], v163 offset:55296
	ds_read_b128 v[236:239], v163 offset:56320
	global_load_lds_dwordx4 v[138:139], off
	v_lshl_add_u64 v[138:139], v[158:159], 0, s[26:27]
	s_add_i32 m0, s24, 0x2000
	s_add_i32 s24, s70, s43
	global_load_lds_dwordx4 v[138:139], off
	v_lshl_add_u64 v[138:139], v[178:179], 0, s[26:27]
	s_mov_b32 m0, s24
	s_nop 0
	global_load_lds_dwordx4 v[138:139], off
	v_lshl_add_u64 v[138:139], v[240:241], 0, s[26:27]
	s_add_i32 m0, s24, 0x2000
	s_nop 0
	global_load_lds_dwordx4 v[138:139], off
	v_lshl_add_u64 v[138:139], v[242:243], 0, s[26:27]
	s_mov_b32 m0, s58
	s_nop 0
	global_load_lds_dwordx4 v[138:139], off
	v_lshl_add_u64 v[138:139], v[244:245], 0, s[26:27]
	s_mov_b32 m0, s59
	s_nop 0
	global_load_lds_dwordx4 v[138:139], off
	s_waitcnt vmcnt(8)
	s_waitcnt lgkmcnt(0)
	s_barrier
	s_waitcnt lgkmcnt(0)
	v_mfma_f32_16x16x32_bf16 v[62:65], v[164:167], v[208:211], v[62:65]
	v_mfma_f32_16x16x32_bf16 v[58:61], v[184:187], v[208:211], v[58:61]
	v_mfma_f32_16x16x32_bf16 v[46:49], v[164:167], v[216:219], v[46:49]
	v_mfma_f32_16x16x32_bf16 v[42:45], v[184:187], v[216:219], v[42:45]
	v_mfma_f32_16x16x32_bf16 v[30:33], v[164:167], v[224:227], v[30:33]
	v_mfma_f32_16x16x32_bf16 v[26:29], v[184:187], v[224:227], v[26:29]
	v_mfma_f32_16x16x32_bf16 v[14:17], v[164:167], v[232:235], v[14:17]
	v_mfma_f32_16x16x32_bf16 v[10:13], v[184:187], v[232:235], v[10:13]
	v_mfma_f32_16x16x32_bf16 v[62:65], v[180:183], v[212:215], v[62:65]
	v_mfma_f32_16x16x32_bf16 v[58:61], v[188:191], v[212:215], v[58:61]
	v_mfma_f32_16x16x32_bf16 v[46:49], v[180:183], v[220:223], v[46:49]
	v_mfma_f32_16x16x32_bf16 v[42:45], v[188:191], v[220:223], v[42:45]
	v_mfma_f32_16x16x32_bf16 v[30:33], v[180:183], v[228:231], v[30:33]
	v_mfma_f32_16x16x32_bf16 v[26:29], v[188:191], v[228:231], v[26:29]
	v_mfma_f32_16x16x32_bf16 v[14:17], v[180:183], v[236:239], v[14:17]
	v_mfma_f32_16x16x32_bf16 v[10:13], v[188:191], v[236:239], v[10:13]
	v_mfma_f32_16x16x32_bf16 v[54:57], v[192:195], v[208:211], v[54:57]
	v_mfma_f32_16x16x32_bf16 v[50:53], v[200:203], v[208:211], v[50:53]
	v_mfma_f32_16x16x32_bf16 v[38:41], v[192:195], v[216:219], v[38:41]
	v_mfma_f32_16x16x32_bf16 v[34:37], v[200:203], v[216:219], v[34:37]
	v_mfma_f32_16x16x32_bf16 v[22:25], v[192:195], v[224:227], v[22:25]
	v_mfma_f32_16x16x32_bf16 v[18:21], v[200:203], v[224:227], v[18:21]
	v_mfma_f32_16x16x32_bf16 v[6:9], v[192:195], v[232:235], v[6:9]
	v_mfma_f32_16x16x32_bf16 v[2:5], v[200:203], v[232:235], v[2:5]
	v_mfma_f32_16x16x32_bf16 v[54:57], v[196:199], v[212:215], v[54:57]
	v_mfma_f32_16x16x32_bf16 v[50:53], v[204:207], v[212:215], v[50:53]
	v_mfma_f32_16x16x32_bf16 v[38:41], v[196:199], v[220:223], v[38:41]
	v_mfma_f32_16x16x32_bf16 v[34:37], v[204:207], v[220:223], v[34:37]
	v_mfma_f32_16x16x32_bf16 v[22:25], v[196:199], v[228:231], v[22:25]
	v_mfma_f32_16x16x32_bf16 v[18:21], v[204:207], v[228:231], v[18:21]
	v_mfma_f32_16x16x32_bf16 v[6:9], v[196:199], v[236:239], v[6:9]
	v_mfma_f32_16x16x32_bf16 v[2:5], v[204:207], v[236:239], v[2:5]
	s_barrier
	s_add_u32 s17, s17, 0x100
	s_addc_u32 s67, s67, 0
	s_add_u32 s22, s22, 0x100
	s_addc_u32 s23, s23, 0
	s_cmp_ge_i32 s68, s61
	s_mov_b32 s24, s68
	s_cbranch_scc0 .LBB0_383

; #define PG8_STAGE(bufoff, gbase, voff) do { _Pragma("unroll") for (int _i = 0; _i < 2; ++_i) \
;         __builtin_amdgcn_global_load_lds((const unsigned*)((const char*)(gbase) + (voff)[_i]), (LAS unsigned*)(lds + (bufoff) + ldsw + _i * 8192), 16, 0, 0); } while (0)
; #define PG8_LDA(dst, b, h) do { _Pragma("unroll") for (int m = 0; m < 4; ++m) _Pragma("unroll") for (int k = 0; k < 2; ++k) dst[m][k] = *(const LAS bf16x8*)(lds + PG8_SA(b, h) + aoff + m * 2048 + k * 1024); } while (0)
; template <class Epi, class Sched, bool HALFN = false>
; __device__ __forceinline__ void gemm_phase(LAS unsigned char* lds, const Gemm g, const Sched& S, const Epi& E) {
;     ...
;         for (int t = 0; t < nt; t += 2) {
;             const bool last = (t == nt - 2);
;             const char* a1 = cA + (size_t)(t + 1) * kstep;
;             const char* a2 = last ? nA : cA + (size_t)(t + 2) * kstep; const char* b2 = last ? nB : cB + (size_t)(t + 2) * kstep;
;             const char* a3 = a2 + kstep; const char* b3 = b2 + kstep;
;             if constexpr (HALFN) {
;             PG8_LDB(B0, 0, 0); PG8_SCHED; PG8_LDA(At, 0, 0); PG8_STAGE(PG8_SA(1, 1), a1 + hstep, voffA);
;             PG8_WAIT_V(6); PG8_WAIT_L(0); PG8_BAR; PG8_MMA(0, 0, At, B0); PG8_BAR; PG8_SCHED;
;             PG8_LDA(At, 0, 1); PG8_STAGE(PG8_SB(0, 0), b2, voffB); PG8_STAGE(PG8_SA(0, 0), a2, voffA);
;             PG8_WAIT_V(6); PG8_WAIT_L(0); PG8_BAR; PG8_MMA(1, 0, At, B0); PG8_BAR; PG8_SCHED;
;             PG8_LDB(B0, 1, 0); PG8_SCHED; PG8_LDA(At, 1, 0); PG8_STAGE(PG8_SA(0, 1), a2 + hstep, voffA);
;             PG8_WAIT_V(6); PG8_WAIT_L(0); PG8_BAR; PG8_MMA(0, 0, At, B0); PG8_BAR; PG8_SCHED;
;             PG8_LDA(At, 1, 1); PG8_STAGE(PG8_SB(1, 0), b3, voffB); PG8_STAGE(PG8_SA(1, 0), a3, voffA);
;             PG8_WAIT_V(6); PG8_WAIT_L(0); PG8_BAR; PG8_MMA(1, 0, At, B0); PG8_BAR; PG8_SCHED;
;             } else {
;             PG8_LDB(B0, 0, 0); PG8_LDB(B1, 0, 1); PG8_SCHED; PG8_LDA(At, 0, 0); PG8_STAGE(PG8_SA(1, 1), a1 + hstep, voffA);
;             PG8_WAIT_V(8); PG8_WAIT_L(0); PG8_BAR; PG8_MMA(0, 0, At, B0); PG8_MMA(0, 1, At, B1); PG8_BAR; PG8_SCHED;
;             PG8_LDA(At, 0, 1); PG8_STAGE(PG8_SB(0, 0), b2, voffB); PG8_STAGE(PG8_SB(0, 1), b2 + hstep, voffB); PG8_STAGE(PG8_SA(0, 0), a2, voffA);
;             PG8_WAIT_V(8); PG8_WAIT_L(0); PG8_BAR; PG8_MMA(1, 0, At, B0); PG8_MMA(1, 1, At, B1); PG8_BAR; PG8_SCHED;
.LBB0_466:
	s_add_i32 s34, s24, 2
	s_add_u32 s35, s4, 0x80
	s_addc_u32 s25, s5, 0
	s_add_i32 s72, 0, 0x10000
	s_cmp_eq_u32 s62, s24
	s_cselect_b32 s25, s21, s25
	s_cselect_b32 s24, s20, s35
	v_add_u32_e32 v0, s72, v180
	s_cselect_b32 s71, s23, s69
	s_cselect_b32 s70, s22, s68
	s_add_i32 s35, 0, 0x14000
	ds_read_b128 v[160:163], v0
	ds_read_b128 v[164:167], v0 offset:1024
	ds_read_b128 v[184:187], v0 offset:2048
	ds_read_b128 v[188:191], v0 offset:3072
	v_add_u32_e32 v0, s35, v180
	ds_read_b128 v[192:195], v0
	ds_read_b128 v[196:199], v0 offset:1024
	ds_read_b128 v[200:203], v0 offset:2048
	ds_read_b128 v[204:207], v0 offset:3072
	v_lshl_add_u64 v[240:241], s[4:5], 0, v[158:159]
	s_add_i32 m0, s55, 0xc000
	ds_read_b128 v[208:211], v182
	ds_read_b128 v[212:215], v182 offset:1024
	ds_read_b128 v[216:219], v182 offset:2048
	ds_read_b128 v[220:223], v182 offset:3072
	ds_read_b128 v[224:227], v182 offset:4096
	ds_read_b128 v[228:231], v182 offset:5120
	ds_read_b128 v[232:235], v182 offset:6144
	ds_read_b128 v[236:239], v182 offset:7168
	global_load_lds_dwordx4 v[240:241], off
	v_lshl_add_u64 v[240:241], s[4:5], 0, v[156:157]
	s_add_i32 m0, s55, 0xe000
	s_nop 0
	global_load_lds_dwordx4 v[240:241], off
	s_waitcnt vmcnt(8)
	s_waitcnt lgkmcnt(0)
	s_barrier
	s_waitcnt lgkmcnt(0)
	v_mfma_f32_16x16x32_bf16 v[122:125], v[160:163], v[208:211], v[122:125]
	v_mfma_f32_16x16x32_bf16 v[126:129], v[184:187], v[208:211], v[126:129]
	v_mfma_f32_16x16x32_bf16 v[110:113], v[160:163], v[216:219], v[110:113]
	v_mfma_f32_16x16x32_bf16 v[106:109], v[184:187], v[216:219], v[106:109]
	v_mfma_f32_16x16x32_bf16 v[94:97], v[160:163], v[224:227], v[94:97]
	v_mfma_f32_16x16x32_bf16 v[90:93], v[184:187], v[224:227], v[90:93]
	v_mfma_f32_16x16x32_bf16 v[78:81], v[160:163], v[232:235], v[78:81]
	v_mfma_f32_16x16x32_bf16 v[74:77], v[184:187], v[232:235], v[74:77]
	v_mfma_f32_16x16x32_bf16 v[122:125], v[164:167], v[212:215], v[122:125]
	v_mfma_f32_16x16x32_bf16 v[126:129], v[188:191], v[212:215], v[126:129]
	v_mfma_f32_16x16x32_bf16 v[110:113], v[164:167], v[220:223], v[110:113]
	v_mfma_f32_16x16x32_bf16 v[106:109], v[188:191], v[220:223], v[106:109]
	v_mfma_f32_16x16x32_bf16 v[94:97], v[164:167], v[228:231], v[94:97]
	v_mfma_f32_16x16x32_bf16 v[90:93], v[188:191], v[228:231], v[90:93]
	v_mfma_f32_16x16x32_bf16 v[78:81], v[164:167], v[236:239], v[78:81]
	v_mfma_f32_16x16x32_bf16 v[74:77], v[188:191], v[236:239], v[74:77]
	v_mfma_f32_16x16x32_bf16 v[118:121], v[192:195], v[208:211], v[118:121]
	v_mfma_f32_16x16x32_bf16 v[114:117], v[200:203], v[208:211], v[114:117]
	v_mfma_f32_16x16x32_bf16 v[102:105], v[192:195], v[216:219], v[102:105]
	v_mfma_f32_16x16x32_bf16 v[98:101], v[200:203], v[216:219], v[98:101]
	v_mfma_f32_16x16x32_bf16 v[86:89], v[192:195], v[224:227], v[86:89]
	v_mfma_f32_16x16x32_bf16 v[82:85], v[200:203], v[224:227], v[82:85]
	v_mfma_f32_16x16x32_bf16 v[70:73], v[192:195], v[232:235], v[70:73]
	v_mfma_f32_16x16x32_bf16 v[66:69], v[200:203], v[232:235], v[66:69]
	v_mfma_f32_16x16x32_bf16 v[118:121], v[196:199], v[212:215], v[118:121]
	v_mfma_f32_16x16x32_bf16 v[114:117], v[204:207], v[212:215], v[114:117]
	v_mfma_f32_16x16x32_bf16 v[102:105], v[196:199], v[220:223], v[102:105]
	v_mfma_f32_16x16x32_bf16 v[98:101], v[204:207], v[220:223], v[98:101]
	v_mfma_f32_16x16x32_bf16 v[86:89], v[196:199], v[228:231], v[86:89]
	v_mfma_f32_16x16x32_bf16 v[82:85], v[204:207], v[228:231], v[82:85]
	v_mfma_f32_16x16x32_bf16 v[70:73], v[196:199], v[236:239], v[70:73]
	v_mfma_f32_16x16x32_bf16 v[66:69], v[204:207], v[236:239], v[66:69]
	s_barrier
	s_add_i32 s72, s72, s54
	v_lshl_add_u64 v[240:241], s[70:71], 0, v[150:151]
	s_mov_b32 m0, s72
	ds_read_b128 v[208:211], v182 offset:16384
	ds_read_b128 v[212:215], v182 offset:17408
	ds_read_b128 v[216:219], v182 offset:18432
	ds_read_b128 v[220:223], v182 offset:19456
	ds_read_b128 v[224:227], v182 offset:20480
	ds_read_b128 v[228:231], v182 offset:21504
	ds_read_b128 v[232:235], v182 offset:22528
	ds_read_b128 v[236:239], v182 offset:23552
	global_load_lds_dwordx4 v[240:241], off
	s_add_i32 m0, s72, 0x2000
	v_lshl_add_u64 v[242:243], s[70:71], 0, v[154:155]
	s_add_u32 s70, s70, s6
	s_addc_u32 s71, s71, s7
	s_add_i32 s35, s35, s54
	global_load_lds_dwordx4 v[242:243], off
	v_lshl_add_u64 v[244:245], s[70:71], 0, v[150:151]
	s_mov_b32 m0, s35
	v_lshl_add_u64 v[246:247], s[70:71], 0, v[154:155]
	global_load_lds_dwordx4 v[244:245], off
	s_add_i32 m0, s35, 0x2000
	v_lshl_add_u64 v[248:249], s[24:25], 0, v[148:149]
	global_load_lds_dwordx4 v[246:247], off
	s_mov_b32 m0, s55
	v_lshl_add_u64 v[250:251], s[24:25], 0, v[152:153]
	global_load_lds_dwordx4 v[248:249], off
	s_mov_b32 m0, s56
	s_nop 0
	global_load_lds_dwordx4 v[250:251], off
	s_waitcnt vmcnt(8)
	s_waitcnt lgkmcnt(0)
	s_barrier
; #define PG8_STAGE(bufoff, gbase, voff) do { _Pragma("unroll") for (int _i = 0; _i < 2; ++_i) \
;         __builtin_amdgcn_global_load_lds((const unsigned*)((const char*)(gbase) + (voff)[_i]), (LAS unsigned*)(lds + (bufoff) + ldsw + _i * 8192), 16, 0, 0); } while (0)
; #define PG8_LDA(dst, b, h) do { _Pragma("unroll") for (int m = 0; m < 4; ++m) _Pragma("unroll") for (int k = 0; k < 2; ++k) dst[m][k] = *(const LAS bf16x8*)(lds + PG8_SA(b, h) + aoff + m * 2048 + k * 1024); } while (0)
; #define PG8_LDB(dst, b, h) do { _Pragma("unroll") for (int n = 0; n < 2; ++n) _Pragma("unroll") for (int k = 0; k < 2; ++k) dst[n][k] = *(const LAS bf16x8*)(lds + PG8_SB(b, h) + boff + n * 2048 + k * 1024); } while (0)
; #define PG8_MMA(ai, bj, At, Bt) do { __builtin_amdgcn_s_setprio(1); _Pragma("unroll") for (int m = 0; m < 4; ++m) _Pragma("unroll") for (int n = 0; n < 2; ++n) _Pragma("unroll") for (int k = 0; k < 2; ++k) \
;         acc[ai][bj][m][n] = __builtin_amdgcn_mfma_f32_16x16x32_bf16(Bt[n][k], At[m][k], acc[ai][bj][m][n], 0, 0, 0); __builtin_amdgcn_s_setprio(0); } while (0)
; #define PG8_WAIT_V(n) asm volatile("s_waitcnt vmcnt(" #n ")" ::: "memory")
; #define PG8_WAIT_L(n) asm volatile("s_waitcnt lgkmcnt(" #n ")" ::: "memory")
; #define PG8_BAR __builtin_amdgcn_s_barrier()
; #define PG8_SCHED __builtin_amdgcn_sched_barrier(0)
; template <class Epi, class Sched, bool HALFN = false>
; __device__ __forceinline__ void gemm_phase(LAS unsigned char* lds, const Gemm g, const Sched& S, const Epi& E) {
;     ...
;             PG8_WAIT_V(8); PG8_WAIT_L(0); PG8_BAR; PG8_MMA(1, 0, At, B0); PG8_MMA(1, 1, At, B1); PG8_BAR; PG8_SCHED;
;             PG8_LDB(B0, 1, 0); PG8_LDB(B1, 1, 1); PG8_SCHED; PG8_LDA(At, 1, 0); PG8_STAGE(PG8_SA(0, 1), a2 + hstep, voffA);
;             PG8_WAIT_V(8); PG8_WAIT_L(0); PG8_BAR; PG8_MMA(0, 0, At, B0); PG8_MMA(0, 1, At, B1); PG8_BAR; PG8_SCHED;
	s_waitcnt lgkmcnt(0)
	v_mfma_f32_16x16x32_bf16 v[62:65], v[160:163], v[208:211], v[62:65]
	v_mfma_f32_16x16x32_bf16 v[58:61], v[184:187], v[208:211], v[58:61]
	v_mfma_f32_16x16x32_bf16 v[46:49], v[160:163], v[216:219], v[46:49]
	v_mfma_f32_16x16x32_bf16 v[42:45], v[184:187], v[216:219], v[42:45]
	v_mfma_f32_16x16x32_bf16 v[30:33], v[160:163], v[224:227], v[30:33]
	v_mfma_f32_16x16x32_bf16 v[26:29], v[184:187], v[224:227], v[26:29]
	v_mfma_f32_16x16x32_bf16 v[14:17], v[160:163], v[232:235], v[14:17]
	v_mfma_f32_16x16x32_bf16 v[10:13], v[184:187], v[232:235], v[10:13]
	v_mfma_f32_16x16x32_bf16 v[62:65], v[164:167], v[212:215], v[62:65]
	v_mfma_f32_16x16x32_bf16 v[58:61], v[188:191], v[212:215], v[58:61]
	v_mfma_f32_16x16x32_bf16 v[46:49], v[164:167], v[220:223], v[46:49]
	v_mfma_f32_16x16x32_bf16 v[42:45], v[188:191], v[220:223], v[42:45]
	v_mfma_f32_16x16x32_bf16 v[30:33], v[164:167], v[228:231], v[30:33]
	v_mfma_f32_16x16x32_bf16 v[26:29], v[188:191], v[228:231], v[26:29]
	v_mfma_f32_16x16x32_bf16 v[14:17], v[164:167], v[236:239], v[14:17]
	v_mfma_f32_16x16x32_bf16 v[10:13], v[188:191], v[236:239], v[10:13]
	v_mfma_f32_16x16x32_bf16 v[54:57], v[192:195], v[208:211], v[54:57]
	v_mfma_f32_16x16x32_bf16 v[50:53], v[200:203], v[208:211], v[50:53]
	v_mfma_f32_16x16x32_bf16 v[38:41], v[192:195], v[216:219], v[38:41]
	v_mfma_f32_16x16x32_bf16 v[34:37], v[200:203], v[216:219], v[34:37]
	v_mfma_f32_16x16x32_bf16 v[22:25], v[192:195], v[224:227], v[22:25]
	v_mfma_f32_16x16x32_bf16 v[18:21], v[200:203], v[224:227], v[18:21]
	v_mfma_f32_16x16x32_bf16 v[6:9], v[192:195], v[232:235], v[6:9]
	v_mfma_f32_16x16x32_bf16 v[2:5], v[200:203], v[232:235], v[2:5]
	v_mfma_f32_16x16x32_bf16 v[54:57], v[196:199], v[212:215], v[54:57]
	v_mfma_f32_16x16x32_bf16 v[50:53], v[204:207], v[212:215], v[50:53]
	v_mfma_f32_16x16x32_bf16 v[38:41], v[196:199], v[220:223], v[38:41]
	v_mfma_f32_16x16x32_bf16 v[34:37], v[204:207], v[220:223], v[34:37]
	v_mfma_f32_16x16x32_bf16 v[22:25], v[196:199], v[228:231], v[22:25]
	v_mfma_f32_16x16x32_bf16 v[18:21], v[204:207], v[228:231], v[18:21]
	v_mfma_f32_16x16x32_bf16 v[6:9], v[196:199], v[236:239], v[6:9]
	v_mfma_f32_16x16x32_bf16 v[2:5], v[204:207], v[236:239], v[2:5]
	s_barrier
	s_add_i32 s35, 0, 0x18000
	v_add_u32_e32 v0, s35, v180
	s_add_i32 s70, 0, 0x1c000
	ds_read_b128 v[160:163], v0
	ds_read_b128 v[164:167], v0 offset:1024
	ds_read_b128 v[184:187], v0 offset:2048
	ds_read_b128 v[188:191], v0 offset:3072
	v_add_u32_e32 v0, s70, v180
	ds_read_b128 v[192:195], v0
	ds_read_b128 v[196:199], v0 offset:1024
	ds_read_b128 v[200:203], v0 offset:2048
	ds_read_b128 v[204:207], v0 offset:3072
	s_add_u32 s24, s24, s6
	s_addc_u32 s25, s25, s7
	s_mov_b32 m0, s57
	v_lshl_add_u64 v[138:139], s[24:25], 0, v[148:149]
	ds_read_b128 v[208:211], v182 offset:32768
	ds_read_b128 v[212:215], v182 offset:33792
	ds_read_b128 v[216:219], v182 offset:34816
	ds_read_b128 v[220:223], v182 offset:35840
	ds_read_b128 v[224:227], v182 offset:36864
	ds_read_b128 v[228:231], v182 offset:37888
	ds_read_b128 v[232:235], v182 offset:38912
	ds_read_b128 v[236:239], v182 offset:39936
	global_load_lds_dwordx4 v[138:139], off
	v_lshl_add_u64 v[138:139], s[24:25], 0, v[152:153]
	s_mov_b32 m0, s58
	s_nop 0
	global_load_lds_dwordx4 v[138:139], off
	s_waitcnt vmcnt(8)
	s_waitcnt lgkmcnt(0)
	s_barrier
	s_waitcnt lgkmcnt(0)
	v_mfma_f32_16x16x32_bf16 v[122:125], v[160:163], v[208:211], v[122:125]
	v_mfma_f32_16x16x32_bf16 v[126:129], v[184:187], v[208:211], v[126:129]
	v_mfma_f32_16x16x32_bf16 v[110:113], v[160:163], v[216:219], v[110:113]
	v_mfma_f32_16x16x32_bf16 v[106:109], v[184:187], v[216:219], v[106:109]
	v_mfma_f32_16x16x32_bf16 v[94:97], v[160:163], v[224:227], v[94:97]
	v_mfma_f32_16x16x32_bf16 v[90:93], v[184:187], v[224:227], v[90:93]
	v_mfma_f32_16x16x32_bf16 v[78:81], v[160:163], v[232:235], v[78:81]
	v_mfma_f32_16x16x32_bf16 v[74:77], v[184:187], v[232:235], v[74:77]
	v_mfma_f32_16x16x32_bf16 v[122:125], v[164:167], v[212:215], v[122:125]
	v_mfma_f32_16x16x32_bf16 v[126:129], v[188:191], v[212:215], v[126:129]
	v_mfma_f32_16x16x32_bf16 v[110:113], v[164:167], v[220:223], v[110:113]
	v_mfma_f32_16x16x32_bf16 v[106:109], v[188:191], v[220:223], v[106:109]
	v_mfma_f32_16x16x32_bf16 v[94:97], v[164:167], v[228:231], v[94:97]
	v_mfma_f32_16x16x32_bf16 v[90:93], v[188:191], v[228:231], v[90:93]
	v_mfma_f32_16x16x32_bf16 v[78:81], v[164:167], v[236:239], v[78:81]
	v_mfma_f32_16x16x32_bf16 v[74:77], v[188:191], v[236:239], v[74:77]
	v_mfma_f32_16x16x32_bf16 v[118:121], v[192:195], v[208:211], v[118:121]
	v_mfma_f32_16x16x32_bf16 v[114:117], v[200:203], v[208:211], v[114:117]
	v_mfma_f32_16x16x32_bf16 v[102:105], v[192:195], v[216:219], v[102:105]
	v_mfma_f32_16x16x32_bf16 v[98:101], v[200:203], v[216:219], v[98:101]
	v_mfma_f32_16x16x32_bf16 v[86:89], v[192:195], v[224:227], v[86:89]
	v_mfma_f32_16x16x32_bf16 v[82:85], v[200:203], v[224:227], v[82:85]
	v_mfma_f32_16x16x32_bf16 v[70:73], v[192:195], v[232:235], v[70:73]
	v_mfma_f32_16x16x32_bf16 v[66:69], v[200:203], v[232:235], v[66:69]
	v_mfma_f32_16x16x32_bf16 v[118:121], v[196:199], v[212:215], v[118:121]
	v_mfma_f32_16x16x32_bf16 v[114:117], v[204:207], v[212:215], v[114:117]
	v_mfma_f32_16x16x32_bf16 v[102:105], v[196:199], v[220:223], v[102:105]
	v_mfma_f32_16x16x32_bf16 v[98:101], v[204:207], v[220:223], v[98:101]
	v_mfma_f32_16x16x32_bf16 v[86:89], v[196:199], v[228:231], v[86:89]
	v_mfma_f32_16x16x32_bf16 v[82:85], v[204:207], v[228:231], v[82:85]
	v_mfma_f32_16x16x32_bf16 v[70:73], v[196:199], v[236:239], v[70:73]
	v_mfma_f32_16x16x32_bf16 v[66:69], v[204:207], v[236:239], v[66:69]
	s_barrier
; #define PG8_STAGE(bufoff, gbase, voff) do { _Pragma("unroll") for (int _i = 0; _i < 2; ++_i) \
;         __builtin_amdgcn_global_load_lds((const unsigned*)((const char*)(gbase) + (voff)[_i]), (LAS unsigned*)(lds + (bufoff) + ldsw + _i * 8192), 16, 0, 0); } while (0)
; #define PG8_LDA(dst, b, h) do { _Pragma("unroll") for (int m = 0; m < 4; ++m) _Pragma("unroll") for (int k = 0; k < 2; ++k) dst[m][k] = *(const LAS bf16x8*)(lds + PG8_SA(b, h) + aoff + m * 2048 + k * 1024); } while (0)
; #define PG8_MMA(ai, bj, At, Bt) do { __builtin_amdgcn_s_setprio(1); _Pragma("unroll") for (int m = 0; m < 4; ++m) _Pragma("unroll") for (int n = 0; n < 2; ++n) _Pragma("unroll") for (int k = 0; k < 2; ++k) \
;         acc[ai][bj][m][n] = __builtin_amdgcn_mfma_f32_16x16x32_bf16(Bt[n][k], At[m][k], acc[ai][bj][m][n], 0, 0, 0); __builtin_amdgcn_s_setprio(0); } while (0)
; #define PG8_WAIT_V(n) asm volatile("s_waitcnt vmcnt(" #n ")" ::: "memory")
; #define PG8_WAIT_L(n) asm volatile("s_waitcnt lgkmcnt(" #n ")" ::: "memory")
; #define PG8_BAR __builtin_amdgcn_s_barrier()
; #define PG8_SCHED __builtin_amdgcn_sched_barrier(0)
; template <class Epi, class Sched, bool HALFN = false>
; __device__ __forceinline__ void gemm_phase(LAS unsigned char* lds, const Gemm g, const Sched& S, const Epi& E) {
;     ...
;             PG8_LDA(At, 1, 1); PG8_STAGE(PG8_SB(1, 0), b3, voffB); PG8_STAGE(PG8_SB(1, 1), b3 + hstep, voffB); PG8_STAGE(PG8_SA(1, 0), a3, voffA);
;             PG8_WAIT_V(8); PG8_WAIT_L(0); PG8_BAR; PG8_MMA(1, 0, At, B0); PG8_MMA(1, 1, At, B1); PG8_BAR; PG8_SCHED;
;             }
;         }
	s_add_i32 s24, s35, s54
	v_lshl_add_u64 v[138:139], v[240:241], 0, s[26:27]
	s_mov_b32 m0, s24
	ds_read_b128 v[208:211], v182 offset:49152
	ds_read_b128 v[212:215], v182 offset:50176
	ds_read_b128 v[216:219], v182 offset:51200
	ds_read_b128 v[220:223], v182 offset:52224
	ds_read_b128 v[224:227], v182 offset:53248
	ds_read_b128 v[228:231], v182 offset:54272
	ds_read_b128 v[232:235], v182 offset:55296
	ds_read_b128 v[236:239], v182 offset:56320
	global_load_lds_dwordx4 v[138:139], off
	v_lshl_add_u64 v[138:139], v[242:243], 0, s[26:27]
	s_add_i32 m0, s24, 0x2000
	s_add_i32 s24, s70, s54
	global_load_lds_dwordx4 v[138:139], off
	v_lshl_add_u64 v[138:139], v[244:245], 0, s[26:27]
	s_mov_b32 m0, s24
	s_nop 0
	global_load_lds_dwordx4 v[138:139], off
	v_lshl_add_u64 v[138:139], v[246:247], 0, s[26:27]
	s_add_i32 m0, s24, 0x2000
	s_nop 0
	global_load_lds_dwordx4 v[138:139], off
	v_lshl_add_u64 v[138:139], v[248:249], 0, s[26:27]
	s_mov_b32 m0, s59
	s_nop 0
	global_load_lds_dwordx4 v[138:139], off
	v_lshl_add_u64 v[138:139], v[250:251], 0, s[26:27]
	s_mov_b32 m0, s60
	s_nop 0
	global_load_lds_dwordx4 v[138:139], off
	s_waitcnt vmcnt(8)
	s_waitcnt lgkmcnt(0)
	s_barrier
	s_waitcnt lgkmcnt(0)
	v_mfma_f32_16x16x32_bf16 v[62:65], v[160:163], v[208:211], v[62:65]
	v_mfma_f32_16x16x32_bf16 v[58:61], v[184:187], v[208:211], v[58:61]
	v_mfma_f32_16x16x32_bf16 v[46:49], v[160:163], v[216:219], v[46:49]
	v_mfma_f32_16x16x32_bf16 v[42:45], v[184:187], v[216:219], v[42:45]
	v_mfma_f32_16x16x32_bf16 v[30:33], v[160:163], v[224:227], v[30:33]
	v_mfma_f32_16x16x32_bf16 v[26:29], v[184:187], v[224:227], v[26:29]
	v_mfma_f32_16x16x32_bf16 v[14:17], v[160:163], v[232:235], v[14:17]
	v_mfma_f32_16x16x32_bf16 v[10:13], v[184:187], v[232:235], v[10:13]
	v_mfma_f32_16x16x32_bf16 v[62:65], v[164:167], v[212:215], v[62:65]
	v_mfma_f32_16x16x32_bf16 v[58:61], v[188:191], v[212:215], v[58:61]
	v_mfma_f32_16x16x32_bf16 v[46:49], v[164:167], v[220:223], v[46:49]
	v_mfma_f32_16x16x32_bf16 v[42:45], v[188:191], v[220:223], v[42:45]
	v_mfma_f32_16x16x32_bf16 v[30:33], v[164:167], v[228:231], v[30:33]
	v_mfma_f32_16x16x32_bf16 v[26:29], v[188:191], v[228:231], v[26:29]
	v_mfma_f32_16x16x32_bf16 v[14:17], v[164:167], v[236:239], v[14:17]
	v_mfma_f32_16x16x32_bf16 v[10:13], v[188:191], v[236:239], v[10:13]
	v_mfma_f32_16x16x32_bf16 v[54:57], v[192:195], v[208:211], v[54:57]
	v_mfma_f32_16x16x32_bf16 v[50:53], v[200:203], v[208:211], v[50:53]
	v_mfma_f32_16x16x32_bf16 v[38:41], v[192:195], v[216:219], v[38:41]
	v_mfma_f32_16x16x32_bf16 v[34:37], v[200:203], v[216:219], v[34:37]
	v_mfma_f32_16x16x32_bf16 v[22:25], v[192:195], v[224:227], v[22:25]
	v_mfma_f32_16x16x32_bf16 v[18:21], v[200:203], v[224:227], v[18:21]
	v_mfma_f32_16x16x32_bf16 v[6:9], v[192:195], v[232:235], v[6:9]
	v_mfma_f32_16x16x32_bf16 v[2:5], v[200:203], v[232:235], v[2:5]
	v_mfma_f32_16x16x32_bf16 v[54:57], v[196:199], v[212:215], v[54:57]
	v_mfma_f32_16x16x32_bf16 v[50:53], v[204:207], v[212:215], v[50:53]
	v_mfma_f32_16x16x32_bf16 v[38:41], v[196:199], v[220:223], v[38:41]
	v_mfma_f32_16x16x32_bf16 v[34:37], v[204:207], v[220:223], v[34:37]
	v_mfma_f32_16x16x32_bf16 v[22:25], v[196:199], v[228:231], v[22:25]
	v_mfma_f32_16x16x32_bf16 v[18:21], v[204:207], v[228:231], v[18:21]
	v_mfma_f32_16x16x32_bf16 v[6:9], v[196:199], v[236:239], v[6:9]
	v_mfma_f32_16x16x32_bf16 v[2:5], v[204:207], v[236:239], v[2:5]
	s_barrier
	s_add_u32 s68, s68, 0x100
	s_addc_u32 s69, s69, 0
	s_add_u32 s4, s4, 0x100
	s_addc_u32 s5, s5, 0
	s_cmp_ge_i32 s34, s61
	s_mov_b32 s24, s34
	s_cbranch_scc0 .LBB0_466
	s_mov_b32 s70, 0x80000
	s_mov_b32 s71, 0x90000
	s_mov_b32 s72, 0xa0000
	s_movk_i32 s69, 0x6c00
	v_readlane_b32 s68, v254, 38

; #define PG8_STAGE(bufoff, gbase, voff) do { _Pragma("unroll") for (int _i = 0; _i < 2; ++_i) \
;         __builtin_amdgcn_global_load_lds((const unsigned*)((const char*)(gbase) + (voff)[_i]), (LAS unsigned*)(lds + (bufoff) + ldsw + _i * 8192), 16, 0, 0); } while (0)
; #define PG8_LDA(dst, b, h) do { _Pragma("unroll") for (int m = 0; m < 4; ++m) _Pragma("unroll") for (int k = 0; k < 2; ++k) dst[m][k] = *(const LAS bf16x8*)(lds + PG8_SA(b, h) + aoff + m * 2048 + k * 1024); } while (0)
; template <class Epi, class Sched, bool HALFN = false>
; __device__ __forceinline__ void gemm_phase(LAS unsigned char* lds, const Gemm g, const Sched& S, const Epi& E) {
;     ...
;         for (int t = 0; t < nt; t += 2) {
;             const bool last = (t == nt - 2);
;             const char* a1 = cA + (size_t)(t + 1) * kstep;
;             const char* a2 = last ? nA : cA + (size_t)(t + 2) * kstep; const char* b2 = last ? nB : cB + (size_t)(t + 2) * kstep;
;             const char* a3 = a2 + kstep; const char* b3 = b2 + kstep;
;             if constexpr (HALFN) {
;             PG8_LDB(B0, 0, 0); PG8_SCHED; PG8_LDA(At, 0, 0); PG8_STAGE(PG8_SA(1, 1), a1 + hstep, voffA);
;             PG8_WAIT_V(6); PG8_WAIT_L(0); PG8_BAR; PG8_MMA(0, 0, At, B0); PG8_BAR; PG8_SCHED;
;             PG8_LDA(At, 0, 1); PG8_STAGE(PG8_SB(0, 0), b2, voffB); PG8_STAGE(PG8_SA(0, 0), a2, voffA);
;             PG8_WAIT_V(6); PG8_WAIT_L(0); PG8_BAR; PG8_MMA(1, 0, At, B0); PG8_BAR; PG8_SCHED;
;             PG8_LDB(B0, 1, 0); PG8_SCHED; PG8_LDA(At, 1, 0); PG8_STAGE(PG8_SA(0, 1), a2 + hstep, voffA);
;             PG8_WAIT_V(6); PG8_WAIT_L(0); PG8_BAR; PG8_MMA(0, 0, At, B0); PG8_BAR; PG8_SCHED;
;             PG8_LDA(At, 1, 1); PG8_STAGE(PG8_SB(1, 0), b3, voffB); PG8_STAGE(PG8_SA(1, 0), a3, voffA);
;             PG8_WAIT_V(6); PG8_WAIT_L(0); PG8_BAR; PG8_MMA(1, 0, At, B0); PG8_BAR; PG8_SCHED;
;             } else {
;             PG8_LDB(B0, 0, 0); PG8_LDB(B1, 0, 1); PG8_SCHED; PG8_LDA(At, 0, 0); PG8_STAGE(PG8_SA(1, 1), a1 + hstep, voffA);
;             PG8_WAIT_V(8); PG8_WAIT_L(0); PG8_BAR; PG8_MMA(0, 0, At, B0); PG8_MMA(0, 1, At, B1); PG8_BAR; PG8_SCHED;
;             PG8_LDA(At, 0, 1); PG8_STAGE(PG8_SB(0, 0), b2, voffB); PG8_STAGE(PG8_SB(0, 1), b2 + hstep, voffB); PG8_STAGE(PG8_SA(0, 0), a2, voffA);
;             PG8_WAIT_V(8); PG8_WAIT_L(0); PG8_BAR; PG8_MMA(1, 0, At, B0); PG8_MMA(1, 1, At, B1); PG8_BAR; PG8_SCHED;
.LBB0_557:
	s_add_i32 s64, s22, 2
	s_add_u32 s65, s20, 0x80
	s_addc_u32 s23, s21, 0
	s_add_i32 s68, 0, 0x10000
	s_cmp_eq_u32 s56, s22
	s_cselect_b32 s23, s5, s23
	s_cselect_b32 s22, s4, s65
	v_add_u32_e32 v0, s68, v161
	s_cselect_b32 s67, s19, s63
	s_cselect_b32 s66, s18, s62
	s_add_i32 s65, 0, 0x14000
	ds_read_b128 v[180:183], v0
	ds_read_b128 v[184:187], v0 offset:1024
	ds_read_b128 v[188:191], v0 offset:2048
	ds_read_b128 v[192:195], v0 offset:3072
	v_add_u32_e32 v0, s65, v161
	ds_read_b128 v[196:199], v0
	ds_read_b128 v[200:203], v0 offset:1024
	ds_read_b128 v[204:207], v0 offset:2048
	ds_read_b128 v[208:211], v0 offset:3072
	v_lshl_add_u64 v[138:139], s[20:21], 0, v[158:159]
	s_add_i32 m0, s25, 0xc000
	ds_read_b128 v[212:215], v164
	ds_read_b128 v[216:219], v164 offset:1024
	ds_read_b128 v[220:223], v164 offset:2048
	ds_read_b128 v[224:227], v164 offset:3072
	ds_read_b128 v[228:231], v164 offset:4096
	ds_read_b128 v[232:235], v164 offset:5120
	ds_read_b128 v[236:239], v164 offset:6144
	ds_read_b128 v[240:243], v164 offset:7168
	global_load_lds_dwordx4 v[138:139], off
	v_lshl_add_u64 v[138:139], s[20:21], 0, v[156:157]
	s_add_i32 m0, s25, 0xe000
	s_nop 0
	global_load_lds_dwordx4 v[138:139], off
	s_waitcnt vmcnt(8)
	s_waitcnt lgkmcnt(0)
	s_barrier
	s_waitcnt lgkmcnt(0)
	v_mfma_f32_16x16x32_bf16 v[122:125], v[180:183], v[212:215], v[122:125]
	v_mfma_f32_16x16x32_bf16 v[126:129], v[188:191], v[212:215], v[126:129]
	v_mfma_f32_16x16x32_bf16 v[110:113], v[180:183], v[220:223], v[110:113]
	v_mfma_f32_16x16x32_bf16 v[106:109], v[188:191], v[220:223], v[106:109]
	v_mfma_f32_16x16x32_bf16 v[94:97], v[180:183], v[228:231], v[94:97]
	v_mfma_f32_16x16x32_bf16 v[90:93], v[188:191], v[228:231], v[90:93]
	v_mfma_f32_16x16x32_bf16 v[78:81], v[180:183], v[236:239], v[78:81]
	v_mfma_f32_16x16x32_bf16 v[74:77], v[188:191], v[236:239], v[74:77]
	v_mfma_f32_16x16x32_bf16 v[122:125], v[184:187], v[216:219], v[122:125]
	v_mfma_f32_16x16x32_bf16 v[126:129], v[192:195], v[216:219], v[126:129]
	v_mfma_f32_16x16x32_bf16 v[110:113], v[184:187], v[224:227], v[110:113]
	v_mfma_f32_16x16x32_bf16 v[106:109], v[192:195], v[224:227], v[106:109]
	v_mfma_f32_16x16x32_bf16 v[94:97], v[184:187], v[232:235], v[94:97]
	v_mfma_f32_16x16x32_bf16 v[90:93], v[192:195], v[232:235], v[90:93]
	v_mfma_f32_16x16x32_bf16 v[78:81], v[184:187], v[240:243], v[78:81]
	v_mfma_f32_16x16x32_bf16 v[74:77], v[192:195], v[240:243], v[74:77]
	v_mfma_f32_16x16x32_bf16 v[118:121], v[196:199], v[212:215], v[118:121]
	v_mfma_f32_16x16x32_bf16 v[114:117], v[204:207], v[212:215], v[114:117]
	v_mfma_f32_16x16x32_bf16 v[102:105], v[196:199], v[220:223], v[102:105]
	v_mfma_f32_16x16x32_bf16 v[98:101], v[204:207], v[220:223], v[98:101]
	v_mfma_f32_16x16x32_bf16 v[86:89], v[196:199], v[228:231], v[86:89]
	v_mfma_f32_16x16x32_bf16 v[82:85], v[204:207], v[228:231], v[82:85]
	v_mfma_f32_16x16x32_bf16 v[70:73], v[196:199], v[236:239], v[70:73]
	v_mfma_f32_16x16x32_bf16 v[66:69], v[204:207], v[236:239], v[66:69]
	v_mfma_f32_16x16x32_bf16 v[118:121], v[200:203], v[216:219], v[118:121]
	v_mfma_f32_16x16x32_bf16 v[114:117], v[208:211], v[216:219], v[114:117]
	v_mfma_f32_16x16x32_bf16 v[102:105], v[200:203], v[224:227], v[102:105]
	v_mfma_f32_16x16x32_bf16 v[98:101], v[208:211], v[224:227], v[98:101]
	v_mfma_f32_16x16x32_bf16 v[86:89], v[200:203], v[232:235], v[86:89]
	v_mfma_f32_16x16x32_bf16 v[82:85], v[208:211], v[232:235], v[82:85]
	v_mfma_f32_16x16x32_bf16 v[70:73], v[200:203], v[240:243], v[70:73]
	v_mfma_f32_16x16x32_bf16 v[66:69], v[208:211], v[240:243], v[66:69]
	s_barrier
	s_add_i32 s68, s68, s24
	v_lshl_add_u64 v[138:139], s[66:67], 0, v[152:153]
	s_mov_b32 m0, s68
	ds_read_b128 v[212:215], v164 offset:16384
	ds_read_b128 v[216:219], v164 offset:17408
	ds_read_b128 v[220:223], v164 offset:18432
	ds_read_b128 v[224:227], v164 offset:19456
	ds_read_b128 v[228:231], v164 offset:20480
	ds_read_b128 v[232:235], v164 offset:21504
	ds_read_b128 v[236:239], v164 offset:22528
	ds_read_b128 v[240:243], v164 offset:23552
	global_load_lds_dwordx4 v[138:139], off
	s_add_i32 m0, s68, 0x2000
	v_lshl_add_u64 v[166:167], s[66:67], 0, v[148:149]
	s_add_u32 s66, s66, s10
	s_addc_u32 s67, s67, s11
	s_add_i32 s65, s65, s24
	global_load_lds_dwordx4 v[166:167], off
	v_lshl_add_u64 v[178:179], s[66:67], 0, v[152:153]
	s_mov_b32 m0, s65
	v_lshl_add_u64 v[244:245], s[66:67], 0, v[148:149]
	global_load_lds_dwordx4 v[178:179], off
	s_add_i32 m0, s65, 0x2000
	v_lshl_add_u64 v[246:247], s[22:23], 0, v[154:155]
	global_load_lds_dwordx4 v[244:245], off
	s_mov_b32 m0, s25
	v_lshl_add_u64 v[248:249], s[22:23], 0, v[150:151]
	global_load_lds_dwordx4 v[246:247], off
	s_mov_b32 m0, s42
	s_nop 0
	global_load_lds_dwordx4 v[248:249], off
	s_waitcnt vmcnt(8)
	s_waitcnt lgkmcnt(0)
	s_barrier
; #define PG8_STAGE(bufoff, gbase, voff) do { _Pragma("unroll") for (int _i = 0; _i < 2; ++_i) \
;         __builtin_amdgcn_global_load_lds((const unsigned*)((const char*)(gbase) + (voff)[_i]), (LAS unsigned*)(lds + (bufoff) + ldsw + _i * 8192), 16, 0, 0); } while (0)
; #define PG8_LDA(dst, b, h) do { _Pragma("unroll") for (int m = 0; m < 4; ++m) _Pragma("unroll") for (int k = 0; k < 2; ++k) dst[m][k] = *(const LAS bf16x8*)(lds + PG8_SA(b, h) + aoff + m * 2048 + k * 1024); } while (0)
; #define PG8_LDB(dst, b, h) do { _Pragma("unroll") for (int n = 0; n < 2; ++n) _Pragma("unroll") for (int k = 0; k < 2; ++k) dst[n][k] = *(const LAS bf16x8*)(lds + PG8_SB(b, h) + boff + n * 2048 + k * 1024); } while (0)
; #define PG8_MMA(ai, bj, At, Bt) do { __builtin_amdgcn_s_setprio(1); _Pragma("unroll") for (int m = 0; m < 4; ++m) _Pragma("unroll") for (int n = 0; n < 2; ++n) _Pragma("unroll") for (int k = 0; k < 2; ++k) \
;         acc[ai][bj][m][n] = __builtin_amdgcn_mfma_f32_16x16x32_bf16(Bt[n][k], At[m][k], acc[ai][bj][m][n], 0, 0, 0); __builtin_amdgcn_s_setprio(0); } while (0)
; #define PG8_WAIT_V(n) asm volatile("s_waitcnt vmcnt(" #n ")" ::: "memory")
; #define PG8_WAIT_L(n) asm volatile("s_waitcnt lgkmcnt(" #n ")" ::: "memory")
; #define PG8_BAR __builtin_amdgcn_s_barrier()
; #define PG8_SCHED __builtin_amdgcn_sched_barrier(0)
; template <class Epi, class Sched, bool HALFN = false>
; __device__ __forceinline__ void gemm_phase(LAS unsigned char* lds, const Gemm g, const Sched& S, const Epi& E) {
;     ...
;             PG8_WAIT_V(8); PG8_WAIT_L(0); PG8_BAR; PG8_MMA(1, 0, At, B0); PG8_MMA(1, 1, At, B1); PG8_BAR; PG8_SCHED;
;             PG8_LDB(B0, 1, 0); PG8_LDB(B1, 1, 1); PG8_SCHED; PG8_LDA(At, 1, 0); PG8_STAGE(PG8_SA(0, 1), a2 + hstep, voffA);
;             PG8_WAIT_V(8); PG8_WAIT_L(0); PG8_BAR; PG8_MMA(0, 0, At, B0); PG8_MMA(0, 1, At, B1); PG8_BAR; PG8_SCHED;
	s_waitcnt lgkmcnt(0)
	v_mfma_f32_16x16x32_bf16 v[62:65], v[180:183], v[212:215], v[62:65]
	v_mfma_f32_16x16x32_bf16 v[58:61], v[188:191], v[212:215], v[58:61]
	v_mfma_f32_16x16x32_bf16 v[46:49], v[180:183], v[220:223], v[46:49]
	v_mfma_f32_16x16x32_bf16 v[42:45], v[188:191], v[220:223], v[42:45]
	v_mfma_f32_16x16x32_bf16 v[30:33], v[180:183], v[228:231], v[30:33]
	v_mfma_f32_16x16x32_bf16 v[26:29], v[188:191], v[228:231], v[26:29]
	v_mfma_f32_16x16x32_bf16 v[14:17], v[180:183], v[236:239], v[14:17]
	v_mfma_f32_16x16x32_bf16 v[10:13], v[188:191], v[236:239], v[10:13]
	v_mfma_f32_16x16x32_bf16 v[62:65], v[184:187], v[216:219], v[62:65]
	v_mfma_f32_16x16x32_bf16 v[58:61], v[192:195], v[216:219], v[58:61]
	v_mfma_f32_16x16x32_bf16 v[46:49], v[184:187], v[224:227], v[46:49]
	v_mfma_f32_16x16x32_bf16 v[42:45], v[192:195], v[224:227], v[42:45]
	v_mfma_f32_16x16x32_bf16 v[30:33], v[184:187], v[232:235], v[30:33]
	v_mfma_f32_16x16x32_bf16 v[26:29], v[192:195], v[232:235], v[26:29]
	v_mfma_f32_16x16x32_bf16 v[14:17], v[184:187], v[240:243], v[14:17]
	v_mfma_f32_16x16x32_bf16 v[10:13], v[192:195], v[240:243], v[10:13]
	v_mfma_f32_16x16x32_bf16 v[54:57], v[196:199], v[212:215], v[54:57]
	v_mfma_f32_16x16x32_bf16 v[50:53], v[204:207], v[212:215], v[50:53]
	v_mfma_f32_16x16x32_bf16 v[38:41], v[196:199], v[220:223], v[38:41]
	v_mfma_f32_16x16x32_bf16 v[34:37], v[204:207], v[220:223], v[34:37]
	v_mfma_f32_16x16x32_bf16 v[22:25], v[196:199], v[228:231], v[22:25]
	v_mfma_f32_16x16x32_bf16 v[18:21], v[204:207], v[228:231], v[18:21]
	v_mfma_f32_16x16x32_bf16 v[6:9], v[196:199], v[236:239], v[6:9]
	v_mfma_f32_16x16x32_bf16 v[2:5], v[204:207], v[236:239], v[2:5]
	v_mfma_f32_16x16x32_bf16 v[54:57], v[200:203], v[216:219], v[54:57]
	v_mfma_f32_16x16x32_bf16 v[50:53], v[208:211], v[216:219], v[50:53]
	v_mfma_f32_16x16x32_bf16 v[38:41], v[200:203], v[224:227], v[38:41]
	v_mfma_f32_16x16x32_bf16 v[34:37], v[208:211], v[224:227], v[34:37]
	v_mfma_f32_16x16x32_bf16 v[22:25], v[200:203], v[232:235], v[22:25]
	v_mfma_f32_16x16x32_bf16 v[18:21], v[208:211], v[232:235], v[18:21]
	v_mfma_f32_16x16x32_bf16 v[6:9], v[200:203], v[240:243], v[6:9]
	v_mfma_f32_16x16x32_bf16 v[2:5], v[208:211], v[240:243], v[2:5]
	s_barrier
	s_add_i32 s65, 0, 0x18000
	v_add_u32_e32 v0, s65, v161
	s_add_i32 s66, 0, 0x1c000
	ds_read_b128 v[180:183], v0
	ds_read_b128 v[184:187], v0 offset:1024
	ds_read_b128 v[188:191], v0 offset:2048
	ds_read_b128 v[192:195], v0 offset:3072
	v_add_u32_e32 v0, s66, v161
	ds_read_b128 v[196:199], v0
	ds_read_b128 v[200:203], v0 offset:1024
	ds_read_b128 v[204:207], v0 offset:2048
	ds_read_b128 v[208:211], v0 offset:3072
	s_add_u32 s22, s22, s10
	s_addc_u32 s23, s23, s11
	s_mov_b32 m0, s43
	v_lshl_add_u64 v[250:251], s[22:23], 0, v[154:155]
	ds_read_b128 v[212:215], v164 offset:32768
	ds_read_b128 v[216:219], v164 offset:33792
	ds_read_b128 v[220:223], v164 offset:34816
	ds_read_b128 v[224:227], v164 offset:35840
	ds_read_b128 v[228:231], v164 offset:36864
	ds_read_b128 v[232:235], v164 offset:37888
	ds_read_b128 v[236:239], v164 offset:38912
	ds_read_b128 v[240:243], v164 offset:39936
	global_load_lds_dwordx4 v[250:251], off
	v_lshl_add_u64 v[250:251], s[22:23], 0, v[150:151]
	s_mov_b32 m0, s44
	s_nop 0
	global_load_lds_dwordx4 v[250:251], off
	s_waitcnt vmcnt(8)
	s_waitcnt lgkmcnt(0)
	s_barrier
	s_waitcnt lgkmcnt(0)
	v_mfma_f32_16x16x32_bf16 v[122:125], v[180:183], v[212:215], v[122:125]
	v_mfma_f32_16x16x32_bf16 v[126:129], v[188:191], v[212:215], v[126:129]
	v_mfma_f32_16x16x32_bf16 v[110:113], v[180:183], v[220:223], v[110:113]
	v_mfma_f32_16x16x32_bf16 v[106:109], v[188:191], v[220:223], v[106:109]
	v_mfma_f32_16x16x32_bf16 v[94:97], v[180:183], v[228:231], v[94:97]
	v_mfma_f32_16x16x32_bf16 v[90:93], v[188:191], v[228:231], v[90:93]
	v_mfma_f32_16x16x32_bf16 v[78:81], v[180:183], v[236:239], v[78:81]
	v_mfma_f32_16x16x32_bf16 v[74:77], v[188:191], v[236:239], v[74:77]
	v_mfma_f32_16x16x32_bf16 v[122:125], v[184:187], v[216:219], v[122:125]
	v_mfma_f32_16x16x32_bf16 v[126:129], v[192:195], v[216:219], v[126:129]
	v_mfma_f32_16x16x32_bf16 v[110:113], v[184:187], v[224:227], v[110:113]
	v_mfma_f32_16x16x32_bf16 v[106:109], v[192:195], v[224:227], v[106:109]
	v_mfma_f32_16x16x32_bf16 v[94:97], v[184:187], v[232:235], v[94:97]
	v_mfma_f32_16x16x32_bf16 v[90:93], v[192:195], v[232:235], v[90:93]
	v_mfma_f32_16x16x32_bf16 v[78:81], v[184:187], v[240:243], v[78:81]
	v_mfma_f32_16x16x32_bf16 v[74:77], v[192:195], v[240:243], v[74:77]
	v_mfma_f32_16x16x32_bf16 v[118:121], v[196:199], v[212:215], v[118:121]
	v_mfma_f32_16x16x32_bf16 v[114:117], v[204:207], v[212:215], v[114:117]
	v_mfma_f32_16x16x32_bf16 v[102:105], v[196:199], v[220:223], v[102:105]
	v_mfma_f32_16x16x32_bf16 v[98:101], v[204:207], v[220:223], v[98:101]
	v_mfma_f32_16x16x32_bf16 v[86:89], v[196:199], v[228:231], v[86:89]
	v_mfma_f32_16x16x32_bf16 v[82:85], v[204:207], v[228:231], v[82:85]
	v_mfma_f32_16x16x32_bf16 v[70:73], v[196:199], v[236:239], v[70:73]
	v_mfma_f32_16x16x32_bf16 v[66:69], v[204:207], v[236:239], v[66:69]
	v_mfma_f32_16x16x32_bf16 v[118:121], v[200:203], v[216:219], v[118:121]
	v_mfma_f32_16x16x32_bf16 v[114:117], v[208:211], v[216:219], v[114:117]
	v_mfma_f32_16x16x32_bf16 v[102:105], v[200:203], v[224:227], v[102:105]
	v_mfma_f32_16x16x32_bf16 v[98:101], v[208:211], v[224:227], v[98:101]
	v_mfma_f32_16x16x32_bf16 v[86:89], v[200:203], v[232:235], v[86:89]
	v_mfma_f32_16x16x32_bf16 v[82:85], v[208:211], v[232:235], v[82:85]
	v_mfma_f32_16x16x32_bf16 v[70:73], v[200:203], v[240:243], v[70:73]
	v_mfma_f32_16x16x32_bf16 v[66:69], v[208:211], v[240:243], v[66:69]
	s_barrier
; #define PG8_STAGE(bufoff, gbase, voff) do { _Pragma("unroll") for (int _i = 0; _i < 2; ++_i) \
;         __builtin_amdgcn_global_load_lds((const unsigned*)((const char*)(gbase) + (voff)[_i]), (LAS unsigned*)(lds + (bufoff) + ldsw + _i * 8192), 16, 0, 0); } while (0)
; #define PG8_LDA(dst, b, h) do { _Pragma("unroll") for (int m = 0; m < 4; ++m) _Pragma("unroll") for (int k = 0; k < 2; ++k) dst[m][k] = *(const LAS bf16x8*)(lds + PG8_SA(b, h) + aoff + m * 2048 + k * 1024); } while (0)
; #define PG8_MMA(ai, bj, At, Bt) do { __builtin_amdgcn_s_setprio(1); _Pragma("unroll") for (int m = 0; m < 4; ++m) _Pragma("unroll") for (int n = 0; n < 2; ++n) _Pragma("unroll") for (int k = 0; k < 2; ++k) \
;         acc[ai][bj][m][n] = __builtin_amdgcn_mfma_f32_16x16x32_bf16(Bt[n][k], At[m][k], acc[ai][bj][m][n], 0, 0, 0); __builtin_amdgcn_s_setprio(0); } while (0)
; #define PG8_WAIT_V(n) asm volatile("s_waitcnt vmcnt(" #n ")" ::: "memory")
; #define PG8_WAIT_L(n) asm volatile("s_waitcnt lgkmcnt(" #n ")" ::: "memory")
; #define PG8_BAR __builtin_amdgcn_s_barrier()
; #define PG8_SCHED __builtin_amdgcn_sched_barrier(0)
; template <class Epi, class Sched, bool HALFN = false>
; __device__ __forceinline__ void gemm_phase(LAS unsigned char* lds, const Gemm g, const Sched& S, const Epi& E) {
;     ...
;             PG8_LDA(At, 1, 1); PG8_STAGE(PG8_SB(1, 0), b3, voffB); PG8_STAGE(PG8_SB(1, 1), b3 + hstep, voffB); PG8_STAGE(PG8_SA(1, 0), a3, voffA);
;             PG8_WAIT_V(8); PG8_WAIT_L(0); PG8_BAR; PG8_MMA(1, 0, At, B0); PG8_MMA(1, 1, At, B1); PG8_BAR; PG8_SCHED;
;             }
;         }
	s_add_i32 s22, s65, s24
	v_lshl_add_u64 v[138:139], v[138:139], 0, s[26:27]
	s_mov_b32 m0, s22
	ds_read_b128 v[212:215], v164 offset:49152
	ds_read_b128 v[216:219], v164 offset:50176
	ds_read_b128 v[220:223], v164 offset:51200
	ds_read_b128 v[224:227], v164 offset:52224
	ds_read_b128 v[228:231], v164 offset:53248
	ds_read_b128 v[232:235], v164 offset:54272
	ds_read_b128 v[236:239], v164 offset:55296
	ds_read_b128 v[240:243], v164 offset:56320
	global_load_lds_dwordx4 v[138:139], off
	v_lshl_add_u64 v[138:139], v[166:167], 0, s[26:27]
	s_add_i32 m0, s22, 0x2000
	s_add_i32 s22, s66, s24
	global_load_lds_dwordx4 v[138:139], off
	v_lshl_add_u64 v[138:139], v[178:179], 0, s[26:27]
	s_mov_b32 m0, s22
	s_nop 0
	global_load_lds_dwordx4 v[138:139], off
	v_lshl_add_u64 v[138:139], v[244:245], 0, s[26:27]
	s_add_i32 m0, s22, 0x2000
	s_nop 0
	global_load_lds_dwordx4 v[138:139], off
	v_lshl_add_u64 v[138:139], v[246:247], 0, s[26:27]
	s_mov_b32 m0, s45
	s_nop 0
	global_load_lds_dwordx4 v[138:139], off
	v_lshl_add_u64 v[138:139], v[248:249], 0, s[26:27]
	s_mov_b32 m0, s54
	s_nop 0
	global_load_lds_dwordx4 v[138:139], off
	s_waitcnt vmcnt(8)
	s_waitcnt lgkmcnt(0)
	s_barrier
	s_waitcnt lgkmcnt(0)
	v_mfma_f32_16x16x32_bf16 v[62:65], v[180:183], v[212:215], v[62:65]
	v_mfma_f32_16x16x32_bf16 v[58:61], v[188:191], v[212:215], v[58:61]
	v_mfma_f32_16x16x32_bf16 v[46:49], v[180:183], v[220:223], v[46:49]
	v_mfma_f32_16x16x32_bf16 v[42:45], v[188:191], v[220:223], v[42:45]
	v_mfma_f32_16x16x32_bf16 v[30:33], v[180:183], v[228:231], v[30:33]
	v_mfma_f32_16x16x32_bf16 v[26:29], v[188:191], v[228:231], v[26:29]
	v_mfma_f32_16x16x32_bf16 v[14:17], v[180:183], v[236:239], v[14:17]
	v_mfma_f32_16x16x32_bf16 v[10:13], v[188:191], v[236:239], v[10:13]
	v_mfma_f32_16x16x32_bf16 v[62:65], v[184:187], v[216:219], v[62:65]
	v_mfma_f32_16x16x32_bf16 v[58:61], v[192:195], v[216:219], v[58:61]
	v_mfma_f32_16x16x32_bf16 v[46:49], v[184:187], v[224:227], v[46:49]
	v_mfma_f32_16x16x32_bf16 v[42:45], v[192:195], v[224:227], v[42:45]
	v_mfma_f32_16x16x32_bf16 v[30:33], v[184:187], v[232:235], v[30:33]
	v_mfma_f32_16x16x32_bf16 v[26:29], v[192:195], v[232:235], v[26:29]
	v_mfma_f32_16x16x32_bf16 v[14:17], v[184:187], v[240:243], v[14:17]
	v_mfma_f32_16x16x32_bf16 v[10:13], v[192:195], v[240:243], v[10:13]
	v_mfma_f32_16x16x32_bf16 v[54:57], v[196:199], v[212:215], v[54:57]
	v_mfma_f32_16x16x32_bf16 v[50:53], v[204:207], v[212:215], v[50:53]
	v_mfma_f32_16x16x32_bf16 v[38:41], v[196:199], v[220:223], v[38:41]
	v_mfma_f32_16x16x32_bf16 v[34:37], v[204:207], v[220:223], v[34:37]
	v_mfma_f32_16x16x32_bf16 v[22:25], v[196:199], v[228:231], v[22:25]
	v_mfma_f32_16x16x32_bf16 v[18:21], v[204:207], v[228:231], v[18:21]
	v_mfma_f32_16x16x32_bf16 v[6:9], v[196:199], v[236:239], v[6:9]
	v_mfma_f32_16x16x32_bf16 v[2:5], v[204:207], v[236:239], v[2:5]
	v_mfma_f32_16x16x32_bf16 v[54:57], v[200:203], v[216:219], v[54:57]
	v_mfma_f32_16x16x32_bf16 v[50:53], v[208:211], v[216:219], v[50:53]
	v_mfma_f32_16x16x32_bf16 v[38:41], v[200:203], v[224:227], v[38:41]
	v_mfma_f32_16x16x32_bf16 v[34:37], v[208:211], v[224:227], v[34:37]
	v_mfma_f32_16x16x32_bf16 v[22:25], v[200:203], v[232:235], v[22:25]
	v_mfma_f32_16x16x32_bf16 v[18:21], v[208:211], v[232:235], v[18:21]
	v_mfma_f32_16x16x32_bf16 v[6:9], v[200:203], v[240:243], v[6:9]
	v_mfma_f32_16x16x32_bf16 v[2:5], v[208:211], v[240:243], v[2:5]
	s_barrier
	s_add_u32 s62, s62, 0x100
	s_addc_u32 s63, s63, 0
	s_add_u32 s20, s20, 0x100
	s_addc_u32 s21, s21, 0
	s_cmp_ge_i32 s64, s55
	s_mov_b32 s22, s64
	s_cbranch_scc0 .LBB0_557
	s_movk_i32 s67, 0x1600
	v_readlane_b32 s68, v254, 38

; #define PG8_STAGE(bufoff, gbase, voff) do { _Pragma("unroll") for (int _i = 0; _i < 2; ++_i) \
;         __builtin_amdgcn_global_load_lds((const unsigned*)((const char*)(gbase) + (voff)[_i]), (LAS unsigned*)(lds + (bufoff) + ldsw + _i * 8192), 16, 0, 0); } while (0)
; #define PG8_LDA(dst, b, h) do { _Pragma("unroll") for (int m = 0; m < 4; ++m) _Pragma("unroll") for (int k = 0; k < 2; ++k) dst[m][k] = *(const LAS bf16x8*)(lds + PG8_SA(b, h) + aoff + m * 2048 + k * 1024); } while (0)
; template <class Epi, class Sched, bool HALFN = false>
; __device__ __forceinline__ void gemm_phase(LAS unsigned char* lds, const Gemm g, const Sched& S, const Epi& E) {
;     ...
;         for (int t = 0; t < nt; t += 2) {
;             const bool last = (t == nt - 2);
;             const char* a1 = cA + (size_t)(t + 1) * kstep;
;             const char* a2 = last ? nA : cA + (size_t)(t + 2) * kstep; const char* b2 = last ? nB : cB + (size_t)(t + 2) * kstep;
;             const char* a3 = a2 + kstep; const char* b3 = b2 + kstep;
;             if constexpr (HALFN) {
;             PG8_LDB(B0, 0, 0); PG8_SCHED; PG8_LDA(At, 0, 0); PG8_STAGE(PG8_SA(1, 1), a1 + hstep, voffA);
;             PG8_WAIT_V(6); PG8_WAIT_L(0); PG8_BAR; PG8_MMA(0, 0, At, B0); PG8_BAR; PG8_SCHED;
;             PG8_LDA(At, 0, 1); PG8_STAGE(PG8_SB(0, 0), b2, voffB); PG8_STAGE(PG8_SA(0, 0), a2, voffA);
;             PG8_WAIT_V(6); PG8_WAIT_L(0); PG8_BAR; PG8_MMA(1, 0, At, B0); PG8_BAR; PG8_SCHED;
;             PG8_LDB(B0, 1, 0); PG8_SCHED; PG8_LDA(At, 1, 0); PG8_STAGE(PG8_SA(0, 1), a2 + hstep, voffA);
;             PG8_WAIT_V(6); PG8_WAIT_L(0); PG8_BAR; PG8_MMA(0, 0, At, B0); PG8_BAR; PG8_SCHED;
;             PG8_LDA(At, 1, 1); PG8_STAGE(PG8_SB(1, 0), b3, voffB); PG8_STAGE(PG8_SA(1, 0), a3, voffA);
;             PG8_WAIT_V(6); PG8_WAIT_L(0); PG8_BAR; PG8_MMA(1, 0, At, B0); PG8_BAR; PG8_SCHED;
;             } else {
;             PG8_LDB(B0, 0, 0); PG8_LDB(B1, 0, 1); PG8_SCHED; PG8_LDA(At, 0, 0); PG8_STAGE(PG8_SA(1, 1), a1 + hstep, voffA);
;             PG8_WAIT_V(8); PG8_WAIT_L(0); PG8_BAR; PG8_MMA(0, 0, At, B0); PG8_MMA(0, 1, At, B1); PG8_BAR; PG8_SCHED;
;             PG8_LDA(At, 0, 1); PG8_STAGE(PG8_SB(0, 0), b2, voffB); PG8_STAGE(PG8_SB(0, 1), b2 + hstep, voffB); PG8_STAGE(PG8_SA(0, 0), a2, voffA);
;             PG8_WAIT_V(8); PG8_WAIT_L(0); PG8_BAR; PG8_MMA(1, 0, At, B0); PG8_MMA(1, 1, At, B1); PG8_BAR; PG8_SCHED;
.LBB0_590:
	s_add_i32 s65, s24, 2
	s_add_u32 s66, s22, 0x80
	s_addc_u32 s25, s23, 0
	s_add_i32 s68, 0, 0x10000
	s_cmp_eq_u32 s57, s24
	s_cselect_b32 s25, s19, s25
	s_cselect_b32 s24, s18, s66
	v_add_u32_e32 v0, s68, v161
	s_cselect_b32 s67, s21, s64
	s_cselect_b32 s66, s20, s63
	s_add_i32 s69, 0, 0x14000
	ds_read_b128 v[180:183], v0
	ds_read_b128 v[184:187], v0 offset:1024
	ds_read_b128 v[188:191], v0 offset:2048
	ds_read_b128 v[192:195], v0 offset:3072
	v_add_u32_e32 v0, s69, v161
	ds_read_b128 v[196:199], v0
	ds_read_b128 v[200:203], v0 offset:1024
	ds_read_b128 v[204:207], v0 offset:2048
	ds_read_b128 v[208:211], v0 offset:3072
	v_lshl_add_u64 v[138:139], s[22:23], 0, v[158:159]
	s_add_i32 m0, s42, 0xc000
	ds_read_b128 v[212:215], v164
	ds_read_b128 v[216:219], v164 offset:1024
	ds_read_b128 v[220:223], v164 offset:2048
	ds_read_b128 v[224:227], v164 offset:3072
	ds_read_b128 v[228:231], v164 offset:4096
	ds_read_b128 v[232:235], v164 offset:5120
	ds_read_b128 v[236:239], v164 offset:6144
	ds_read_b128 v[240:243], v164 offset:7168
	global_load_lds_dwordx4 v[138:139], off
	v_lshl_add_u64 v[138:139], s[22:23], 0, v[156:157]
	s_add_i32 m0, s42, 0xe000
	s_nop 0
	global_load_lds_dwordx4 v[138:139], off
	s_waitcnt vmcnt(8)
	s_waitcnt lgkmcnt(0)
	s_barrier
	s_waitcnt lgkmcnt(0)
	v_mfma_f32_16x16x32_bf16 v[122:125], v[180:183], v[212:215], v[122:125]
	v_mfma_f32_16x16x32_bf16 v[126:129], v[188:191], v[212:215], v[126:129]
	v_mfma_f32_16x16x32_bf16 v[110:113], v[180:183], v[220:223], v[110:113]
	v_mfma_f32_16x16x32_bf16 v[106:109], v[188:191], v[220:223], v[106:109]
	v_mfma_f32_16x16x32_bf16 v[94:97], v[180:183], v[228:231], v[94:97]
	v_mfma_f32_16x16x32_bf16 v[90:93], v[188:191], v[228:231], v[90:93]
	v_mfma_f32_16x16x32_bf16 v[78:81], v[180:183], v[236:239], v[78:81]
	v_mfma_f32_16x16x32_bf16 v[74:77], v[188:191], v[236:239], v[74:77]
	v_mfma_f32_16x16x32_bf16 v[122:125], v[184:187], v[216:219], v[122:125]
	v_mfma_f32_16x16x32_bf16 v[126:129], v[192:195], v[216:219], v[126:129]
	v_mfma_f32_16x16x32_bf16 v[110:113], v[184:187], v[224:227], v[110:113]
	v_mfma_f32_16x16x32_bf16 v[106:109], v[192:195], v[224:227], v[106:109]
	v_mfma_f32_16x16x32_bf16 v[94:97], v[184:187], v[232:235], v[94:97]
	v_mfma_f32_16x16x32_bf16 v[90:93], v[192:195], v[232:235], v[90:93]
	v_mfma_f32_16x16x32_bf16 v[78:81], v[184:187], v[240:243], v[78:81]
	v_mfma_f32_16x16x32_bf16 v[74:77], v[192:195], v[240:243], v[74:77]
	v_mfma_f32_16x16x32_bf16 v[118:121], v[196:199], v[212:215], v[118:121]
	v_mfma_f32_16x16x32_bf16 v[114:117], v[204:207], v[212:215], v[114:117]
	v_mfma_f32_16x16x32_bf16 v[102:105], v[196:199], v[220:223], v[102:105]
	v_mfma_f32_16x16x32_bf16 v[98:101], v[204:207], v[220:223], v[98:101]
	v_mfma_f32_16x16x32_bf16 v[86:89], v[196:199], v[228:231], v[86:89]
	v_mfma_f32_16x16x32_bf16 v[82:85], v[204:207], v[228:231], v[82:85]
	v_mfma_f32_16x16x32_bf16 v[70:73], v[196:199], v[236:239], v[70:73]
	v_mfma_f32_16x16x32_bf16 v[66:69], v[204:207], v[236:239], v[66:69]
	v_mfma_f32_16x16x32_bf16 v[118:121], v[200:203], v[216:219], v[118:121]
	v_mfma_f32_16x16x32_bf16 v[114:117], v[208:211], v[216:219], v[114:117]
	v_mfma_f32_16x16x32_bf16 v[102:105], v[200:203], v[224:227], v[102:105]
	v_mfma_f32_16x16x32_bf16 v[98:101], v[208:211], v[224:227], v[98:101]
	v_mfma_f32_16x16x32_bf16 v[86:89], v[200:203], v[232:235], v[86:89]
	v_mfma_f32_16x16x32_bf16 v[82:85], v[208:211], v[232:235], v[82:85]
	v_mfma_f32_16x16x32_bf16 v[70:73], v[200:203], v[240:243], v[70:73]
	v_mfma_f32_16x16x32_bf16 v[66:69], v[208:211], v[240:243], v[66:69]
	s_barrier
	s_add_i32 s68, s68, s41
	v_lshl_add_u64 v[138:139], s[66:67], 0, v[150:151]
	s_mov_b32 m0, s68
	ds_read_b128 v[212:215], v164 offset:16384
	ds_read_b128 v[216:219], v164 offset:17408
	ds_read_b128 v[220:223], v164 offset:18432
	ds_read_b128 v[224:227], v164 offset:19456
	ds_read_b128 v[228:231], v164 offset:20480
	ds_read_b128 v[232:235], v164 offset:21504
	ds_read_b128 v[236:239], v164 offset:22528
	ds_read_b128 v[240:243], v164 offset:23552
	global_load_lds_dwordx4 v[138:139], off
	s_add_i32 m0, s68, 0x2000
	v_lshl_add_u64 v[166:167], s[66:67], 0, v[154:155]
	s_add_u32 s66, s66, s8
	s_addc_u32 s67, s67, s9
	s_add_i32 s68, s69, s41
	global_load_lds_dwordx4 v[166:167], off
	v_lshl_add_u64 v[244:245], s[66:67], 0, v[150:151]
	s_mov_b32 m0, s68
	v_lshl_add_u64 v[246:247], s[66:67], 0, v[154:155]
	global_load_lds_dwordx4 v[244:245], off
	s_add_i32 m0, s68, 0x2000
	v_lshl_add_u64 v[248:249], s[24:25], 0, v[148:149]
	global_load_lds_dwordx4 v[246:247], off
	s_mov_b32 m0, s42
	v_lshl_add_u64 v[250:251], s[24:25], 0, v[152:153]
	global_load_lds_dwordx4 v[248:249], off
	s_mov_b32 m0, s43
	s_nop 0
	global_load_lds_dwordx4 v[250:251], off
	s_waitcnt vmcnt(8)
	s_waitcnt lgkmcnt(0)
	s_barrier
; #define PG8_STAGE(bufoff, gbase, voff) do { _Pragma("unroll") for (int _i = 0; _i < 2; ++_i) \
;         __builtin_amdgcn_global_load_lds((const unsigned*)((const char*)(gbase) + (voff)[_i]), (LAS unsigned*)(lds + (bufoff) + ldsw + _i * 8192), 16, 0, 0); } while (0)
; #define PG8_LDA(dst, b, h) do { _Pragma("unroll") for (int m = 0; m < 4; ++m) _Pragma("unroll") for (int k = 0; k < 2; ++k) dst[m][k] = *(const LAS bf16x8*)(lds + PG8_SA(b, h) + aoff + m * 2048 + k * 1024); } while (0)
; #define PG8_LDB(dst, b, h) do { _Pragma("unroll") for (int n = 0; n < 2; ++n) _Pragma("unroll") for (int k = 0; k < 2; ++k) dst[n][k] = *(const LAS bf16x8*)(lds + PG8_SB(b, h) + boff + n * 2048 + k * 1024); } while (0)
; #define PG8_MMA(ai, bj, At, Bt) do { __builtin_amdgcn_s_setprio(1); _Pragma("unroll") for (int m = 0; m < 4; ++m) _Pragma("unroll") for (int n = 0; n < 2; ++n) _Pragma("unroll") for (int k = 0; k < 2; ++k) \
;         acc[ai][bj][m][n] = __builtin_amdgcn_mfma_f32_16x16x32_bf16(Bt[n][k], At[m][k], acc[ai][bj][m][n], 0, 0, 0); __builtin_amdgcn_s_setprio(0); } while (0)
; #define PG8_WAIT_V(n) asm volatile("s_waitcnt vmcnt(" #n ")" ::: "memory")
; #define PG8_WAIT_L(n) asm volatile("s_waitcnt lgkmcnt(" #n ")" ::: "memory")
; #define PG8_BAR __builtin_amdgcn_s_barrier()
; #define PG8_SCHED __builtin_amdgcn_sched_barrier(0)
; template <class Epi, class Sched, bool HALFN = false>
; __device__ __forceinline__ void gemm_phase(LAS unsigned char* lds, const Gemm g, const Sched& S, const Epi& E) {
;     ...
;             PG8_WAIT_V(8); PG8_WAIT_L(0); PG8_BAR; PG8_MMA(1, 0, At, B0); PG8_MMA(1, 1, At, B1); PG8_BAR; PG8_SCHED;
;             PG8_LDB(B0, 1, 0); PG8_LDB(B1, 1, 1); PG8_SCHED; PG8_LDA(At, 1, 0); PG8_STAGE(PG8_SA(0, 1), a2 + hstep, voffA);
;             PG8_WAIT_V(8); PG8_WAIT_L(0); PG8_BAR; PG8_MMA(0, 0, At, B0); PG8_MMA(0, 1, At, B1); PG8_BAR; PG8_SCHED;
	s_waitcnt lgkmcnt(0)
	v_mfma_f32_16x16x32_bf16 v[62:65], v[180:183], v[212:215], v[62:65]
	v_mfma_f32_16x16x32_bf16 v[58:61], v[188:191], v[212:215], v[58:61]
	v_mfma_f32_16x16x32_bf16 v[46:49], v[180:183], v[220:223], v[46:49]
	v_mfma_f32_16x16x32_bf16 v[42:45], v[188:191], v[220:223], v[42:45]
	v_mfma_f32_16x16x32_bf16 v[30:33], v[180:183], v[228:231], v[30:33]
	v_mfma_f32_16x16x32_bf16 v[26:29], v[188:191], v[228:231], v[26:29]
	v_mfma_f32_16x16x32_bf16 v[14:17], v[180:183], v[236:239], v[14:17]
	v_mfma_f32_16x16x32_bf16 v[10:13], v[188:191], v[236:239], v[10:13]
	v_mfma_f32_16x16x32_bf16 v[62:65], v[184:187], v[216:219], v[62:65]
	v_mfma_f32_16x16x32_bf16 v[58:61], v[192:195], v[216:219], v[58:61]
	v_mfma_f32_16x16x32_bf16 v[46:49], v[184:187], v[224:227], v[46:49]
	v_mfma_f32_16x16x32_bf16 v[42:45], v[192:195], v[224:227], v[42:45]
	v_mfma_f32_16x16x32_bf16 v[30:33], v[184:187], v[232:235], v[30:33]
	v_mfma_f32_16x16x32_bf16 v[26:29], v[192:195], v[232:235], v[26:29]
	v_mfma_f32_16x16x32_bf16 v[14:17], v[184:187], v[240:243], v[14:17]
	v_mfma_f32_16x16x32_bf16 v[10:13], v[192:195], v[240:243], v[10:13]
	v_mfma_f32_16x16x32_bf16 v[54:57], v[196:199], v[212:215], v[54:57]
	v_mfma_f32_16x16x32_bf16 v[50:53], v[204:207], v[212:215], v[50:53]
	v_mfma_f32_16x16x32_bf16 v[38:41], v[196:199], v[220:223], v[38:41]
	v_mfma_f32_16x16x32_bf16 v[34:37], v[204:207], v[220:223], v[34:37]
	v_mfma_f32_16x16x32_bf16 v[22:25], v[196:199], v[228:231], v[22:25]
	v_mfma_f32_16x16x32_bf16 v[18:21], v[204:207], v[228:231], v[18:21]
	v_mfma_f32_16x16x32_bf16 v[6:9], v[196:199], v[236:239], v[6:9]
	v_mfma_f32_16x16x32_bf16 v[2:5], v[204:207], v[236:239], v[2:5]
	v_mfma_f32_16x16x32_bf16 v[54:57], v[200:203], v[216:219], v[54:57]
	v_mfma_f32_16x16x32_bf16 v[50:53], v[208:211], v[216:219], v[50:53]
	v_mfma_f32_16x16x32_bf16 v[38:41], v[200:203], v[224:227], v[38:41]
	v_mfma_f32_16x16x32_bf16 v[34:37], v[208:211], v[224:227], v[34:37]
	v_mfma_f32_16x16x32_bf16 v[22:25], v[200:203], v[232:235], v[22:25]
	v_mfma_f32_16x16x32_bf16 v[18:21], v[208:211], v[232:235], v[18:21]
	v_mfma_f32_16x16x32_bf16 v[6:9], v[200:203], v[240:243], v[6:9]
	v_mfma_f32_16x16x32_bf16 v[2:5], v[208:211], v[240:243], v[2:5]
	s_barrier
	s_add_i32 s66, 0, 0x18000
	v_add_u32_e32 v0, s66, v161
	s_add_i32 s67, 0, 0x1c000
	ds_read_b128 v[180:183], v0
	ds_read_b128 v[184:187], v0 offset:1024
	ds_read_b128 v[188:191], v0 offset:2048
	ds_read_b128 v[192:195], v0 offset:3072
	v_add_u32_e32 v0, s67, v161
	ds_read_b128 v[196:199], v0
	ds_read_b128 v[200:203], v0 offset:1024
	ds_read_b128 v[204:207], v0 offset:2048
	ds_read_b128 v[208:211], v0 offset:3072
	s_add_u32 s24, s24, s8
	s_addc_u32 s25, s25, s9
	s_mov_b32 m0, s44
	v_lshl_add_u64 v[178:179], s[24:25], 0, v[148:149]
	ds_read_b128 v[212:215], v164 offset:32768
	ds_read_b128 v[216:219], v164 offset:33792
	ds_read_b128 v[220:223], v164 offset:34816
	ds_read_b128 v[224:227], v164 offset:35840
	ds_read_b128 v[228:231], v164 offset:36864
	ds_read_b128 v[232:235], v164 offset:37888
	ds_read_b128 v[236:239], v164 offset:38912
	ds_read_b128 v[240:243], v164 offset:39936
	global_load_lds_dwordx4 v[178:179], off
	v_lshl_add_u64 v[178:179], s[24:25], 0, v[152:153]
	s_mov_b32 m0, s45
	s_nop 0
	global_load_lds_dwordx4 v[178:179], off
	s_waitcnt vmcnt(8)
	s_waitcnt lgkmcnt(0)
	s_barrier
	s_waitcnt lgkmcnt(0)
	v_mfma_f32_16x16x32_bf16 v[122:125], v[180:183], v[212:215], v[122:125]
	v_mfma_f32_16x16x32_bf16 v[126:129], v[188:191], v[212:215], v[126:129]
	v_mfma_f32_16x16x32_bf16 v[110:113], v[180:183], v[220:223], v[110:113]
	v_mfma_f32_16x16x32_bf16 v[106:109], v[188:191], v[220:223], v[106:109]
	v_mfma_f32_16x16x32_bf16 v[94:97], v[180:183], v[228:231], v[94:97]
	v_mfma_f32_16x16x32_bf16 v[90:93], v[188:191], v[228:231], v[90:93]
	v_mfma_f32_16x16x32_bf16 v[78:81], v[180:183], v[236:239], v[78:81]
	v_mfma_f32_16x16x32_bf16 v[74:77], v[188:191], v[236:239], v[74:77]
	v_mfma_f32_16x16x32_bf16 v[122:125], v[184:187], v[216:219], v[122:125]
	v_mfma_f32_16x16x32_bf16 v[126:129], v[192:195], v[216:219], v[126:129]
	v_mfma_f32_16x16x32_bf16 v[110:113], v[184:187], v[224:227], v[110:113]
	v_mfma_f32_16x16x32_bf16 v[106:109], v[192:195], v[224:227], v[106:109]
	v_mfma_f32_16x16x32_bf16 v[94:97], v[184:187], v[232:235], v[94:97]
	v_mfma_f32_16x16x32_bf16 v[90:93], v[192:195], v[232:235], v[90:93]
	v_mfma_f32_16x16x32_bf16 v[78:81], v[184:187], v[240:243], v[78:81]
	v_mfma_f32_16x16x32_bf16 v[74:77], v[192:195], v[240:243], v[74:77]
	v_mfma_f32_16x16x32_bf16 v[118:121], v[196:199], v[212:215], v[118:121]
	v_mfma_f32_16x16x32_bf16 v[114:117], v[204:207], v[212:215], v[114:117]
	v_mfma_f32_16x16x32_bf16 v[102:105], v[196:199], v[220:223], v[102:105]
	v_mfma_f32_16x16x32_bf16 v[98:101], v[204:207], v[220:223], v[98:101]
	v_mfma_f32_16x16x32_bf16 v[86:89], v[196:199], v[228:231], v[86:89]
	v_mfma_f32_16x16x32_bf16 v[82:85], v[204:207], v[228:231], v[82:85]
	v_mfma_f32_16x16x32_bf16 v[70:73], v[196:199], v[236:239], v[70:73]
	v_mfma_f32_16x16x32_bf16 v[66:69], v[204:207], v[236:239], v[66:69]
	v_mfma_f32_16x16x32_bf16 v[118:121], v[200:203], v[216:219], v[118:121]
	v_mfma_f32_16x16x32_bf16 v[114:117], v[208:211], v[216:219], v[114:117]
	v_mfma_f32_16x16x32_bf16 v[102:105], v[200:203], v[224:227], v[102:105]
	v_mfma_f32_16x16x32_bf16 v[98:101], v[208:211], v[224:227], v[98:101]
	v_mfma_f32_16x16x32_bf16 v[86:89], v[200:203], v[232:235], v[86:89]
	v_mfma_f32_16x16x32_bf16 v[82:85], v[208:211], v[232:235], v[82:85]
	v_mfma_f32_16x16x32_bf16 v[70:73], v[200:203], v[240:243], v[70:73]
	v_mfma_f32_16x16x32_bf16 v[66:69], v[208:211], v[240:243], v[66:69]
	s_barrier
; #define PG8_STAGE(bufoff, gbase, voff) do { _Pragma("unroll") for (int _i = 0; _i < 2; ++_i) \
;         __builtin_amdgcn_global_load_lds((const unsigned*)((const char*)(gbase) + (voff)[_i]), (LAS unsigned*)(lds + (bufoff) + ldsw + _i * 8192), 16, 0, 0); } while (0)
; #define PG8_LDA(dst, b, h) do { _Pragma("unroll") for (int m = 0; m < 4; ++m) _Pragma("unroll") for (int k = 0; k < 2; ++k) dst[m][k] = *(const LAS bf16x8*)(lds + PG8_SA(b, h) + aoff + m * 2048 + k * 1024); } while (0)
; #define PG8_MMA(ai, bj, At, Bt) do { __builtin_amdgcn_s_setprio(1); _Pragma("unroll") for (int m = 0; m < 4; ++m) _Pragma("unroll") for (int n = 0; n < 2; ++n) _Pragma("unroll") for (int k = 0; k < 2; ++k) \
;         acc[ai][bj][m][n] = __builtin_amdgcn_mfma_f32_16x16x32_bf16(Bt[n][k], At[m][k], acc[ai][bj][m][n], 0, 0, 0); __builtin_amdgcn_s_setprio(0); } while (0)
; #define PG8_WAIT_V(n) asm volatile("s_waitcnt vmcnt(" #n ")" ::: "memory")
; #define PG8_WAIT_L(n) asm volatile("s_waitcnt lgkmcnt(" #n ")" ::: "memory")
; #define PG8_BAR __builtin_amdgcn_s_barrier()
; #define PG8_SCHED __builtin_amdgcn_sched_barrier(0)
; template <class Epi, class Sched, bool HALFN = false>
; __device__ __forceinline__ void gemm_phase(LAS unsigned char* lds, const Gemm g, const Sched& S, const Epi& E) {
;     ...
;             PG8_LDA(At, 1, 1); PG8_STAGE(PG8_SB(1, 0), b3, voffB); PG8_STAGE(PG8_SB(1, 1), b3 + hstep, voffB); PG8_STAGE(PG8_SA(1, 0), a3, voffA);
;             PG8_WAIT_V(8); PG8_WAIT_L(0); PG8_BAR; PG8_MMA(1, 0, At, B0); PG8_MMA(1, 1, At, B1); PG8_BAR; PG8_SCHED;
;             }
;         }
	s_add_i32 s24, s66, s41
	v_lshl_add_u64 v[138:139], v[138:139], 0, s[26:27]
	s_mov_b32 m0, s24
	ds_read_b128 v[212:215], v164 offset:49152
	ds_read_b128 v[216:219], v164 offset:50176
	ds_read_b128 v[220:223], v164 offset:51200
	ds_read_b128 v[224:227], v164 offset:52224
	ds_read_b128 v[228:231], v164 offset:53248
	ds_read_b128 v[232:235], v164 offset:54272
	ds_read_b128 v[236:239], v164 offset:55296
	ds_read_b128 v[240:243], v164 offset:56320
	global_load_lds_dwordx4 v[138:139], off
	v_lshl_add_u64 v[138:139], v[166:167], 0, s[26:27]
	s_add_i32 m0, s24, 0x2000
	s_add_i32 s24, s67, s41
	global_load_lds_dwordx4 v[138:139], off
	v_lshl_add_u64 v[138:139], v[244:245], 0, s[26:27]
	s_mov_b32 m0, s24
	s_nop 0
	global_load_lds_dwordx4 v[138:139], off
	v_lshl_add_u64 v[138:139], v[246:247], 0, s[26:27]
	s_add_i32 m0, s24, 0x2000
	s_nop 0
	global_load_lds_dwordx4 v[138:139], off
	v_lshl_add_u64 v[138:139], v[248:249], 0, s[26:27]
	s_mov_b32 m0, s54
	s_nop 0
	global_load_lds_dwordx4 v[138:139], off
	v_lshl_add_u64 v[138:139], v[250:251], 0, s[26:27]
	s_mov_b32 m0, s55
	s_nop 0
	global_load_lds_dwordx4 v[138:139], off
	s_waitcnt vmcnt(8)
	s_waitcnt lgkmcnt(0)
	s_barrier
	s_waitcnt lgkmcnt(0)
	v_mfma_f32_16x16x32_bf16 v[62:65], v[180:183], v[212:215], v[62:65]
	v_mfma_f32_16x16x32_bf16 v[58:61], v[188:191], v[212:215], v[58:61]
	v_mfma_f32_16x16x32_bf16 v[46:49], v[180:183], v[220:223], v[46:49]
	v_mfma_f32_16x16x32_bf16 v[42:45], v[188:191], v[220:223], v[42:45]
	v_mfma_f32_16x16x32_bf16 v[30:33], v[180:183], v[228:231], v[30:33]
	v_mfma_f32_16x16x32_bf16 v[26:29], v[188:191], v[228:231], v[26:29]
	v_mfma_f32_16x16x32_bf16 v[14:17], v[180:183], v[236:239], v[14:17]
	v_mfma_f32_16x16x32_bf16 v[10:13], v[188:191], v[236:239], v[10:13]
	v_mfma_f32_16x16x32_bf16 v[62:65], v[184:187], v[216:219], v[62:65]
	v_mfma_f32_16x16x32_bf16 v[58:61], v[192:195], v[216:219], v[58:61]
	v_mfma_f32_16x16x32_bf16 v[46:49], v[184:187], v[224:227], v[46:49]
	v_mfma_f32_16x16x32_bf16 v[42:45], v[192:195], v[224:227], v[42:45]
	v_mfma_f32_16x16x32_bf16 v[30:33], v[184:187], v[232:235], v[30:33]
	v_mfma_f32_16x16x32_bf16 v[26:29], v[192:195], v[232:235], v[26:29]
	v_mfma_f32_16x16x32_bf16 v[14:17], v[184:187], v[240:243], v[14:17]
	v_mfma_f32_16x16x32_bf16 v[10:13], v[192:195], v[240:243], v[10:13]
	v_mfma_f32_16x16x32_bf16 v[54:57], v[196:199], v[212:215], v[54:57]
	v_mfma_f32_16x16x32_bf16 v[50:53], v[204:207], v[212:215], v[50:53]
	v_mfma_f32_16x16x32_bf16 v[38:41], v[196:199], v[220:223], v[38:41]
	v_mfma_f32_16x16x32_bf16 v[34:37], v[204:207], v[220:223], v[34:37]
	v_mfma_f32_16x16x32_bf16 v[22:25], v[196:199], v[228:231], v[22:25]
	v_mfma_f32_16x16x32_bf16 v[18:21], v[204:207], v[228:231], v[18:21]
	v_mfma_f32_16x16x32_bf16 v[6:9], v[196:199], v[236:239], v[6:9]
	v_mfma_f32_16x16x32_bf16 v[2:5], v[204:207], v[236:239], v[2:5]
	v_mfma_f32_16x16x32_bf16 v[54:57], v[200:203], v[216:219], v[54:57]
	v_mfma_f32_16x16x32_bf16 v[50:53], v[208:211], v[216:219], v[50:53]
	v_mfma_f32_16x16x32_bf16 v[38:41], v[200:203], v[224:227], v[38:41]
	v_mfma_f32_16x16x32_bf16 v[34:37], v[208:211], v[224:227], v[34:37]
	v_mfma_f32_16x16x32_bf16 v[22:25], v[200:203], v[232:235], v[22:25]
	v_mfma_f32_16x16x32_bf16 v[18:21], v[208:211], v[232:235], v[18:21]
	v_mfma_f32_16x16x32_bf16 v[6:9], v[200:203], v[240:243], v[6:9]
	v_mfma_f32_16x16x32_bf16 v[2:5], v[208:211], v[240:243], v[2:5]
	s_barrier
	s_add_u32 s63, s63, 0x100
	s_addc_u32 s64, s64, 0
	s_add_u32 s22, s22, 0x100
	s_addc_u32 s23, s23, 0
	s_cmp_ge_i32 s65, s56
	s_mov_b32 s24, s65
	s_cbranch_scc0 .LBB0_590
	s_movk_i32 s67, 0x1600
	s_movk_i32 s69, 0x6c00
	v_readlane_b32 s68, v254, 38

; #define PG8_STAGE(bufoff, gbase, voff) do { _Pragma("unroll") for (int _i = 0; _i < 2; ++_i) \
;         __builtin_amdgcn_global_load_lds((const unsigned*)((const char*)(gbase) + (voff)[_i]), (LAS unsigned*)(lds + (bufoff) + ldsw + _i * 8192), 16, 0, 0); } while (0)
; #define PG8_LDA(dst, b, h) do { _Pragma("unroll") for (int m = 0; m < 4; ++m) _Pragma("unroll") for (int k = 0; k < 2; ++k) dst[m][k] = *(const LAS bf16x8*)(lds + PG8_SA(b, h) + aoff + m * 2048 + k * 1024); } while (0)
; template <class Epi, class Sched, bool HALFN = false>
; __device__ __forceinline__ void gemm_phase(LAS unsigned char* lds, const Gemm g, const Sched& S, const Epi& E) {
;     ...
;         for (int t = 0; t < nt; t += 2) {
;             const bool last = (t == nt - 2);
;             const char* a1 = cA + (size_t)(t + 1) * kstep;
;             const char* a2 = last ? nA : cA + (size_t)(t + 2) * kstep; const char* b2 = last ? nB : cB + (size_t)(t + 2) * kstep;
;             const char* a3 = a2 + kstep; const char* b3 = b2 + kstep;
;             if constexpr (HALFN) {
;             PG8_LDB(B0, 0, 0); PG8_SCHED; PG8_LDA(At, 0, 0); PG8_STAGE(PG8_SA(1, 1), a1 + hstep, voffA);
;             PG8_WAIT_V(6); PG8_WAIT_L(0); PG8_BAR; PG8_MMA(0, 0, At, B0); PG8_BAR; PG8_SCHED;
;             PG8_LDA(At, 0, 1); PG8_STAGE(PG8_SB(0, 0), b2, voffB); PG8_STAGE(PG8_SA(0, 0), a2, voffA);
;             PG8_WAIT_V(6); PG8_WAIT_L(0); PG8_BAR; PG8_MMA(1, 0, At, B0); PG8_BAR; PG8_SCHED;
;             PG8_LDB(B0, 1, 0); PG8_SCHED; PG8_LDA(At, 1, 0); PG8_STAGE(PG8_SA(0, 1), a2 + hstep, voffA);
;             PG8_WAIT_V(6); PG8_WAIT_L(0); PG8_BAR; PG8_MMA(0, 0, At, B0); PG8_BAR; PG8_SCHED;
;             PG8_LDA(At, 1, 1); PG8_STAGE(PG8_SB(1, 0), b3, voffB); PG8_STAGE(PG8_SA(1, 0), a3, voffA);
;             PG8_WAIT_V(6); PG8_WAIT_L(0); PG8_BAR; PG8_MMA(1, 0, At, B0); PG8_BAR; PG8_SCHED;
;             } else {
;             PG8_LDB(B0, 0, 0); PG8_LDB(B1, 0, 1); PG8_SCHED; PG8_LDA(At, 0, 0); PG8_STAGE(PG8_SA(1, 1), a1 + hstep, voffA);
;             PG8_WAIT_V(8); PG8_WAIT_L(0); PG8_BAR; PG8_MMA(0, 0, At, B0); PG8_MMA(0, 1, At, B1); PG8_BAR; PG8_SCHED;
;             PG8_LDA(At, 0, 1); PG8_STAGE(PG8_SB(0, 0), b2, voffB); PG8_STAGE(PG8_SB(0, 1), b2 + hstep, voffB); PG8_STAGE(PG8_SA(0, 0), a2, voffA);
;             PG8_WAIT_V(8); PG8_WAIT_L(0); PG8_BAR; PG8_MMA(1, 0, At, B0); PG8_MMA(1, 1, At, B1); PG8_BAR; PG8_SCHED;
.LBB0_630:
	s_add_i32 s62, s20, 2
	s_add_u32 s63, s18, 0x80
	s_addc_u32 s21, s19, 0
	s_add_i32 s66, 0, 0x10000
	s_cmp_eq_u32 s45, s20
	s_cselect_b32 s21, s5, s21
	s_cselect_b32 s20, s4, s63
	v_add_u32_e32 v138, s66, v167
	s_cselect_b32 s65, s17, s61
	s_cselect_b32 s64, s16, s60
	s_add_i32 s63, 0, 0x14000
	ds_read_b128 v[154:157], v138
	ds_read_b128 v[158:161], v138 offset:1024
	ds_read_b128 v[162:165], v138 offset:2048
	ds_read_b128 v[182:185], v138 offset:3072
	v_add_u32_e32 v138, s63, v167
	ds_read_b128 v[186:189], v138
	ds_read_b128 v[190:193], v138 offset:1024
	ds_read_b128 v[194:197], v138 offset:2048
	ds_read_b128 v[198:201], v138 offset:3072
	v_lshl_add_u64 v[234:235], s[18:19], 0, v[152:153]
	s_add_i32 m0, s34, 0xc000
	ds_read_b128 v[202:205], v180
	ds_read_b128 v[206:209], v180 offset:1024
	ds_read_b128 v[210:213], v180 offset:2048
	ds_read_b128 v[214:217], v180 offset:3072
	ds_read_b128 v[218:221], v180 offset:4096
	ds_read_b128 v[222:225], v180 offset:5120
	ds_read_b128 v[226:229], v180 offset:6144
	ds_read_b128 v[230:233], v180 offset:7168
	global_load_lds_dwordx4 v[234:235], off
	v_lshl_add_u64 v[234:235], s[18:19], 0, v[150:151]
	s_add_i32 m0, s34, 0xe000
	s_nop 0
	global_load_lds_dwordx4 v[234:235], off
	s_waitcnt vmcnt(8)
	s_waitcnt lgkmcnt(0)
	s_barrier
	s_waitcnt lgkmcnt(0)
	v_mfma_f32_16x16x32_bf16 v[126:129], v[154:157], v[202:205], v[126:129]
	v_mfma_f32_16x16x32_bf16 v[122:125], v[162:165], v[202:205], v[122:125]
	v_mfma_f32_16x16x32_bf16 v[118:121], v[154:157], v[210:213], v[118:121]
	v_mfma_f32_16x16x32_bf16 v[114:117], v[162:165], v[210:213], v[114:117]
	v_mfma_f32_16x16x32_bf16 v[106:109], v[154:157], v[218:221], v[106:109]
	v_mfma_f32_16x16x32_bf16 v[98:101], v[162:165], v[218:221], v[98:101]
	v_mfma_f32_16x16x32_bf16 v[90:93], v[154:157], v[226:229], v[90:93]
	v_mfma_f32_16x16x32_bf16 v[82:85], v[162:165], v[226:229], v[82:85]
	v_mfma_f32_16x16x32_bf16 v[126:129], v[158:161], v[206:209], v[126:129]
	v_mfma_f32_16x16x32_bf16 v[122:125], v[182:185], v[206:209], v[122:125]
	v_mfma_f32_16x16x32_bf16 v[118:121], v[158:161], v[214:217], v[118:121]
	v_mfma_f32_16x16x32_bf16 v[114:117], v[182:185], v[214:217], v[114:117]
	v_mfma_f32_16x16x32_bf16 v[106:109], v[158:161], v[222:225], v[106:109]
	v_mfma_f32_16x16x32_bf16 v[98:101], v[182:185], v[222:225], v[98:101]
	v_mfma_f32_16x16x32_bf16 v[90:93], v[158:161], v[230:233], v[90:93]
	v_mfma_f32_16x16x32_bf16 v[82:85], v[182:185], v[230:233], v[82:85]
	v_mfma_f32_16x16x32_bf16 v[110:113], v[186:189], v[202:205], v[110:113]
	v_mfma_f32_16x16x32_bf16 v[102:105], v[194:197], v[202:205], v[102:105]
	v_mfma_f32_16x16x32_bf16 v[94:97], v[186:189], v[210:213], v[94:97]
	v_mfma_f32_16x16x32_bf16 v[86:89], v[194:197], v[210:213], v[86:89]
	v_mfma_f32_16x16x32_bf16 v[78:81], v[186:189], v[218:221], v[78:81]
	v_mfma_f32_16x16x32_bf16 v[74:77], v[194:197], v[218:221], v[74:77]
	v_mfma_f32_16x16x32_bf16 v[70:73], v[186:189], v[226:229], v[70:73]
	v_mfma_f32_16x16x32_bf16 v[66:69], v[194:197], v[226:229], v[66:69]
	v_mfma_f32_16x16x32_bf16 v[110:113], v[190:193], v[206:209], v[110:113]
	v_mfma_f32_16x16x32_bf16 v[102:105], v[198:201], v[206:209], v[102:105]
	v_mfma_f32_16x16x32_bf16 v[94:97], v[190:193], v[214:217], v[94:97]
	v_mfma_f32_16x16x32_bf16 v[86:89], v[198:201], v[214:217], v[86:89]
	v_mfma_f32_16x16x32_bf16 v[78:81], v[190:193], v[222:225], v[78:81]
	v_mfma_f32_16x16x32_bf16 v[74:77], v[198:201], v[222:225], v[74:77]
	v_mfma_f32_16x16x32_bf16 v[70:73], v[190:193], v[230:233], v[70:73]
	v_mfma_f32_16x16x32_bf16 v[66:69], v[198:201], v[230:233], v[66:69]
	s_barrier
	s_add_i32 s66, s66, s25
	v_lshl_add_u64 v[234:235], s[64:65], 0, v[0:1]
	s_mov_b32 m0, s66
	ds_read_b128 v[202:205], v180 offset:16384
	ds_read_b128 v[206:209], v180 offset:17408
	ds_read_b128 v[210:213], v180 offset:18432
	ds_read_b128 v[214:217], v180 offset:19456
	ds_read_b128 v[218:221], v180 offset:20480
	ds_read_b128 v[222:225], v180 offset:21504
	ds_read_b128 v[226:229], v180 offset:22528
	ds_read_b128 v[230:233], v180 offset:23552
	global_load_lds_dwordx4 v[234:235], off
	s_add_i32 m0, s66, 0x2000
	v_lshl_add_u64 v[236:237], s[64:65], 0, v[148:149]
	s_add_u32 s64, s64, s6
	s_addc_u32 s65, s65, s7
	s_add_i32 s63, s63, s25
	global_load_lds_dwordx4 v[236:237], off
	v_lshl_add_u64 v[238:239], s[64:65], 0, v[0:1]
	s_mov_b32 m0, s63
	v_lshl_add_u64 v[240:241], s[64:65], 0, v[148:149]
	global_load_lds_dwordx4 v[238:239], off
	s_add_i32 m0, s63, 0x2000
	v_lshl_add_u64 v[242:243], s[20:21], 0, v[0:1]
	global_load_lds_dwordx4 v[240:241], off
	s_mov_b32 m0, s34
	v_lshl_add_u64 v[244:245], s[20:21], 0, v[148:149]
	global_load_lds_dwordx4 v[242:243], off
	s_mov_b32 m0, s35
	s_nop 0
	global_load_lds_dwordx4 v[244:245], off
	s_waitcnt vmcnt(8)
	s_waitcnt lgkmcnt(0)
	s_barrier
; #define PG8_STAGE(bufoff, gbase, voff) do { _Pragma("unroll") for (int _i = 0; _i < 2; ++_i) \
;         __builtin_amdgcn_global_load_lds((const unsigned*)((const char*)(gbase) + (voff)[_i]), (LAS unsigned*)(lds + (bufoff) + ldsw + _i * 8192), 16, 0, 0); } while (0)
; #define PG8_LDA(dst, b, h) do { _Pragma("unroll") for (int m = 0; m < 4; ++m) _Pragma("unroll") for (int k = 0; k < 2; ++k) dst[m][k] = *(const LAS bf16x8*)(lds + PG8_SA(b, h) + aoff + m * 2048 + k * 1024); } while (0)
; #define PG8_LDB(dst, b, h) do { _Pragma("unroll") for (int n = 0; n < 2; ++n) _Pragma("unroll") for (int k = 0; k < 2; ++k) dst[n][k] = *(const LAS bf16x8*)(lds + PG8_SB(b, h) + boff + n * 2048 + k * 1024); } while (0)
; #define PG8_MMA(ai, bj, At, Bt) do { __builtin_amdgcn_s_setprio(1); _Pragma("unroll") for (int m = 0; m < 4; ++m) _Pragma("unroll") for (int n = 0; n < 2; ++n) _Pragma("unroll") for (int k = 0; k < 2; ++k) \
;         acc[ai][bj][m][n] = __builtin_amdgcn_mfma_f32_16x16x32_bf16(Bt[n][k], At[m][k], acc[ai][bj][m][n], 0, 0, 0); __builtin_amdgcn_s_setprio(0); } while (0)
; #define PG8_WAIT_V(n) asm volatile("s_waitcnt vmcnt(" #n ")" ::: "memory")
; #define PG8_WAIT_L(n) asm volatile("s_waitcnt lgkmcnt(" #n ")" ::: "memory")
; #define PG8_BAR __builtin_amdgcn_s_barrier()
; #define PG8_SCHED __builtin_amdgcn_sched_barrier(0)
; template <class Epi, class Sched, bool HALFN = false>
; __device__ __forceinline__ void gemm_phase(LAS unsigned char* lds, const Gemm g, const Sched& S, const Epi& E) {
;     ...
;             PG8_WAIT_V(8); PG8_WAIT_L(0); PG8_BAR; PG8_MMA(1, 0, At, B0); PG8_MMA(1, 1, At, B1); PG8_BAR; PG8_SCHED;
;             PG8_LDB(B0, 1, 0); PG8_LDB(B1, 1, 1); PG8_SCHED; PG8_LDA(At, 1, 0); PG8_STAGE(PG8_SA(0, 1), a2 + hstep, voffA);
;             PG8_WAIT_V(8); PG8_WAIT_L(0); PG8_BAR; PG8_MMA(0, 0, At, B0); PG8_MMA(0, 1, At, B1); PG8_BAR; PG8_SCHED;
	s_waitcnt lgkmcnt(0)
	v_mfma_f32_16x16x32_bf16 v[62:65], v[154:157], v[202:205], v[62:65]
	v_mfma_f32_16x16x32_bf16 v[58:61], v[162:165], v[202:205], v[58:61]
	v_mfma_f32_16x16x32_bf16 v[54:57], v[154:157], v[210:213], v[54:57]
	v_mfma_f32_16x16x32_bf16 v[50:53], v[162:165], v[210:213], v[50:53]
	v_mfma_f32_16x16x32_bf16 v[42:45], v[154:157], v[218:221], v[42:45]
	v_mfma_f32_16x16x32_bf16 v[34:37], v[162:165], v[218:221], v[34:37]
	v_mfma_f32_16x16x32_bf16 v[26:29], v[154:157], v[226:229], v[26:29]
	v_mfma_f32_16x16x32_bf16 v[18:21], v[162:165], v[226:229], v[18:21]
	v_mfma_f32_16x16x32_bf16 v[62:65], v[158:161], v[206:209], v[62:65]
	v_mfma_f32_16x16x32_bf16 v[58:61], v[182:185], v[206:209], v[58:61]
	v_mfma_f32_16x16x32_bf16 v[54:57], v[158:161], v[214:217], v[54:57]
	v_mfma_f32_16x16x32_bf16 v[50:53], v[182:185], v[214:217], v[50:53]
	v_mfma_f32_16x16x32_bf16 v[42:45], v[158:161], v[222:225], v[42:45]
	v_mfma_f32_16x16x32_bf16 v[34:37], v[182:185], v[222:225], v[34:37]
	v_mfma_f32_16x16x32_bf16 v[26:29], v[158:161], v[230:233], v[26:29]
	v_mfma_f32_16x16x32_bf16 v[18:21], v[182:185], v[230:233], v[18:21]
	v_mfma_f32_16x16x32_bf16 v[46:49], v[186:189], v[202:205], v[46:49]
	v_mfma_f32_16x16x32_bf16 v[38:41], v[194:197], v[202:205], v[38:41]
	v_mfma_f32_16x16x32_bf16 v[30:33], v[186:189], v[210:213], v[30:33]
	v_mfma_f32_16x16x32_bf16 v[22:25], v[194:197], v[210:213], v[22:25]
	v_mfma_f32_16x16x32_bf16 v[14:17], v[186:189], v[218:221], v[14:17]
	v_mfma_f32_16x16x32_bf16 v[10:13], v[194:197], v[218:221], v[10:13]
	v_mfma_f32_16x16x32_bf16 v[6:9], v[186:189], v[226:229], v[6:9]
	v_mfma_f32_16x16x32_bf16 v[2:5], v[194:197], v[226:229], v[2:5]
	v_mfma_f32_16x16x32_bf16 v[46:49], v[190:193], v[206:209], v[46:49]
	v_mfma_f32_16x16x32_bf16 v[38:41], v[198:201], v[206:209], v[38:41]
	v_mfma_f32_16x16x32_bf16 v[30:33], v[190:193], v[214:217], v[30:33]
	v_mfma_f32_16x16x32_bf16 v[22:25], v[198:201], v[214:217], v[22:25]
	v_mfma_f32_16x16x32_bf16 v[14:17], v[190:193], v[222:225], v[14:17]
	v_mfma_f32_16x16x32_bf16 v[10:13], v[198:201], v[222:225], v[10:13]
	v_mfma_f32_16x16x32_bf16 v[6:9], v[190:193], v[230:233], v[6:9]
	v_mfma_f32_16x16x32_bf16 v[2:5], v[198:201], v[230:233], v[2:5]
	s_barrier
	s_add_i32 s63, 0, 0x18000
	v_add_u32_e32 v138, s63, v167
	s_add_i32 s64, 0, 0x1c000
	ds_read_b128 v[154:157], v138
	ds_read_b128 v[158:161], v138 offset:1024
	ds_read_b128 v[162:165], v138 offset:2048
	ds_read_b128 v[182:185], v138 offset:3072
	v_add_u32_e32 v138, s64, v167
	ds_read_b128 v[186:189], v138
	ds_read_b128 v[190:193], v138 offset:1024
	ds_read_b128 v[194:197], v138 offset:2048
	ds_read_b128 v[198:201], v138 offset:3072
	s_add_u32 s20, s20, s6
	s_addc_u32 s21, s21, s7
	s_mov_b32 m0, s40
	v_lshl_add_u64 v[246:247], s[20:21], 0, v[0:1]
	ds_read_b128 v[202:205], v180 offset:32768
	ds_read_b128 v[206:209], v180 offset:33792
	ds_read_b128 v[210:213], v180 offset:34816
	ds_read_b128 v[214:217], v180 offset:35840
	ds_read_b128 v[218:221], v180 offset:36864
	ds_read_b128 v[222:225], v180 offset:37888
	ds_read_b128 v[226:229], v180 offset:38912
	ds_read_b128 v[230:233], v180 offset:39936
	global_load_lds_dwordx4 v[246:247], off
	v_lshl_add_u64 v[246:247], s[20:21], 0, v[148:149]
	s_mov_b32 m0, s41
	s_nop 0
	global_load_lds_dwordx4 v[246:247], off
	s_waitcnt vmcnt(8)
	s_waitcnt lgkmcnt(0)
	s_barrier
	s_waitcnt lgkmcnt(0)
	v_mfma_f32_16x16x32_bf16 v[126:129], v[154:157], v[202:205], v[126:129]
	v_mfma_f32_16x16x32_bf16 v[122:125], v[162:165], v[202:205], v[122:125]
	v_mfma_f32_16x16x32_bf16 v[118:121], v[154:157], v[210:213], v[118:121]
	v_mfma_f32_16x16x32_bf16 v[114:117], v[162:165], v[210:213], v[114:117]
	v_mfma_f32_16x16x32_bf16 v[106:109], v[154:157], v[218:221], v[106:109]
	v_mfma_f32_16x16x32_bf16 v[98:101], v[162:165], v[218:221], v[98:101]
	v_mfma_f32_16x16x32_bf16 v[90:93], v[154:157], v[226:229], v[90:93]
	v_mfma_f32_16x16x32_bf16 v[82:85], v[162:165], v[226:229], v[82:85]
	v_mfma_f32_16x16x32_bf16 v[126:129], v[158:161], v[206:209], v[126:129]
	v_mfma_f32_16x16x32_bf16 v[122:125], v[182:185], v[206:209], v[122:125]
	v_mfma_f32_16x16x32_bf16 v[118:121], v[158:161], v[214:217], v[118:121]
	v_mfma_f32_16x16x32_bf16 v[114:117], v[182:185], v[214:217], v[114:117]
	v_mfma_f32_16x16x32_bf16 v[106:109], v[158:161], v[222:225], v[106:109]
	v_mfma_f32_16x16x32_bf16 v[98:101], v[182:185], v[222:225], v[98:101]
	v_mfma_f32_16x16x32_bf16 v[90:93], v[158:161], v[230:233], v[90:93]
	v_mfma_f32_16x16x32_bf16 v[82:85], v[182:185], v[230:233], v[82:85]
	v_mfma_f32_16x16x32_bf16 v[110:113], v[186:189], v[202:205], v[110:113]
	v_mfma_f32_16x16x32_bf16 v[102:105], v[194:197], v[202:205], v[102:105]
	v_mfma_f32_16x16x32_bf16 v[94:97], v[186:189], v[210:213], v[94:97]
	v_mfma_f32_16x16x32_bf16 v[86:89], v[194:197], v[210:213], v[86:89]
	v_mfma_f32_16x16x32_bf16 v[78:81], v[186:189], v[218:221], v[78:81]
	v_mfma_f32_16x16x32_bf16 v[74:77], v[194:197], v[218:221], v[74:77]
	v_mfma_f32_16x16x32_bf16 v[70:73], v[186:189], v[226:229], v[70:73]
	v_mfma_f32_16x16x32_bf16 v[66:69], v[194:197], v[226:229], v[66:69]
	v_mfma_f32_16x16x32_bf16 v[110:113], v[190:193], v[206:209], v[110:113]
	v_mfma_f32_16x16x32_bf16 v[102:105], v[198:201], v[206:209], v[102:105]
	v_mfma_f32_16x16x32_bf16 v[94:97], v[190:193], v[214:217], v[94:97]
	v_mfma_f32_16x16x32_bf16 v[86:89], v[198:201], v[214:217], v[86:89]
	v_mfma_f32_16x16x32_bf16 v[78:81], v[190:193], v[222:225], v[78:81]
	v_mfma_f32_16x16x32_bf16 v[74:77], v[198:201], v[222:225], v[74:77]
	v_mfma_f32_16x16x32_bf16 v[70:73], v[190:193], v[230:233], v[70:73]
	v_mfma_f32_16x16x32_bf16 v[66:69], v[198:201], v[230:233], v[66:69]
	s_barrier
; #define PG8_STAGE(bufoff, gbase, voff) do { _Pragma("unroll") for (int _i = 0; _i < 2; ++_i) \
;         __builtin_amdgcn_global_load_lds((const unsigned*)((const char*)(gbase) + (voff)[_i]), (LAS unsigned*)(lds + (bufoff) + ldsw + _i * 8192), 16, 0, 0); } while (0)
; #define PG8_LDA(dst, b, h) do { _Pragma("unroll") for (int m = 0; m < 4; ++m) _Pragma("unroll") for (int k = 0; k < 2; ++k) dst[m][k] = *(const LAS bf16x8*)(lds + PG8_SA(b, h) + aoff + m * 2048 + k * 1024); } while (0)
; #define PG8_MMA(ai, bj, At, Bt) do { __builtin_amdgcn_s_setprio(1); _Pragma("unroll") for (int m = 0; m < 4; ++m) _Pragma("unroll") for (int n = 0; n < 2; ++n) _Pragma("unroll") for (int k = 0; k < 2; ++k) \
;         acc[ai][bj][m][n] = __builtin_amdgcn_mfma_f32_16x16x32_bf16(Bt[n][k], At[m][k], acc[ai][bj][m][n], 0, 0, 0); __builtin_amdgcn_s_setprio(0); } while (0)
; #define PG8_WAIT_V(n) asm volatile("s_waitcnt vmcnt(" #n ")" ::: "memory")
; #define PG8_WAIT_L(n) asm volatile("s_waitcnt lgkmcnt(" #n ")" ::: "memory")
; #define PG8_BAR __builtin_amdgcn_s_barrier()
; #define PG8_SCHED __builtin_amdgcn_sched_barrier(0)
; template <class Epi, class Sched, bool HALFN = false>
; __device__ __forceinline__ void gemm_phase(LAS unsigned char* lds, const Gemm g, const Sched& S, const Epi& E) {
;     ...
;             PG8_LDA(At, 1, 1); PG8_STAGE(PG8_SB(1, 0), b3, voffB); PG8_STAGE(PG8_SB(1, 1), b3 + hstep, voffB); PG8_STAGE(PG8_SA(1, 0), a3, voffA);
;             PG8_WAIT_V(8); PG8_WAIT_L(0); PG8_BAR; PG8_MMA(1, 0, At, B0); PG8_MMA(1, 1, At, B1); PG8_BAR; PG8_SCHED;
;             }
;         }
	s_add_i32 s20, s63, s25
	v_lshl_add_u64 v[234:235], v[234:235], 0, s[26:27]
	s_mov_b32 m0, s20
	ds_read_b128 v[202:205], v180 offset:49152
	ds_read_b128 v[206:209], v180 offset:50176
	ds_read_b128 v[210:213], v180 offset:51200
	ds_read_b128 v[214:217], v180 offset:52224
	ds_read_b128 v[218:221], v180 offset:53248
	ds_read_b128 v[222:225], v180 offset:54272
	ds_read_b128 v[226:229], v180 offset:55296
	ds_read_b128 v[230:233], v180 offset:56320
	global_load_lds_dwordx4 v[234:235], off
	v_lshl_add_u64 v[234:235], v[236:237], 0, s[26:27]
	s_add_i32 m0, s20, 0x2000
	s_add_i32 s20, s64, s25
	global_load_lds_dwordx4 v[234:235], off
	v_lshl_add_u64 v[234:235], v[238:239], 0, s[26:27]
	s_mov_b32 m0, s20
	s_nop 0
	global_load_lds_dwordx4 v[234:235], off
	v_lshl_add_u64 v[234:235], v[240:241], 0, s[26:27]
	s_add_i32 m0, s20, 0x2000
	s_nop 0
	global_load_lds_dwordx4 v[234:235], off
	v_lshl_add_u64 v[234:235], v[242:243], 0, s[26:27]
	s_mov_b32 m0, s43
	s_nop 0
	global_load_lds_dwordx4 v[234:235], off
	v_lshl_add_u64 v[234:235], v[244:245], 0, s[26:27]
	s_mov_b32 m0, s44
	s_nop 0
	global_load_lds_dwordx4 v[234:235], off
	s_waitcnt vmcnt(8)
	s_waitcnt lgkmcnt(0)
	s_barrier
	s_waitcnt lgkmcnt(0)
	v_mfma_f32_16x16x32_bf16 v[62:65], v[154:157], v[202:205], v[62:65]
	v_mfma_f32_16x16x32_bf16 v[58:61], v[162:165], v[202:205], v[58:61]
	v_mfma_f32_16x16x32_bf16 v[54:57], v[154:157], v[210:213], v[54:57]
	v_mfma_f32_16x16x32_bf16 v[50:53], v[162:165], v[210:213], v[50:53]
	v_mfma_f32_16x16x32_bf16 v[42:45], v[154:157], v[218:221], v[42:45]
	v_mfma_f32_16x16x32_bf16 v[34:37], v[162:165], v[218:221], v[34:37]
	v_mfma_f32_16x16x32_bf16 v[26:29], v[154:157], v[226:229], v[26:29]
	v_mfma_f32_16x16x32_bf16 v[18:21], v[162:165], v[226:229], v[18:21]
	v_mfma_f32_16x16x32_bf16 v[62:65], v[158:161], v[206:209], v[62:65]
	v_mfma_f32_16x16x32_bf16 v[58:61], v[182:185], v[206:209], v[58:61]
	v_mfma_f32_16x16x32_bf16 v[54:57], v[158:161], v[214:217], v[54:57]
	v_mfma_f32_16x16x32_bf16 v[50:53], v[182:185], v[214:217], v[50:53]
	v_mfma_f32_16x16x32_bf16 v[42:45], v[158:161], v[222:225], v[42:45]
	v_mfma_f32_16x16x32_bf16 v[34:37], v[182:185], v[222:225], v[34:37]
	v_mfma_f32_16x16x32_bf16 v[26:29], v[158:161], v[230:233], v[26:29]
	v_mfma_f32_16x16x32_bf16 v[18:21], v[182:185], v[230:233], v[18:21]
	v_mfma_f32_16x16x32_bf16 v[46:49], v[186:189], v[202:205], v[46:49]
	v_mfma_f32_16x16x32_bf16 v[38:41], v[194:197], v[202:205], v[38:41]
	v_mfma_f32_16x16x32_bf16 v[30:33], v[186:189], v[210:213], v[30:33]
	v_mfma_f32_16x16x32_bf16 v[22:25], v[194:197], v[210:213], v[22:25]
	v_mfma_f32_16x16x32_bf16 v[14:17], v[186:189], v[218:221], v[14:17]
	v_mfma_f32_16x16x32_bf16 v[10:13], v[194:197], v[218:221], v[10:13]
	v_mfma_f32_16x16x32_bf16 v[6:9], v[186:189], v[226:229], v[6:9]
	v_mfma_f32_16x16x32_bf16 v[2:5], v[194:197], v[226:229], v[2:5]
	v_mfma_f32_16x16x32_bf16 v[46:49], v[190:193], v[206:209], v[46:49]
	v_mfma_f32_16x16x32_bf16 v[38:41], v[198:201], v[206:209], v[38:41]
	v_mfma_f32_16x16x32_bf16 v[30:33], v[190:193], v[214:217], v[30:33]
	v_mfma_f32_16x16x32_bf16 v[22:25], v[198:201], v[214:217], v[22:25]
	v_mfma_f32_16x16x32_bf16 v[14:17], v[190:193], v[222:225], v[14:17]
	v_mfma_f32_16x16x32_bf16 v[10:13], v[198:201], v[222:225], v[10:13]
	v_mfma_f32_16x16x32_bf16 v[6:9], v[190:193], v[230:233], v[6:9]
	v_mfma_f32_16x16x32_bf16 v[2:5], v[198:201], v[230:233], v[2:5]
	s_barrier
	s_add_u32 s60, s60, 0x100
	s_addc_u32 s61, s61, 0
	s_add_u32 s18, s18, 0x100
	s_addc_u32 s19, s19, 0
	s_cmp_ge_i32 s62, s42
	s_mov_b32 s20, s62
	s_cbranch_scc0 .LBB0_630
;     __device__ __forceinline__ void operator()(AccT acc, const Unit& u, int wr, int wc, int fr, int fq) const {
;     ...
;             for (int m = 0; m < 4; ++m) { const size_t off = (size_t)(row0 + ai * HALF + m * 16) * D_ + col0;
; #pragma unroll
;                 for (int bj = 0; bj < 2; ++bj)
; #pragma unroll
;                     for (int n = 0; n < 2; ++n) { const f32x4 bs = *(const f32x4*)(xin + off + bj * HALF + n * 16); *(f32x4*)(xout + off + bj * HALF + n * 16) = bs + acc[ai][bj][m][n] * scale; }
	v_pk_mul_f32 v[162:163], v[128:129], 0.5 op_sel_hi:[1,0]
	v_pk_mul_f32 v[164:165], v[126:127], 0.5 op_sel_hi:[1,0]
	v_pk_mul_f32 v[128:129], v[124:125], 0.5 op_sel_hi:[1,0]
	v_pk_mul_f32 v[126:127], v[122:123], 0.5 op_sel_hi:[1,0]
	v_pk_mul_f32 v[160:161], v[112:113], 0.5 op_sel_hi:[1,0]
	v_pk_mul_f32 v[158:159], v[110:111], 0.5 op_sel_hi:[1,0]
	v_pk_mul_f32 v[154:155], v[104:105], 0.5 op_sel_hi:[1,0]
	v_pk_mul_f32 v[156:157], v[102:103], 0.5 op_sel_hi:[1,0]
	v_pk_mul_f32 v[122:123], v[120:121], 0.5 op_sel_hi:[1,0]
	v_pk_mul_f32 v[124:125], v[118:119], 0.5 op_sel_hi:[1,0]
	v_pk_mul_f32 v[112:113], v[116:117], 0.5 op_sel_hi:[1,0]
	v_pk_mul_f32 v[110:111], v[114:115], 0.5 op_sel_hi:[1,0]
	v_pk_mul_f32 v[120:121], v[96:97], 0.5 op_sel_hi:[1,0]
	v_pk_mul_f32 v[118:119], v[94:95], 0.5 op_sel_hi:[1,0]
	v_pk_mul_f32 v[114:115], v[88:89], 0.5 op_sel_hi:[1,0]
	v_pk_mul_f32 v[116:117], v[86:87], 0.5 op_sel_hi:[1,0]
	v_pk_mul_f32 v[108:109], v[108:109], 0.5 op_sel_hi:[1,0]
	v_pk_mul_f32 v[106:107], v[106:107], 0.5 op_sel_hi:[1,0]
	v_pk_mul_f32 v[96:97], v[100:101], 0.5 op_sel_hi:[1,0]
	v_pk_mul_f32 v[94:95], v[98:99], 0.5 op_sel_hi:[1,0]
	v_pk_mul_f32 v[104:105], v[80:81], 0.5 op_sel_hi:[1,0]
	v_pk_mul_f32 v[102:103], v[78:79], 0.5 op_sel_hi:[1,0]
	v_pk_mul_f32 v[98:99], v[76:77], 0.5 op_sel_hi:[1,0]
	v_pk_mul_f32 v[100:101], v[74:75], 0.5 op_sel_hi:[1,0]
	v_pk_mul_f32 v[92:93], v[92:93], 0.5 op_sel_hi:[1,0]
	v_pk_mul_f32 v[90:91], v[90:91], 0.5 op_sel_hi:[1,0]
	v_pk_mul_f32 v[80:81], v[84:85], 0.5 op_sel_hi:[1,0]
	v_pk_mul_f32 v[78:79], v[82:83], 0.5 op_sel_hi:[1,0]
	v_pk_mul_f32 v[88:89], v[72:73], 0.5 op_sel_hi:[1,0]
	v_pk_mul_f32 v[86:87], v[70:71], 0.5 op_sel_hi:[1,0]
	v_pk_mul_f32 v[82:83], v[68:69], 0.5 op_sel_hi:[1,0]
	v_pk_mul_f32 v[84:85], v[66:67], 0.5 op_sel_hi:[1,0]
	v_pk_mul_f32 v[74:75], v[64:65], 0.5 op_sel_hi:[1,0]
	v_pk_mul_f32 v[76:77], v[62:63], 0.5 op_sel_hi:[1,0]
	v_pk_mul_f32 v[64:65], v[60:61], 0.5 op_sel_hi:[1,0]
	v_pk_mul_f32 v[62:63], v[58:59], 0.5 op_sel_hi:[1,0]
	v_pk_mul_f32 v[72:73], v[48:49], 0.5 op_sel_hi:[1,0]
	v_pk_mul_f32 v[70:71], v[46:47], 0.5 op_sel_hi:[1,0]
	v_pk_mul_f32 v[66:67], v[40:41], 0.5 op_sel_hi:[1,0]
	v_pk_mul_f32 v[68:69], v[38:39], 0.5 op_sel_hi:[1,0]
	v_pk_mul_f32 v[58:59], v[56:57], 0.5 op_sel_hi:[1,0]
	v_pk_mul_f32 v[60:61], v[54:55], 0.5 op_sel_hi:[1,0]
	v_pk_mul_f32 v[48:49], v[52:53], 0.5 op_sel_hi:[1,0]
	v_pk_mul_f32 v[46:47], v[50:51], 0.5 op_sel_hi:[1,0]
	v_pk_mul_f32 v[56:57], v[32:33], 0.5 op_sel_hi:[1,0]
	v_pk_mul_f32 v[54:55], v[30:31], 0.5 op_sel_hi:[1,0]
	v_pk_mul_f32 v[50:51], v[24:25], 0.5 op_sel_hi:[1,0]
	v_pk_mul_f32 v[52:53], v[22:23], 0.5 op_sel_hi:[1,0]
	v_pk_mul_f32 v[38:39], v[44:45], 0.5 op_sel_hi:[1,0]
	v_pk_mul_f32 v[40:41], v[42:43], 0.5 op_sel_hi:[1,0]
	v_pk_mul_f32 v[24:25], v[36:37], 0.5 op_sel_hi:[1,0]
	v_pk_mul_f32 v[22:23], v[34:35], 0.5 op_sel_hi:[1,0]
	v_pk_mul_f32 v[36:37], v[16:17], 0.5 op_sel_hi:[1,0]
	v_pk_mul_f32 v[34:35], v[14:15], 0.5 op_sel_hi:[1,0]
	v_pk_mul_f32 v[30:31], v[12:13], 0.5 op_sel_hi:[1,0]
	v_pk_mul_f32 v[32:33], v[10:11], 0.5 op_sel_hi:[1,0]
	v_pk_mul_f32 v[14:15], v[28:29], 0.5 op_sel_hi:[1,0]
	v_pk_mul_f32 v[16:17], v[26:27], 0.5 op_sel_hi:[1,0]
	v_pk_mul_f32 v[12:13], v[20:21], 0.5 op_sel_hi:[1,0]
	v_pk_mul_f32 v[10:11], v[18:19], 0.5 op_sel_hi:[1,0]
	v_pk_mul_f32 v[8:9], v[8:9], 0.5 op_sel_hi:[1,0]
	v_pk_mul_f32 v[6:7], v[6:7], 0.5 op_sel_hi:[1,0]
	v_pk_mul_f32 v[4:5], v[4:5], 0.5 op_sel_hi:[1,0]
	v_pk_mul_f32 v[2:3], v[2:3], 0.5 op_sel_hi:[1,0]

; #define PG8_STAGE(bufoff, gbase, voff) do { _Pragma("unroll") for (int _i = 0; _i < 2; ++_i) \
;         __builtin_amdgcn_global_load_lds((const unsigned*)((const char*)(gbase) + (voff)[_i]), (LAS unsigned*)(lds + (bufoff) + ldsw + _i * 8192), 16, 0, 0); } while (0)
; #define PG8_LDA(dst, b, h) do { _Pragma("unroll") for (int m = 0; m < 4; ++m) _Pragma("unroll") for (int k = 0; k < 2; ++k) dst[m][k] = *(const LAS bf16x8*)(lds + PG8_SA(b, h) + aoff + m * 2048 + k * 1024); } while (0)
; template <class Epi, class Sched, bool HALFN = false>
; __device__ __forceinline__ void gemm_phase(LAS unsigned char* lds, const Gemm g, const Sched& S, const Epi& E) {
;     ...
;         for (int t = 0; t < nt; t += 2) {
;             const bool last = (t == nt - 2);
;             const char* a1 = cA + (size_t)(t + 1) * kstep;
;             const char* a2 = last ? nA : cA + (size_t)(t + 2) * kstep; const char* b2 = last ? nB : cB + (size_t)(t + 2) * kstep;
;             const char* a3 = a2 + kstep; const char* b3 = b2 + kstep;
;             if constexpr (HALFN) {
;             PG8_LDB(B0, 0, 0); PG8_SCHED; PG8_LDA(At, 0, 0); PG8_STAGE(PG8_SA(1, 1), a1 + hstep, voffA);
;             PG8_WAIT_V(6); PG8_WAIT_L(0); PG8_BAR; PG8_MMA(0, 0, At, B0); PG8_BAR; PG8_SCHED;
;             PG8_LDA(At, 0, 1); PG8_STAGE(PG8_SB(0, 0), b2, voffB); PG8_STAGE(PG8_SA(0, 0), a2, voffA);
;             PG8_WAIT_V(6); PG8_WAIT_L(0); PG8_BAR; PG8_MMA(1, 0, At, B0); PG8_BAR; PG8_SCHED;
;             PG8_LDB(B0, 1, 0); PG8_SCHED; PG8_LDA(At, 1, 0); PG8_STAGE(PG8_SA(0, 1), a2 + hstep, voffA);
;             PG8_WAIT_V(6); PG8_WAIT_L(0); PG8_BAR; PG8_MMA(0, 0, At, B0); PG8_BAR; PG8_SCHED;
;             PG8_LDA(At, 1, 1); PG8_STAGE(PG8_SB(1, 0), b3, voffB); PG8_STAGE(PG8_SA(1, 0), a3, voffA);
;             PG8_WAIT_V(6); PG8_WAIT_L(0); PG8_BAR; PG8_MMA(1, 0, At, B0); PG8_BAR; PG8_SCHED;
;             } else {
;             PG8_LDB(B0, 0, 0); PG8_LDB(B1, 0, 1); PG8_SCHED; PG8_LDA(At, 0, 0); PG8_STAGE(PG8_SA(1, 1), a1 + hstep, voffA);
;             PG8_WAIT_V(8); PG8_WAIT_L(0); PG8_BAR; PG8_MMA(0, 0, At, B0); PG8_MMA(0, 1, At, B1); PG8_BAR; PG8_SCHED;
;             PG8_LDA(At, 0, 1); PG8_STAGE(PG8_SB(0, 0), b2, voffB); PG8_STAGE(PG8_SB(0, 1), b2 + hstep, voffB); PG8_STAGE(PG8_SA(0, 0), a2, voffA);
;             PG8_WAIT_V(8); PG8_WAIT_L(0); PG8_BAR; PG8_MMA(1, 0, At, B0); PG8_MMA(1, 1, At, B1); PG8_BAR; PG8_SCHED;
.LBB0_654:
	s_add_i32 s62, s20, 2
	s_add_u32 s63, s18, 0x80
	s_addc_u32 s21, s19, 0
	s_add_i32 s66, 0, 0x10000
	s_cmp_eq_u32 s54, s20
	s_cselect_b32 s21, s5, s21
	s_cselect_b32 s20, s4, s63
	v_add_u32_e32 v138, s66, v161
	s_cselect_b32 s65, s17, s61
	s_cselect_b32 s64, s16, s60
	s_add_i32 s63, 0, 0x14000
	ds_read_b128 v[164:167], v138
	ds_read_b128 v[180:183], v138 offset:1024
	ds_read_b128 v[184:187], v138 offset:2048
	ds_read_b128 v[188:191], v138 offset:3072
	v_add_u32_e32 v138, s63, v161
	ds_read_b128 v[192:195], v138
	ds_read_b128 v[196:199], v138 offset:1024
	ds_read_b128 v[200:203], v138 offset:2048
	ds_read_b128 v[204:207], v138 offset:3072
	v_lshl_add_u64 v[158:159], s[18:19], 0, v[156:157]
	s_add_i32 m0, s34, 0xc000
	ds_read_b128 v[208:211], v163
	ds_read_b128 v[212:215], v163 offset:1024
	ds_read_b128 v[216:219], v163 offset:2048
	ds_read_b128 v[220:223], v163 offset:3072
	ds_read_b128 v[224:227], v163 offset:4096
	ds_read_b128 v[228:231], v163 offset:5120
	ds_read_b128 v[232:235], v163 offset:6144
	ds_read_b128 v[236:239], v163 offset:7168
	global_load_lds_dwordx4 v[158:159], off
	v_lshl_add_u64 v[158:159], s[18:19], 0, v[154:155]
	s_add_i32 m0, s34, 0xe000
	s_nop 0
	global_load_lds_dwordx4 v[158:159], off
	s_waitcnt vmcnt(8)
	s_waitcnt lgkmcnt(0)
	s_barrier
	s_waitcnt lgkmcnt(0)
	v_mfma_f32_16x16x32_bf16 v[126:129], v[164:167], v[208:211], v[126:129]
	v_mfma_f32_16x16x32_bf16 v[118:121], v[184:187], v[208:211], v[118:121]
	v_mfma_f32_16x16x32_bf16 v[110:113], v[164:167], v[216:219], v[110:113]
	v_mfma_f32_16x16x32_bf16 v[102:105], v[184:187], v[216:219], v[102:105]
	v_mfma_f32_16x16x32_bf16 v[94:97], v[164:167], v[224:227], v[94:97]
	v_mfma_f32_16x16x32_bf16 v[86:89], v[184:187], v[224:227], v[86:89]
	v_mfma_f32_16x16x32_bf16 v[78:81], v[164:167], v[232:235], v[78:81]
	v_mfma_f32_16x16x32_bf16 v[70:73], v[184:187], v[232:235], v[70:73]
	v_mfma_f32_16x16x32_bf16 v[126:129], v[180:183], v[212:215], v[126:129]
	v_mfma_f32_16x16x32_bf16 v[118:121], v[188:191], v[212:215], v[118:121]
	v_mfma_f32_16x16x32_bf16 v[110:113], v[180:183], v[220:223], v[110:113]
	v_mfma_f32_16x16x32_bf16 v[102:105], v[188:191], v[220:223], v[102:105]
	v_mfma_f32_16x16x32_bf16 v[94:97], v[180:183], v[228:231], v[94:97]
	v_mfma_f32_16x16x32_bf16 v[86:89], v[188:191], v[228:231], v[86:89]
	v_mfma_f32_16x16x32_bf16 v[78:81], v[180:183], v[236:239], v[78:81]
	v_mfma_f32_16x16x32_bf16 v[70:73], v[188:191], v[236:239], v[70:73]
	v_mfma_f32_16x16x32_bf16 v[122:125], v[192:195], v[208:211], v[122:125]
	v_mfma_f32_16x16x32_bf16 v[114:117], v[200:203], v[208:211], v[114:117]
	v_mfma_f32_16x16x32_bf16 v[106:109], v[192:195], v[216:219], v[106:109]
	v_mfma_f32_16x16x32_bf16 v[98:101], v[200:203], v[216:219], v[98:101]
	v_mfma_f32_16x16x32_bf16 v[90:93], v[192:195], v[224:227], v[90:93]
	v_mfma_f32_16x16x32_bf16 v[82:85], v[200:203], v[224:227], v[82:85]
	v_mfma_f32_16x16x32_bf16 v[74:77], v[192:195], v[232:235], v[74:77]
	v_mfma_f32_16x16x32_bf16 v[66:69], v[200:203], v[232:235], v[66:69]
	v_mfma_f32_16x16x32_bf16 v[122:125], v[196:199], v[212:215], v[122:125]
	v_mfma_f32_16x16x32_bf16 v[114:117], v[204:207], v[212:215], v[114:117]
	v_mfma_f32_16x16x32_bf16 v[106:109], v[196:199], v[220:223], v[106:109]
	v_mfma_f32_16x16x32_bf16 v[98:101], v[204:207], v[220:223], v[98:101]
	v_mfma_f32_16x16x32_bf16 v[90:93], v[196:199], v[228:231], v[90:93]
	v_mfma_f32_16x16x32_bf16 v[82:85], v[204:207], v[228:231], v[82:85]
	v_mfma_f32_16x16x32_bf16 v[74:77], v[196:199], v[236:239], v[74:77]
	v_mfma_f32_16x16x32_bf16 v[66:69], v[204:207], v[236:239], v[66:69]
	s_barrier
	s_add_i32 s66, s66, s22
	v_lshl_add_u64 v[158:159], s[64:65], 0, v[0:1]
	s_mov_b32 m0, s66
	ds_read_b128 v[208:211], v163 offset:16384
	ds_read_b128 v[212:215], v163 offset:17408
	ds_read_b128 v[216:219], v163 offset:18432
	ds_read_b128 v[220:223], v163 offset:19456
	ds_read_b128 v[224:227], v163 offset:20480
	ds_read_b128 v[228:231], v163 offset:21504
	ds_read_b128 v[232:235], v163 offset:22528
	ds_read_b128 v[236:239], v163 offset:23552
	global_load_lds_dwordx4 v[158:159], off
	s_add_i32 m0, s66, 0x2000
	v_lshl_add_u64 v[240:241], s[64:65], 0, v[148:149]
	s_add_u32 s64, s64, s6
	s_addc_u32 s65, s65, s7
	s_add_i32 s63, s63, s22
	global_load_lds_dwordx4 v[240:241], off
	v_lshl_add_u64 v[242:243], s[64:65], 0, v[0:1]
	s_mov_b32 m0, s63
	v_lshl_add_u64 v[244:245], s[64:65], 0, v[148:149]
	global_load_lds_dwordx4 v[242:243], off
	s_add_i32 m0, s63, 0x2000
	v_lshl_add_u64 v[246:247], s[20:21], 0, v[152:153]
	global_load_lds_dwordx4 v[244:245], off
	s_mov_b32 m0, s34
	v_lshl_add_u64 v[248:249], s[20:21], 0, v[150:151]
	global_load_lds_dwordx4 v[246:247], off
	s_mov_b32 m0, s35
	s_nop 0
	global_load_lds_dwordx4 v[248:249], off
	s_waitcnt vmcnt(8)
	s_waitcnt lgkmcnt(0)
	s_barrier
; #define PG8_STAGE(bufoff, gbase, voff) do { _Pragma("unroll") for (int _i = 0; _i < 2; ++_i) \
;         __builtin_amdgcn_global_load_lds((const unsigned*)((const char*)(gbase) + (voff)[_i]), (LAS unsigned*)(lds + (bufoff) + ldsw + _i * 8192), 16, 0, 0); } while (0)
; #define PG8_LDA(dst, b, h) do { _Pragma("unroll") for (int m = 0; m < 4; ++m) _Pragma("unroll") for (int k = 0; k < 2; ++k) dst[m][k] = *(const LAS bf16x8*)(lds + PG8_SA(b, h) + aoff + m * 2048 + k * 1024); } while (0)
; #define PG8_LDB(dst, b, h) do { _Pragma("unroll") for (int n = 0; n < 2; ++n) _Pragma("unroll") for (int k = 0; k < 2; ++k) dst[n][k] = *(const LAS bf16x8*)(lds + PG8_SB(b, h) + boff + n * 2048 + k * 1024); } while (0)
; #define PG8_MMA(ai, bj, At, Bt) do { __builtin_amdgcn_s_setprio(1); _Pragma("unroll") for (int m = 0; m < 4; ++m) _Pragma("unroll") for (int n = 0; n < 2; ++n) _Pragma("unroll") for (int k = 0; k < 2; ++k) \
;         acc[ai][bj][m][n] = __builtin_amdgcn_mfma_f32_16x16x32_bf16(Bt[n][k], At[m][k], acc[ai][bj][m][n], 0, 0, 0); __builtin_amdgcn_s_setprio(0); } while (0)
; #define PG8_WAIT_V(n) asm volatile("s_waitcnt vmcnt(" #n ")" ::: "memory")
; #define PG8_WAIT_L(n) asm volatile("s_waitcnt lgkmcnt(" #n ")" ::: "memory")
; #define PG8_BAR __builtin_amdgcn_s_barrier()
; #define PG8_SCHED __builtin_amdgcn_sched_barrier(0)
; template <class Epi, class Sched, bool HALFN = false>
; __device__ __forceinline__ void gemm_phase(LAS unsigned char* lds, const Gemm g, const Sched& S, const Epi& E) {
;     ...
;             PG8_WAIT_V(8); PG8_WAIT_L(0); PG8_BAR; PG8_MMA(1, 0, At, B0); PG8_MMA(1, 1, At, B1); PG8_BAR; PG8_SCHED;
;             PG8_LDB(B0, 1, 0); PG8_LDB(B1, 1, 1); PG8_SCHED; PG8_LDA(At, 1, 0); PG8_STAGE(PG8_SA(0, 1), a2 + hstep, voffA);
;             PG8_WAIT_V(8); PG8_WAIT_L(0); PG8_BAR; PG8_MMA(0, 0, At, B0); PG8_MMA(0, 1, At, B1); PG8_BAR; PG8_SCHED;
	s_waitcnt lgkmcnt(0)
	v_mfma_f32_16x16x32_bf16 v[62:65], v[164:167], v[208:211], v[62:65]
	v_mfma_f32_16x16x32_bf16 v[54:57], v[184:187], v[208:211], v[54:57]
	v_mfma_f32_16x16x32_bf16 v[46:49], v[164:167], v[216:219], v[46:49]
	v_mfma_f32_16x16x32_bf16 v[38:41], v[184:187], v[216:219], v[38:41]
	v_mfma_f32_16x16x32_bf16 v[30:33], v[164:167], v[224:227], v[30:33]
	v_mfma_f32_16x16x32_bf16 v[22:25], v[184:187], v[224:227], v[22:25]
	v_mfma_f32_16x16x32_bf16 v[14:17], v[164:167], v[232:235], v[14:17]
	v_mfma_f32_16x16x32_bf16 v[6:9], v[184:187], v[232:235], v[6:9]
	v_mfma_f32_16x16x32_bf16 v[62:65], v[180:183], v[212:215], v[62:65]
	v_mfma_f32_16x16x32_bf16 v[54:57], v[188:191], v[212:215], v[54:57]
	v_mfma_f32_16x16x32_bf16 v[46:49], v[180:183], v[220:223], v[46:49]
	v_mfma_f32_16x16x32_bf16 v[38:41], v[188:191], v[220:223], v[38:41]
	v_mfma_f32_16x16x32_bf16 v[30:33], v[180:183], v[228:231], v[30:33]
	v_mfma_f32_16x16x32_bf16 v[22:25], v[188:191], v[228:231], v[22:25]
	v_mfma_f32_16x16x32_bf16 v[14:17], v[180:183], v[236:239], v[14:17]
	v_mfma_f32_16x16x32_bf16 v[6:9], v[188:191], v[236:239], v[6:9]
	v_mfma_f32_16x16x32_bf16 v[58:61], v[192:195], v[208:211], v[58:61]
	v_mfma_f32_16x16x32_bf16 v[50:53], v[200:203], v[208:211], v[50:53]
	v_mfma_f32_16x16x32_bf16 v[42:45], v[192:195], v[216:219], v[42:45]
	v_mfma_f32_16x16x32_bf16 v[34:37], v[200:203], v[216:219], v[34:37]
	v_mfma_f32_16x16x32_bf16 v[26:29], v[192:195], v[224:227], v[26:29]
	v_mfma_f32_16x16x32_bf16 v[18:21], v[200:203], v[224:227], v[18:21]
	v_mfma_f32_16x16x32_bf16 v[10:13], v[192:195], v[232:235], v[10:13]
	v_mfma_f32_16x16x32_bf16 v[2:5], v[200:203], v[232:235], v[2:5]
	v_mfma_f32_16x16x32_bf16 v[58:61], v[196:199], v[212:215], v[58:61]
	v_mfma_f32_16x16x32_bf16 v[50:53], v[204:207], v[212:215], v[50:53]
	v_mfma_f32_16x16x32_bf16 v[42:45], v[196:199], v[220:223], v[42:45]
	v_mfma_f32_16x16x32_bf16 v[34:37], v[204:207], v[220:223], v[34:37]
	v_mfma_f32_16x16x32_bf16 v[26:29], v[196:199], v[228:231], v[26:29]
	v_mfma_f32_16x16x32_bf16 v[18:21], v[204:207], v[228:231], v[18:21]
	v_mfma_f32_16x16x32_bf16 v[10:13], v[196:199], v[236:239], v[10:13]
	v_mfma_f32_16x16x32_bf16 v[2:5], v[204:207], v[236:239], v[2:5]
	s_barrier
	s_add_i32 s63, 0, 0x18000
	v_add_u32_e32 v138, s63, v161
	s_add_i32 s64, 0, 0x1c000
	ds_read_b128 v[164:167], v138
	ds_read_b128 v[180:183], v138 offset:1024
	ds_read_b128 v[184:187], v138 offset:2048
	ds_read_b128 v[188:191], v138 offset:3072
	v_add_u32_e32 v138, s64, v161
	ds_read_b128 v[192:195], v138
	ds_read_b128 v[196:199], v138 offset:1024
	ds_read_b128 v[200:203], v138 offset:2048
	ds_read_b128 v[204:207], v138 offset:3072
	s_add_u32 s20, s20, s6
	s_addc_u32 s21, s21, s7
	s_mov_b32 m0, s40
	v_lshl_add_u64 v[250:251], s[20:21], 0, v[152:153]
	ds_read_b128 v[208:211], v163 offset:32768
	ds_read_b128 v[212:215], v163 offset:33792
	ds_read_b128 v[216:219], v163 offset:34816
	ds_read_b128 v[220:223], v163 offset:35840
	ds_read_b128 v[224:227], v163 offset:36864
	ds_read_b128 v[228:231], v163 offset:37888
	ds_read_b128 v[232:235], v163 offset:38912
	ds_read_b128 v[236:239], v163 offset:39936
	global_load_lds_dwordx4 v[250:251], off
	v_lshl_add_u64 v[250:251], s[20:21], 0, v[150:151]
	s_mov_b32 m0, s41
	s_nop 0
	global_load_lds_dwordx4 v[250:251], off
	s_waitcnt vmcnt(8)
	s_waitcnt lgkmcnt(0)
	s_barrier
	s_waitcnt lgkmcnt(0)
	v_mfma_f32_16x16x32_bf16 v[126:129], v[164:167], v[208:211], v[126:129]
	v_mfma_f32_16x16x32_bf16 v[118:121], v[184:187], v[208:211], v[118:121]
	v_mfma_f32_16x16x32_bf16 v[110:113], v[164:167], v[216:219], v[110:113]
	v_mfma_f32_16x16x32_bf16 v[102:105], v[184:187], v[216:219], v[102:105]
	v_mfma_f32_16x16x32_bf16 v[94:97], v[164:167], v[224:227], v[94:97]
	v_mfma_f32_16x16x32_bf16 v[86:89], v[184:187], v[224:227], v[86:89]
	v_mfma_f32_16x16x32_bf16 v[78:81], v[164:167], v[232:235], v[78:81]
	v_mfma_f32_16x16x32_bf16 v[70:73], v[184:187], v[232:235], v[70:73]
	v_mfma_f32_16x16x32_bf16 v[126:129], v[180:183], v[212:215], v[126:129]
	v_mfma_f32_16x16x32_bf16 v[118:121], v[188:191], v[212:215], v[118:121]
	v_mfma_f32_16x16x32_bf16 v[110:113], v[180:183], v[220:223], v[110:113]
	v_mfma_f32_16x16x32_bf16 v[102:105], v[188:191], v[220:223], v[102:105]
	v_mfma_f32_16x16x32_bf16 v[94:97], v[180:183], v[228:231], v[94:97]
	v_mfma_f32_16x16x32_bf16 v[86:89], v[188:191], v[228:231], v[86:89]
	v_mfma_f32_16x16x32_bf16 v[78:81], v[180:183], v[236:239], v[78:81]
	v_mfma_f32_16x16x32_bf16 v[70:73], v[188:191], v[236:239], v[70:73]
	v_mfma_f32_16x16x32_bf16 v[122:125], v[192:195], v[208:211], v[122:125]
	v_mfma_f32_16x16x32_bf16 v[114:117], v[200:203], v[208:211], v[114:117]
	v_mfma_f32_16x16x32_bf16 v[106:109], v[192:195], v[216:219], v[106:109]
	v_mfma_f32_16x16x32_bf16 v[98:101], v[200:203], v[216:219], v[98:101]
	v_mfma_f32_16x16x32_bf16 v[90:93], v[192:195], v[224:227], v[90:93]
	v_mfma_f32_16x16x32_bf16 v[82:85], v[200:203], v[224:227], v[82:85]
	v_mfma_f32_16x16x32_bf16 v[74:77], v[192:195], v[232:235], v[74:77]
	v_mfma_f32_16x16x32_bf16 v[66:69], v[200:203], v[232:235], v[66:69]
	v_mfma_f32_16x16x32_bf16 v[122:125], v[196:199], v[212:215], v[122:125]
	v_mfma_f32_16x16x32_bf16 v[114:117], v[204:207], v[212:215], v[114:117]
	v_mfma_f32_16x16x32_bf16 v[106:109], v[196:199], v[220:223], v[106:109]
	v_mfma_f32_16x16x32_bf16 v[98:101], v[204:207], v[220:223], v[98:101]
	v_mfma_f32_16x16x32_bf16 v[90:93], v[196:199], v[228:231], v[90:93]
	v_mfma_f32_16x16x32_bf16 v[82:85], v[204:207], v[228:231], v[82:85]
	v_mfma_f32_16x16x32_bf16 v[74:77], v[196:199], v[236:239], v[74:77]
	v_mfma_f32_16x16x32_bf16 v[66:69], v[204:207], v[236:239], v[66:69]
	s_barrier
; #define PG8_STAGE(bufoff, gbase, voff) do { _Pragma("unroll") for (int _i = 0; _i < 2; ++_i) \
;         __builtin_amdgcn_global_load_lds((const unsigned*)((const char*)(gbase) + (voff)[_i]), (LAS unsigned*)(lds + (bufoff) + ldsw + _i * 8192), 16, 0, 0); } while (0)
; #define PG8_LDA(dst, b, h) do { _Pragma("unroll") for (int m = 0; m < 4; ++m) _Pragma("unroll") for (int k = 0; k < 2; ++k) dst[m][k] = *(const LAS bf16x8*)(lds + PG8_SA(b, h) + aoff + m * 2048 + k * 1024); } while (0)
; #define PG8_MMA(ai, bj, At, Bt) do { __builtin_amdgcn_s_setprio(1); _Pragma("unroll") for (int m = 0; m < 4; ++m) _Pragma("unroll") for (int n = 0; n < 2; ++n) _Pragma("unroll") for (int k = 0; k < 2; ++k) \
;         acc[ai][bj][m][n] = __builtin_amdgcn_mfma_f32_16x16x32_bf16(Bt[n][k], At[m][k], acc[ai][bj][m][n], 0, 0, 0); __builtin_amdgcn_s_setprio(0); } while (0)
; #define PG8_WAIT_V(n) asm volatile("s_waitcnt vmcnt(" #n ")" ::: "memory")
; #define PG8_WAIT_L(n) asm volatile("s_waitcnt lgkmcnt(" #n ")" ::: "memory")
; #define PG8_BAR __builtin_amdgcn_s_barrier()
; #define PG8_SCHED __builtin_amdgcn_sched_barrier(0)
; template <class Epi, class Sched, bool HALFN = false>
; __device__ __forceinline__ void gemm_phase(LAS unsigned char* lds, const Gemm g, const Sched& S, const Epi& E) {
;     ...
;             PG8_LDA(At, 1, 1); PG8_STAGE(PG8_SB(1, 0), b3, voffB); PG8_STAGE(PG8_SB(1, 1), b3 + hstep, voffB); PG8_STAGE(PG8_SA(1, 0), a3, voffA);
;             PG8_WAIT_V(8); PG8_WAIT_L(0); PG8_BAR; PG8_MMA(1, 0, At, B0); PG8_MMA(1, 1, At, B1); PG8_BAR; PG8_SCHED;
;             }
;         }
	s_add_i32 s20, s63, s22
	v_lshl_add_u64 v[158:159], v[158:159], 0, s[26:27]
	s_mov_b32 m0, s20
	ds_read_b128 v[208:211], v163 offset:49152
	ds_read_b128 v[212:215], v163 offset:50176
	ds_read_b128 v[216:219], v163 offset:51200
	ds_read_b128 v[220:223], v163 offset:52224
	ds_read_b128 v[224:227], v163 offset:53248
	ds_read_b128 v[228:231], v163 offset:54272
	ds_read_b128 v[232:235], v163 offset:55296
	ds_read_b128 v[236:239], v163 offset:56320
	global_load_lds_dwordx4 v[158:159], off
	v_lshl_add_u64 v[158:159], v[240:241], 0, s[26:27]
	s_add_i32 m0, s20, 0x2000
	s_add_i32 s20, s64, s22
	global_load_lds_dwordx4 v[158:159], off
	v_lshl_add_u64 v[158:159], v[242:243], 0, s[26:27]
	s_mov_b32 m0, s20
	s_nop 0
	global_load_lds_dwordx4 v[158:159], off
	v_lshl_add_u64 v[158:159], v[244:245], 0, s[26:27]
	s_add_i32 m0, s20, 0x2000
	s_nop 0
	global_load_lds_dwordx4 v[158:159], off
	v_lshl_add_u64 v[158:159], v[246:247], 0, s[26:27]
	s_mov_b32 m0, s42
	s_nop 0
	global_load_lds_dwordx4 v[158:159], off
	v_lshl_add_u64 v[158:159], v[248:249], 0, s[26:27]
	s_mov_b32 m0, s43
	s_nop 0
	global_load_lds_dwordx4 v[158:159], off
	s_waitcnt vmcnt(8)
	s_waitcnt lgkmcnt(0)
	s_barrier
	s_waitcnt lgkmcnt(0)
	v_mfma_f32_16x16x32_bf16 v[62:65], v[164:167], v[208:211], v[62:65]
	v_mfma_f32_16x16x32_bf16 v[54:57], v[184:187], v[208:211], v[54:57]
	v_mfma_f32_16x16x32_bf16 v[46:49], v[164:167], v[216:219], v[46:49]
	v_mfma_f32_16x16x32_bf16 v[38:41], v[184:187], v[216:219], v[38:41]
	v_mfma_f32_16x16x32_bf16 v[30:33], v[164:167], v[224:227], v[30:33]
	v_mfma_f32_16x16x32_bf16 v[22:25], v[184:187], v[224:227], v[22:25]
	v_mfma_f32_16x16x32_bf16 v[14:17], v[164:167], v[232:235], v[14:17]
	v_mfma_f32_16x16x32_bf16 v[6:9], v[184:187], v[232:235], v[6:9]
	v_mfma_f32_16x16x32_bf16 v[62:65], v[180:183], v[212:215], v[62:65]
	v_mfma_f32_16x16x32_bf16 v[54:57], v[188:191], v[212:215], v[54:57]
	v_mfma_f32_16x16x32_bf16 v[46:49], v[180:183], v[220:223], v[46:49]
	v_mfma_f32_16x16x32_bf16 v[38:41], v[188:191], v[220:223], v[38:41]
	v_mfma_f32_16x16x32_bf16 v[30:33], v[180:183], v[228:231], v[30:33]
	v_mfma_f32_16x16x32_bf16 v[22:25], v[188:191], v[228:231], v[22:25]
	v_mfma_f32_16x16x32_bf16 v[14:17], v[180:183], v[236:239], v[14:17]
	v_mfma_f32_16x16x32_bf16 v[6:9], v[188:191], v[236:239], v[6:9]
	v_mfma_f32_16x16x32_bf16 v[58:61], v[192:195], v[208:211], v[58:61]
	v_mfma_f32_16x16x32_bf16 v[50:53], v[200:203], v[208:211], v[50:53]
	v_mfma_f32_16x16x32_bf16 v[42:45], v[192:195], v[216:219], v[42:45]
	v_mfma_f32_16x16x32_bf16 v[34:37], v[200:203], v[216:219], v[34:37]
	v_mfma_f32_16x16x32_bf16 v[26:29], v[192:195], v[224:227], v[26:29]
	v_mfma_f32_16x16x32_bf16 v[18:21], v[200:203], v[224:227], v[18:21]
	v_mfma_f32_16x16x32_bf16 v[10:13], v[192:195], v[232:235], v[10:13]
	v_mfma_f32_16x16x32_bf16 v[2:5], v[200:203], v[232:235], v[2:5]
	v_mfma_f32_16x16x32_bf16 v[58:61], v[196:199], v[212:215], v[58:61]
	v_mfma_f32_16x16x32_bf16 v[50:53], v[204:207], v[212:215], v[50:53]
	v_mfma_f32_16x16x32_bf16 v[42:45], v[196:199], v[220:223], v[42:45]
	v_mfma_f32_16x16x32_bf16 v[34:37], v[204:207], v[220:223], v[34:37]
	v_mfma_f32_16x16x32_bf16 v[26:29], v[196:199], v[228:231], v[26:29]
	v_mfma_f32_16x16x32_bf16 v[18:21], v[204:207], v[228:231], v[18:21]
	v_mfma_f32_16x16x32_bf16 v[10:13], v[196:199], v[236:239], v[10:13]
	v_mfma_f32_16x16x32_bf16 v[2:5], v[204:207], v[236:239], v[2:5]
	s_barrier
	s_add_u32 s60, s60, 0x100
	s_addc_u32 s61, s61, 0
	s_add_u32 s18, s18, 0x100
	s_addc_u32 s19, s19, 0
	s_cmp_ge_i32 s62, s45
	s_mov_b32 s20, s62
	s_cbranch_scc0 .LBB0_654
